# GEMM epilogue result stores written through (sc0 sc1) so the grid barrier release fence finds a clean L2
# baseline (speedup 1.0000x reference)
; #define GAS __attribute__((address_space(1)))
;     __device__ __forceinline__ void operator()(const f32x4 (&acc)[2][2][4][2], const pg8::Unit& u, int wr, int wc, int fr, int fq) const {
;     ...
;                 for (int m = 0; m < 4; ++m) { const int row = u.pm * 256 + ai * 128 + wr * 64 + m * 16 + fr; pq[ai][m] = *(const GAS f32x4*)(a.ssp + (size_t)row * 16 + 4 * fq); }
; #pragma unroll
;             for (int ai = 0; ai < 2; ++ai)
; #pragma unroll
;                 for (int m = 0; m < 4; ++m) { float sp = (pq[ai][m][0] + pq[ai][m][1]) + (pq[ai][m][2] + pq[ai][m][3]); sp += __shfl_xor(sp, 16); sp += __shfl_xor(sp, 32); rs[ai][m] = rsqrtf(sp * (1.0f / 1024.0f) + EPS); }
.LBB0_314:
	v_bfe_u32 v248, v200, 4, 1
	v_mul_u32_u24_e32 v248, 0x78, v248
	v_mov_b32_e32 v249, 0
	v_readlane_b32 s0, v245, 2
	v_lshl_add_u32 v188, s12, 8, v159
	v_lshlrev_b32_e32 v160, 2, v158
	v_mov_b32_e32 v128, s0
	ds_read_b128 v[128:131], v128
	v_ashrrev_i32_e32 v189, 31, v188
	v_lshlrev_b64 v[132:133], 6, v[188:189]
	v_or_b32_e32 v184, 16, v188
	v_ashrrev_i32_e32 v185, 31, v184
	s_waitcnt lgkmcnt(0)
	v_lshl_add_u64 v[130:131], v[130:131], 0, v[160:161]
	v_lshl_add_u64 v[132:133], v[130:131], 0, v[132:133]
	global_load_dwordx4 v[208:211], v[132:133], off
	v_lshlrev_b64 v[132:133], 6, v[184:185]
	v_lshl_add_u64 v[132:133], v[130:131], 0, v[132:133]
	global_load_dwordx4 v[214:217], v[132:133], off
	v_or_b32_e32 v182, 32, v188
	v_ashrrev_i32_e32 v183, 31, v182
	v_lshlrev_b64 v[132:133], 6, v[182:183]
	v_or_b32_e32 v180, 48, v188
	v_lshl_add_u64 v[132:133], v[130:131], 0, v[132:133]
	v_ashrrev_i32_e32 v181, 31, v180
	global_load_dwordx4 v[150:153], v[132:133], off
	v_lshlrev_b64 v[132:133], 6, v[180:181]
	v_lshl_add_u64 v[132:133], v[130:131], 0, v[132:133]
	global_load_dwordx4 v[146:149], v[132:133], off
	v_add_u32_e32 v178, 0x80, v188
	v_ashrrev_i32_e32 v179, 31, v178
	v_lshlrev_b64 v[132:133], 6, v[178:179]
	v_add_u32_e32 v176, 0x90, v188
	v_lshl_add_u64 v[132:133], v[130:131], 0, v[132:133]
	v_ashrrev_i32_e32 v177, 31, v176
	global_load_dwordx4 v[142:145], v[132:133], off
	v_lshlrev_b64 v[132:133], 6, v[176:177]
	v_lshl_add_u64 v[132:133], v[130:131], 0, v[132:133]
	global_load_dwordx4 v[138:141], v[132:133], off
	v_add_u32_e32 v174, 0xa0, v188
	v_ashrrev_i32_e32 v175, 31, v174
	v_lshlrev_b64 v[132:133], 6, v[174:175]
	v_add_u32_e32 v172, 0xb0, v188
	v_lshl_add_u64 v[132:133], v[130:131], 0, v[132:133]
	v_ashrrev_i32_e32 v173, 31, v172
	global_load_dwordx4 v[134:137], v[132:133], off
	v_lshlrev_b64 v[132:133], 6, v[172:173]
	v_lshl_add_u64 v[130:131], v[130:131], 0, v[132:133]
	global_load_dwordx4 v[130:133], v[130:131], off
	v_and_b32_e32 v173, 64, v200
	v_xor_b32_e32 v160, 16, v200
	v_add_u32_e32 v175, 64, v173
	v_cmp_lt_i32_e32 vcc, v160, v175
	s_mov_b32 s0, 0x358637bd
	s_mov_b32 s12, 0x3a800000
	v_cndmask_b32_e32 v160, v200, v160, vcc
	v_lshlrev_b32_e32 v173, 2, v160
	v_xor_b32_e32 v160, 32, v200
	v_cmp_lt_i32_e32 vcc, v160, v175
	s_movk_i32 s18, 0x1600
	v_readlane_b32 s22, v245, 51
	v_cndmask_b32_e32 v160, v200, v160, vcc
	v_lshlrev_b32_e32 v160, 2, v160
	s_mov_b32 s80, 0x3a800000
	v_readlane_b32 s23, v245, 52
	s_waitcnt vmcnt(0)
	v_mov_b32_e32 v192, v209
	v_mov_b32_e32 v193, v210
	v_mov_b32_e32 v209, v211
	v_pk_add_f32 v[192:193], v[192:193], v[208:209]
	v_mov_b32_e32 v208, v215
	v_mov_b32_e32 v209, v216
	v_mov_b32_e32 v215, v217
	v_pk_add_f32 v[208:209], v[208:209], v[214:215]
	v_mov_b32_e32 v211, v192
	v_mov_b32_e32 v210, v208
	v_mov_b32_e32 v192, v209
	v_pk_add_f32 v[192:193], v[210:211], v[192:193]
	ds_bpermute_b32 v209, v173, v193
	ds_bpermute_b32 v208, v173, v192
	s_waitcnt lgkmcnt(0)
	v_pk_add_f32 v[192:193], v[192:193], v[208:209]
	ds_bpermute_b32 v209, v160, v193
	ds_bpermute_b32 v208, v160, v192
	s_waitcnt lgkmcnt(0)
	v_pk_add_f32 v[208:209], v[192:193], v[208:209]
	v_mov_b64_e32 v[192:193], s[0:1]
	v_pk_fma_f32 v[208:209], v[208:209], s[12:13], v[192:193] op_sel_hi:[1,0,0]
	s_nop 0
	v_mul_f32_e32 v175, 0x4b800000, v209
	v_cmp_gt_f32_e64 s[0:1], s3, v209
	v_cmp_gt_f32_e32 vcc, s3, v208
	s_nop 0
	v_cndmask_b32_e64 v175, v209, v175, s[0:1]
	v_rsq_f32_e32 v175, v175
	v_mov_b32_e32 v209, v152
	v_mov_b32_e32 v152, v147
	v_mov_b32_e32 v147, v149
	v_mul_f32_e32 v177, 0x45800000, v175
	v_cndmask_b32_e64 v190, v175, v177, s[0:1]
	v_mul_f32_e32 v175, 0x4b800000, v208
	v_cndmask_b32_e32 v175, v208, v175, vcc
	v_mov_b32_e32 v208, v151
	v_mov_b32_e32 v151, v153
	v_mov_b32_e32 v153, v148
	v_pk_add_f32 v[150:151], v[208:209], v[150:151]
	v_pk_add_f32 v[146:147], v[152:153], v[146:147]
	v_mov_b32_e32 v149, v150
	v_mov_b32_e32 v148, v146
	v_mov_b32_e32 v150, v147
	v_pk_add_f32 v[146:147], v[148:149], v[150:151]
	ds_bpermute_b32 v149, v173, v147
	ds_bpermute_b32 v148, v173, v146
	v_mov_b32_e32 v150, v143
	v_mov_b32_e32 v151, v144
	v_mov_b32_e32 v143, v145
	v_mov_b32_e32 v144, v139
	v_mov_b32_e32 v145, v140
	v_mov_b32_e32 v139, v141
	v_pk_add_f32 v[142:143], v[150:151], v[142:143]
	v_pk_add_f32 v[138:139], v[144:145], v[138:139]
	s_waitcnt lgkmcnt(0)
	v_pk_add_f32 v[146:147], v[146:147], v[148:149]
	v_mov_b32_e32 v140, v138
	v_mov_b32_e32 v141, v142
	v_mov_b32_e32 v142, v139
	ds_bpermute_b32 v149, v160, v147
	ds_bpermute_b32 v148, v160, v146
	v_pk_add_f32 v[138:139], v[140:141], v[142:143]
	ds_bpermute_b32 v141, v173, v139
	ds_bpermute_b32 v140, v173, v138
	v_mov_b32_e32 v142, v135
	v_mov_b32_e32 v143, v136
	v_mov_b32_e32 v135, v137
	v_mov_b32_e32 v136, v131
	v_mov_b32_e32 v137, v132
	v_mov_b32_e32 v131, v133
	s_waitcnt lgkmcnt(2)
	v_pk_add_f32 v[146:147], v[146:147], v[148:149]
	v_pk_add_f32 v[134:135], v[142:143], v[134:135]
	v_pk_add_f32 v[130:131], v[136:137], v[130:131]
	v_pk_fma_f32 v[146:147], v[146:147], s[12:13], v[192:193] op_sel_hi:[1,0,0]
	s_waitcnt lgkmcnt(0)
	v_pk_add_f32 v[138:139], v[138:139], v[140:141]
	v_mov_b32_e32 v132, v130
	v_mov_b32_e32 v133, v134
	v_mov_b32_e32 v134, v131
	v_mul_f32_e32 v148, 0x4b800000, v147
	v_cmp_gt_f32_e64 s[0:1], s3, v147
	ds_bpermute_b32 v141, v160, v139
	ds_bpermute_b32 v140, v160, v138
	v_pk_add_f32 v[130:131], v[132:133], v[134:135]
	v_cndmask_b32_e64 v147, v147, v148, s[0:1]
	ds_bpermute_b32 v133, v173, v131
	ds_bpermute_b32 v132, v173, v130
	v_rsq_f32_e32 v175, v175
	v_rsq_f32_e32 v147, v147
	s_waitcnt lgkmcnt(2)
; #define GAS __attribute__((address_space(1)))
; __device__ __forceinline__ unsigned pk2(float lo, float hi) { const f32x2 v = {lo, hi}; return __builtin_bit_cast(unsigned, __builtin_convertvector(v, hwbf16x2)); }
; __device__ __forceinline__ float silu_f(float x) { return x * fast_rcp(1.0f + __expf(-x)); }
; template <int MODE, bool SMALL>
; __device__ __forceinline__ float epi_apply(const EpiArgs& a, int row, int g32, int fq, f32x4 v0, f32x4 v1, float rstd) {
;     ...
;         v0 *= rstd; v1 *= rstd;
;         float h[4];
; #pragma unroll
;         for (int j = 0; j < 4; ++j) h[j] = silu_f(v0[j]) * v1[j];
;         u32x2 w; w.x = pk2(h[0], h[1]); w.y = pk2(h[2], h[3]);
;         *(GAS u32x2*)(a.out + (size_t)row * DFF + 16 * g32 + 4 * fq) = w;
	v_pk_add_f32 v[138:139], v[138:139], v[140:141]
	v_pk_mul_f32 v[124:125], v[124:125], v[190:191] op_sel_hi:[1,0]
	v_mul_f32_e32 v177, 0x45800000, v175
	v_mul_f32_e32 v148, 0x45800000, v147
	v_pk_fma_f32 v[138:139], v[138:139], s[12:13], v[192:193] op_sel_hi:[1,0,0]
	s_waitcnt lgkmcnt(0)
	v_pk_add_f32 v[130:131], v[130:131], v[132:133]
	v_cndmask_b32_e32 v186, v175, v177, vcc
	v_cmp_gt_f32_e32 vcc, s3, v146
	v_cndmask_b32_e64 v148, v147, v148, s[0:1]
	v_mul_f32_e32 v147, 0x4b800000, v146
	v_mul_f32_e32 v140, 0x4b800000, v139
	v_cmp_gt_f32_e64 s[0:1], s3, v139
	ds_bpermute_b32 v133, v160, v131
	ds_bpermute_b32 v132, v160, v130
	v_cndmask_b32_e32 v146, v146, v147, vcc
	v_cndmask_b32_e64 v139, v139, v140, s[0:1]
	v_rsq_f32_e32 v146, v146
	v_rsq_f32_e32 v139, v139
	s_waitcnt lgkmcnt(0)
	v_pk_add_f32 v[130:131], v[130:131], v[132:133]
	v_pk_mul_f32 v[126:127], v[126:127], v[190:191] op_sel_hi:[1,0]
	v_mul_f32_e32 v147, 0x45800000, v146
	v_mul_f32_e32 v140, 0x45800000, v139
	v_pk_fma_f32 v[130:131], v[130:131], s[12:13], v[192:193] op_sel_hi:[1,0,0]
	v_cndmask_b32_e32 v146, v146, v147, vcc
	v_cmp_gt_f32_e32 vcc, s3, v138
	v_cndmask_b32_e64 v140, v139, v140, s[0:1]
	v_mul_f32_e32 v139, 0x4b800000, v138
	v_mul_f32_e32 v132, 0x4b800000, v131
	v_cmp_gt_f32_e64 s[0:1], s3, v131
	v_cndmask_b32_e32 v138, v138, v139, vcc
	v_rsq_f32_e32 v138, v138
	v_cndmask_b32_e64 v131, v131, v132, s[0:1]
	v_rsq_f32_e32 v131, v131
	v_pk_mul_f32 v[120:121], v[120:121], v[190:191] op_sel_hi:[1,0]
	v_mul_f32_e32 v139, 0x45800000, v138
	v_cndmask_b32_e32 v138, v138, v139, vcc
	v_mul_f32_e32 v132, 0x45800000, v131
	v_cmp_gt_f32_e32 vcc, s3, v130
	v_cndmask_b32_e64 v132, v131, v132, s[0:1]
	v_mul_f32_e32 v131, 0x4b800000, v130
	v_cndmask_b32_e32 v130, v130, v131, vcc
	v_rsq_f32_e32 v130, v130
	v_lshlrev_b32_e32 v160, 1, v158
	s_lshl_b32 s0, s4, 8
	v_lshl_add_u64 v[128:129], v[128:129], 0, v[160:161]
	v_mul_f32_e32 v131, 0x45800000, v130
	v_cndmask_b32_e32 v130, v130, v131, vcc
	v_mul_f32_e32 v131, 0xbfb8aa3b, v124
	v_exp_f32_e32 v131, v131
	s_or_b32 s4, s0, s60
	v_mad_i64_i32 v[134:135], s[0:1], v188, s18, v[128:129]
	v_add_f32_e32 v131, 1.0, v131
	v_rcp_f32_e32 v136, v131
	v_mul_f32_e32 v131, 0xbfb8aa3b, v125
	v_exp_f32_e32 v131, v131
	s_ashr_i32 s0, s4, 1
	v_pk_mul_f32 v[122:123], v[122:123], v[190:191] op_sel_hi:[1,0]
	s_ashr_i32 s1, s0, 31
	v_add_f32_e32 v131, 1.0, v131
	v_rcp_f32_e32 v137, v131
	s_lshl_b64 s[0:1], s[0:1], 1
	v_pk_mul_f32 v[116:117], v[116:117], v[190:191] op_sel_hi:[1,0]
	v_pk_mul_f32 v[118:119], v[118:119], v[190:191] op_sel_hi:[1,0]
	v_pk_mul_f32 v[124:125], v[124:125], v[136:137]
	v_pk_mul_f32 v[112:113], v[112:113], v[190:191] op_sel_hi:[1,0]
	v_pk_mul_f32 v[120:121], v[120:121], v[124:125]
	v_mul_f32_e32 v124, 0xbfb8aa3b, v126
	v_mul_f32_e32 v125, 0xbfb8aa3b, v127
	v_exp_f32_e32 v124, v124
	v_exp_f32_e32 v125, v125
	v_cvt_pk_bf16_f32 v120, v120, v121
	v_pk_mul_f32 v[114:115], v[114:115], v[190:191] op_sel_hi:[1,0]
	v_add_f32_e32 v124, 1.0, v124
	v_add_f32_e32 v125, 1.0, v125
	v_rcp_f32_e32 v124, v124
	v_rcp_f32_e32 v125, v125
	v_pk_mul_f32 v[108:109], v[108:109], v[186:187] op_sel_hi:[1,0]
	v_pk_mul_f32 v[110:111], v[110:111], v[186:187] op_sel_hi:[1,0]
	v_pk_mul_f32 v[104:105], v[104:105], v[186:187] op_sel_hi:[1,0]
	v_pk_mul_f32 v[124:125], v[126:127], v[124:125]
	v_pk_mul_f32 v[106:107], v[106:107], v[186:187] op_sel_hi:[1,0]
	v_pk_mul_f32 v[122:123], v[122:123], v[124:125]
	v_pk_mul_f32 v[100:101], v[100:101], v[186:187] op_sel_hi:[1,0]
	v_cvt_pk_bf16_f32 v121, v122, v123
	v_lshl_add_u64 v[122:123], v[134:135], 0, s[0:1]
	v_mov_b32_e32 v250, v120
	v_mov_b32_e32 v251, v121
	v_mul_f32_e32 v120, 0xbfb8aa3b, v116
	v_mul_f32_e32 v121, 0xbfb8aa3b, v117
	v_exp_f32_e32 v120, v120
	v_exp_f32_e32 v121, v121
	v_pk_mul_f32 v[102:103], v[102:103], v[186:187] op_sel_hi:[1,0]
	v_pk_mul_f32 v[96:97], v[96:97], v[186:187] op_sel_hi:[1,0]
	v_add_f32_e32 v120, 1.0, v120
	v_add_f32_e32 v121, 1.0, v121
	v_rcp_f32_e32 v120, v120
	v_rcp_f32_e32 v121, v121
	v_pk_mul_f32 v[98:99], v[98:99], v[186:187] op_sel_hi:[1,0]
	v_pk_mul_f32 v[92:93], v[92:93], v[148:149] op_sel_hi:[1,0]
	v_pk_mul_f32 v[94:95], v[94:95], v[148:149] op_sel_hi:[1,0]
	v_pk_mul_f32 v[116:117], v[116:117], v[120:121]
	v_pk_mul_f32 v[88:89], v[88:89], v[148:149] op_sel_hi:[1,0]
	v_pk_mul_f32 v[112:113], v[112:113], v[116:117]
	v_mul_f32_e32 v116, 0xbfb8aa3b, v118
	v_mul_f32_e32 v117, 0xbfb8aa3b, v119
	v_exp_f32_e32 v116, v116
	v_exp_f32_e32 v117, v117
	v_cvt_pk_bf16_f32 v112, v112, v113
	v_pk_mul_f32 v[90:91], v[90:91], v[148:149] op_sel_hi:[1,0]
	v_add_f32_e32 v116, 1.0, v116
	v_add_f32_e32 v117, 1.0, v117
	v_rcp_f32_e32 v116, v116
	v_rcp_f32_e32 v117, v117
	v_pk_mul_f32 v[84:85], v[84:85], v[148:149] op_sel_hi:[1,0]
	v_pk_mul_f32 v[86:87], v[86:87], v[148:149] op_sel_hi:[1,0]
	v_pk_mul_f32 v[80:81], v[80:81], v[148:149] op_sel_hi:[1,0]
	v_pk_mul_f32 v[116:117], v[118:119], v[116:117]
	v_pk_mul_f32 v[82:83], v[82:83], v[148:149] op_sel_hi:[1,0]
	v_pk_mul_f32 v[114:115], v[114:115], v[116:117]
	v_pk_mul_f32 v[76:77], v[76:77], v[146:147] op_sel_hi:[1,0]
	v_cvt_pk_bf16_f32 v113, v114, v115
	v_mul_f32_e32 v114, 0xbfb8aa3b, v108
	v_mul_f32_e32 v115, 0xbfb8aa3b, v109
	v_exp_f32_e32 v114, v114
	v_exp_f32_e32 v115, v115
	v_mov_b32_e32 v252, v112
	v_mov_b32_e32 v253, v113
	v_lshl_add_u64 v[254:255], v[122:123], 0, v[248:249]
	s_nop 0
	v_permlane16_swap_b32_e32 v250, v252
	v_permlane16_swap_b32_e32 v251, v253
	global_store_dwordx4 v[254:255], v[250:253], off sc0 sc1
	v_mad_i64_i32 v[112:113], s[12:13], v184, s18, v[128:129]
	v_add_f32_e32 v114, 1.0, v114
	v_add_f32_e32 v115, 1.0, v115
	v_rcp_f32_e32 v114, v114
; #define GAS __attribute__((address_space(1)))
; __device__ __forceinline__ unsigned pk2(float lo, float hi) { const f32x2 v = {lo, hi}; return __builtin_bit_cast(unsigned, __builtin_convertvector(v, hwbf16x2)); }
; __device__ __forceinline__ float silu_f(float x) { return x * fast_rcp(1.0f + __expf(-x)); }
; template <int MODE, bool SMALL>
; __device__ __forceinline__ float epi_apply(const EpiArgs& a, int row, int g32, int fq, f32x4 v0, f32x4 v1, float rstd) {
;     ...
;         v0 *= rstd; v1 *= rstd;
;         float h[4];
; #pragma unroll
;         for (int j = 0; j < 4; ++j) h[j] = silu_f(v0[j]) * v1[j];
;         u32x2 w; w.x = pk2(h[0], h[1]); w.y = pk2(h[2], h[3]);
;         *(GAS u32x2*)(a.out + (size_t)row * DFF + 16 * g32 + 4 * fq) = w;
	v_rcp_f32_e32 v115, v115
	v_pk_mul_f32 v[78:79], v[78:79], v[146:147] op_sel_hi:[1,0]
	v_pk_mul_f32 v[72:73], v[72:73], v[146:147] op_sel_hi:[1,0]
	v_pk_mul_f32 v[74:75], v[74:75], v[146:147] op_sel_hi:[1,0]
	v_pk_mul_f32 v[108:109], v[108:109], v[114:115]
	v_pk_mul_f32 v[68:69], v[68:69], v[146:147] op_sel_hi:[1,0]
	v_pk_mul_f32 v[104:105], v[104:105], v[108:109]
	v_mul_f32_e32 v108, 0xbfb8aa3b, v110
	v_mul_f32_e32 v109, 0xbfb8aa3b, v111
	v_exp_f32_e32 v108, v108
	v_exp_f32_e32 v109, v109
	v_cvt_pk_bf16_f32 v104, v104, v105
	v_pk_mul_f32 v[70:71], v[70:71], v[146:147] op_sel_hi:[1,0]
	v_add_f32_e32 v108, 1.0, v108
	v_add_f32_e32 v109, 1.0, v109
	v_rcp_f32_e32 v108, v108
	v_rcp_f32_e32 v109, v109
	v_pk_mul_f32 v[64:65], v[64:65], v[146:147] op_sel_hi:[1,0]
	v_pk_mul_f32 v[66:67], v[66:67], v[146:147] op_sel_hi:[1,0]
	v_pk_mul_f32 v[60:61], v[60:61], v[140:141] op_sel_hi:[1,0]
	v_pk_mul_f32 v[108:109], v[110:111], v[108:109]
	v_pk_mul_f32 v[62:63], v[62:63], v[140:141] op_sel_hi:[1,0]
	v_pk_mul_f32 v[106:107], v[106:107], v[108:109]
	v_pk_mul_f32 v[56:57], v[56:57], v[140:141] op_sel_hi:[1,0]
	v_cvt_pk_bf16_f32 v105, v106, v107
	v_lshl_add_u64 v[106:107], v[112:113], 0, s[0:1]
	v_mov_b32_e32 v250, v104
	v_mov_b32_e32 v251, v105
	v_mul_f32_e32 v104, 0xbfb8aa3b, v100
	v_mul_f32_e32 v105, 0xbfb8aa3b, v101
	v_exp_f32_e32 v104, v104
	v_exp_f32_e32 v105, v105
	v_pk_mul_f32 v[58:59], v[58:59], v[140:141] op_sel_hi:[1,0]
	v_pk_mul_f32 v[52:53], v[52:53], v[140:141] op_sel_hi:[1,0]
	v_add_f32_e32 v104, 1.0, v104
	v_add_f32_e32 v105, 1.0, v105
	v_rcp_f32_e32 v104, v104
	v_rcp_f32_e32 v105, v105
	v_pk_mul_f32 v[54:55], v[54:55], v[140:141] op_sel_hi:[1,0]
	v_pk_mul_f32 v[48:49], v[48:49], v[140:141] op_sel_hi:[1,0]
	v_pk_mul_f32 v[50:51], v[50:51], v[140:141] op_sel_hi:[1,0]
	v_pk_mul_f32 v[100:101], v[100:101], v[104:105]
	v_pk_mul_f32 v[44:45], v[44:45], v[138:139] op_sel_hi:[1,0]
	v_pk_mul_f32 v[96:97], v[96:97], v[100:101]
	v_mul_f32_e32 v100, 0xbfb8aa3b, v102
	v_mul_f32_e32 v101, 0xbfb8aa3b, v103
	v_exp_f32_e32 v100, v100
	v_exp_f32_e32 v101, v101
	v_cvt_pk_bf16_f32 v96, v96, v97
	v_pk_mul_f32 v[46:47], v[46:47], v[138:139] op_sel_hi:[1,0]
	v_add_f32_e32 v100, 1.0, v100
	v_add_f32_e32 v101, 1.0, v101
	v_rcp_f32_e32 v100, v100
	v_rcp_f32_e32 v101, v101
	v_pk_mul_f32 v[40:41], v[40:41], v[138:139] op_sel_hi:[1,0]
	v_pk_mul_f32 v[42:43], v[42:43], v[138:139] op_sel_hi:[1,0]
	v_pk_mul_f32 v[36:37], v[36:37], v[138:139] op_sel_hi:[1,0]
	v_pk_mul_f32 v[100:101], v[102:103], v[100:101]
	v_pk_mul_f32 v[38:39], v[38:39], v[138:139] op_sel_hi:[1,0]
	v_pk_mul_f32 v[98:99], v[98:99], v[100:101]
	v_pk_mul_f32 v[32:33], v[32:33], v[138:139] op_sel_hi:[1,0]
	v_cvt_pk_bf16_f32 v97, v98, v99
	v_mul_f32_e32 v98, 0xbfb8aa3b, v92
	v_mul_f32_e32 v99, 0xbfb8aa3b, v93
	v_exp_f32_e32 v98, v98
	v_exp_f32_e32 v99, v99
	v_mov_b32_e32 v252, v96
	v_mov_b32_e32 v253, v97
	v_lshl_add_u64 v[254:255], v[106:107], 0, v[248:249]
	s_nop 0
	v_permlane16_swap_b32_e32 v250, v252
	v_permlane16_swap_b32_e32 v251, v253
	global_store_dwordx4 v[254:255], v[250:253], off sc0 sc1
	v_mad_i64_i32 v[96:97], s[12:13], v182, s18, v[128:129]
	v_add_f32_e32 v98, 1.0, v98
	v_add_f32_e32 v99, 1.0, v99
	v_rcp_f32_e32 v98, v98
	v_rcp_f32_e32 v99, v99
	v_pk_mul_f32 v[34:35], v[34:35], v[138:139] op_sel_hi:[1,0]
	v_pk_mul_f32 v[28:29], v[28:29], v[132:133] op_sel_hi:[1,0]
	v_pk_mul_f32 v[30:31], v[30:31], v[132:133] op_sel_hi:[1,0]
	v_pk_mul_f32 v[92:93], v[92:93], v[98:99]
	v_pk_mul_f32 v[24:25], v[24:25], v[132:133] op_sel_hi:[1,0]
	v_pk_mul_f32 v[88:89], v[88:89], v[92:93]
	v_mul_f32_e32 v92, 0xbfb8aa3b, v94
	v_mul_f32_e32 v93, 0xbfb8aa3b, v95
	v_exp_f32_e32 v92, v92
	v_exp_f32_e32 v93, v93
	v_cvt_pk_bf16_f32 v88, v88, v89
	v_pk_mul_f32 v[26:27], v[26:27], v[132:133] op_sel_hi:[1,0]
	v_add_f32_e32 v92, 1.0, v92
	v_add_f32_e32 v93, 1.0, v93
	v_rcp_f32_e32 v92, v92
	v_rcp_f32_e32 v93, v93
	v_pk_mul_f32 v[20:21], v[20:21], v[132:133] op_sel_hi:[1,0]
	v_pk_mul_f32 v[22:23], v[22:23], v[132:133] op_sel_hi:[1,0]
	v_pk_mul_f32 v[16:17], v[16:17], v[132:133] op_sel_hi:[1,0]
	v_pk_mul_f32 v[92:93], v[94:95], v[92:93]
	v_pk_mul_f32 v[18:19], v[18:19], v[132:133] op_sel_hi:[1,0]
	v_pk_mul_f32 v[90:91], v[90:91], v[92:93]
	v_pk_mul_f32 v[12:13], v[12:13], v[130:131] op_sel_hi:[1,0]
	v_cvt_pk_bf16_f32 v89, v90, v91
	v_lshl_add_u64 v[90:91], v[96:97], 0, s[0:1]
	v_mov_b32_e32 v250, v88
	v_mov_b32_e32 v251, v89
	v_mul_f32_e32 v88, 0xbfb8aa3b, v84
	v_mul_f32_e32 v89, 0xbfb8aa3b, v85
	v_exp_f32_e32 v88, v88
	v_exp_f32_e32 v89, v89
	v_pk_mul_f32 v[14:15], v[14:15], v[130:131] op_sel_hi:[1,0]
	v_pk_mul_f32 v[8:9], v[8:9], v[130:131] op_sel_hi:[1,0]
	v_add_f32_e32 v88, 1.0, v88
	v_add_f32_e32 v89, 1.0, v89
	v_rcp_f32_e32 v88, v88
	v_rcp_f32_e32 v89, v89
	v_pk_mul_f32 v[10:11], v[10:11], v[130:131] op_sel_hi:[1,0]
	v_pk_mul_f32 v[4:5], v[4:5], v[130:131] op_sel_hi:[1,0]
	v_pk_mul_f32 v[6:7], v[6:7], v[130:131] op_sel_hi:[1,0]
	v_pk_mul_f32 v[84:85], v[84:85], v[88:89]
	v_pk_mul_f32 v[0:1], v[0:1], v[130:131] op_sel_hi:[1,0]
	v_pk_mul_f32 v[80:81], v[80:81], v[84:85]
	v_mul_f32_e32 v84, 0xbfb8aa3b, v86
	v_mul_f32_e32 v85, 0xbfb8aa3b, v87
	v_exp_f32_e32 v84, v84
	v_exp_f32_e32 v85, v85
	v_cvt_pk_bf16_f32 v80, v80, v81
	v_pk_mul_f32 v[2:3], v[2:3], v[130:131] op_sel_hi:[1,0]
	v_add_f32_e32 v84, 1.0, v84
	v_add_f32_e32 v85, 1.0, v85
	v_rcp_f32_e32 v84, v84
	v_rcp_f32_e32 v85, v85
	s_and_b64 vcc, exec, s[38:39]
	v_pk_mul_f32 v[84:85], v[86:87], v[84:85]
	s_nop 0
	v_pk_mul_f32 v[82:83], v[82:83], v[84:85]
	s_nop 0
	v_cvt_pk_bf16_f32 v81, v82, v83
	v_mul_f32_e32 v82, 0xbfb8aa3b, v76
	v_mul_f32_e32 v83, 0xbfb8aa3b, v77
; #define GAS __attribute__((address_space(1)))
; __device__ __forceinline__ unsigned pk2(float lo, float hi) { const f32x2 v = {lo, hi}; return __builtin_bit_cast(unsigned, __builtin_convertvector(v, hwbf16x2)); }
; __device__ __forceinline__ float silu_f(float x) { return x * fast_rcp(1.0f + __expf(-x)); }
; template <int MODE, bool SMALL>
; __device__ __forceinline__ float epi_apply(const EpiArgs& a, int row, int g32, int fq, f32x4 v0, f32x4 v1, float rstd) {
;     ...
;         v0 *= rstd; v1 *= rstd;
;         float h[4];
; #pragma unroll
;         for (int j = 0; j < 4; ++j) h[j] = silu_f(v0[j]) * v1[j];
;         u32x2 w; w.x = pk2(h[0], h[1]); w.y = pk2(h[2], h[3]);
;         *(GAS u32x2*)(a.out + (size_t)row * DFF + 16 * g32 + 4 * fq) = w;
	v_exp_f32_e32 v82, v82
	v_exp_f32_e32 v83, v83
	v_mov_b32_e32 v252, v80
	v_mov_b32_e32 v253, v81
	v_lshl_add_u64 v[254:255], v[90:91], 0, v[248:249]
	s_nop 0
	v_permlane16_swap_b32_e32 v250, v252
	v_permlane16_swap_b32_e32 v251, v253
	global_store_dwordx4 v[254:255], v[250:253], off sc0 sc1
	v_mad_i64_i32 v[80:81], s[12:13], v180, s18, v[128:129]
	v_add_f32_e32 v82, 1.0, v82
	v_add_f32_e32 v83, 1.0, v83
	v_rcp_f32_e32 v82, v82
	v_rcp_f32_e32 v83, v83
	s_nop 0
	v_pk_mul_f32 v[76:77], v[76:77], v[82:83]
	s_nop 0
	v_pk_mul_f32 v[72:73], v[72:73], v[76:77]
	v_mul_f32_e32 v76, 0xbfb8aa3b, v78
	v_mul_f32_e32 v77, 0xbfb8aa3b, v79
	v_exp_f32_e32 v76, v76
	v_exp_f32_e32 v77, v77
	v_cvt_pk_bf16_f32 v72, v72, v73
	v_add_f32_e32 v76, 1.0, v76
	v_add_f32_e32 v77, 1.0, v77
	v_rcp_f32_e32 v76, v76
	v_rcp_f32_e32 v77, v77
	s_nop 0
	v_pk_mul_f32 v[76:77], v[78:79], v[76:77]
	s_nop 0
	v_pk_mul_f32 v[74:75], v[74:75], v[76:77]
	s_nop 0
	v_cvt_pk_bf16_f32 v73, v74, v75
	v_lshl_add_u64 v[74:75], v[80:81], 0, s[0:1]
	v_mov_b32_e32 v250, v72
	v_mov_b32_e32 v251, v73
	v_mul_f32_e32 v72, 0xbfb8aa3b, v68
	v_mul_f32_e32 v73, 0xbfb8aa3b, v69
	v_exp_f32_e32 v72, v72
	v_exp_f32_e32 v73, v73
	v_add_f32_e32 v72, 1.0, v72
	v_add_f32_e32 v73, 1.0, v73
	v_rcp_f32_e32 v72, v72
	v_rcp_f32_e32 v73, v73
	s_nop 0
	v_pk_mul_f32 v[68:69], v[68:69], v[72:73]
	s_nop 0
	v_pk_mul_f32 v[64:65], v[64:65], v[68:69]
	v_mul_f32_e32 v68, 0xbfb8aa3b, v70
	v_mul_f32_e32 v69, 0xbfb8aa3b, v71
	v_exp_f32_e32 v68, v68
	v_exp_f32_e32 v69, v69
	v_cvt_pk_bf16_f32 v64, v64, v65
	v_add_f32_e32 v68, 1.0, v68
	v_add_f32_e32 v69, 1.0, v69
	v_rcp_f32_e32 v68, v68
	v_rcp_f32_e32 v69, v69
	s_nop 0
	v_pk_mul_f32 v[68:69], v[70:71], v[68:69]
	s_nop 0
	v_pk_mul_f32 v[66:67], v[66:67], v[68:69]
	s_nop 0
	v_cvt_pk_bf16_f32 v65, v66, v67
	v_mul_f32_e32 v66, 0xbfb8aa3b, v60
	v_mul_f32_e32 v67, 0xbfb8aa3b, v61
	v_exp_f32_e32 v66, v66
	v_exp_f32_e32 v67, v67
	v_mov_b32_e32 v252, v64
	v_mov_b32_e32 v253, v65
	v_lshl_add_u64 v[254:255], v[74:75], 0, v[248:249]
	s_nop 0
	v_permlane16_swap_b32_e32 v250, v252
	v_permlane16_swap_b32_e32 v251, v253
	global_store_dwordx4 v[254:255], v[250:253], off sc0 sc1
	v_mad_i64_i32 v[64:65], s[12:13], v178, s18, v[128:129]
	v_add_f32_e32 v66, 1.0, v66
	v_add_f32_e32 v67, 1.0, v67
	v_rcp_f32_e32 v66, v66
	v_rcp_f32_e32 v67, v67
	s_nop 0
	v_pk_mul_f32 v[60:61], v[60:61], v[66:67]
	s_nop 0
	v_pk_mul_f32 v[56:57], v[56:57], v[60:61]
	v_mul_f32_e32 v60, 0xbfb8aa3b, v62
	v_mul_f32_e32 v61, 0xbfb8aa3b, v63
	v_exp_f32_e32 v60, v60
	v_exp_f32_e32 v61, v61
	v_cvt_pk_bf16_f32 v56, v56, v57
	v_add_f32_e32 v60, 1.0, v60
	v_add_f32_e32 v61, 1.0, v61
	v_rcp_f32_e32 v60, v60
	v_rcp_f32_e32 v61, v61
	s_nop 0
	v_pk_mul_f32 v[60:61], v[62:63], v[60:61]
	s_nop 0
	v_pk_mul_f32 v[58:59], v[58:59], v[60:61]
	s_nop 0
	v_cvt_pk_bf16_f32 v57, v58, v59
	v_lshl_add_u64 v[58:59], v[64:65], 0, s[0:1]
	v_mov_b32_e32 v250, v56
	v_mov_b32_e32 v251, v57
	v_mul_f32_e32 v56, 0xbfb8aa3b, v52
	v_mul_f32_e32 v57, 0xbfb8aa3b, v53
	v_exp_f32_e32 v56, v56
	v_exp_f32_e32 v57, v57
	v_add_f32_e32 v56, 1.0, v56
	v_add_f32_e32 v57, 1.0, v57
	v_rcp_f32_e32 v56, v56
	v_rcp_f32_e32 v57, v57
	s_nop 0
	v_pk_mul_f32 v[52:53], v[52:53], v[56:57]
	s_nop 0
	v_pk_mul_f32 v[48:49], v[48:49], v[52:53]
	v_mul_f32_e32 v52, 0xbfb8aa3b, v54
	v_mul_f32_e32 v53, 0xbfb8aa3b, v55
	v_exp_f32_e32 v52, v52
	v_exp_f32_e32 v53, v53
	v_cvt_pk_bf16_f32 v48, v48, v49
	v_add_f32_e32 v52, 1.0, v52
	v_add_f32_e32 v53, 1.0, v53
	v_rcp_f32_e32 v52, v52
	v_rcp_f32_e32 v53, v53
	s_nop 0
	v_pk_mul_f32 v[52:53], v[54:55], v[52:53]
	s_nop 0
	v_pk_mul_f32 v[50:51], v[50:51], v[52:53]
	s_nop 0
	v_cvt_pk_bf16_f32 v49, v50, v51
	v_mul_f32_e32 v50, 0xbfb8aa3b, v44
	v_mul_f32_e32 v51, 0xbfb8aa3b, v45
	v_exp_f32_e32 v50, v50
	v_exp_f32_e32 v51, v51
	v_mov_b32_e32 v252, v48
	v_mov_b32_e32 v253, v49
	v_lshl_add_u64 v[254:255], v[58:59], 0, v[248:249]
	s_nop 0
	v_permlane16_swap_b32_e32 v250, v252
	v_permlane16_swap_b32_e32 v251, v253
	global_store_dwordx4 v[254:255], v[250:253], off sc0 sc1
	v_mad_i64_i32 v[48:49], s[12:13], v176, s18, v[128:129]
	v_add_f32_e32 v50, 1.0, v50
	v_add_f32_e32 v51, 1.0, v51
	v_rcp_f32_e32 v50, v50
	v_rcp_f32_e32 v51, v51
	s_nop 0
	v_pk_mul_f32 v[44:45], v[44:45], v[50:51]
	s_nop 0
	v_pk_mul_f32 v[40:41], v[40:41], v[44:45]
	v_mul_f32_e32 v44, 0xbfb8aa3b, v46
	v_mul_f32_e32 v45, 0xbfb8aa3b, v47
	v_exp_f32_e32 v44, v44
	v_exp_f32_e32 v45, v45
	v_cvt_pk_bf16_f32 v40, v40, v41
	v_add_f32_e32 v44, 1.0, v44
	v_add_f32_e32 v45, 1.0, v45
	v_rcp_f32_e32 v44, v44
	v_rcp_f32_e32 v45, v45
	s_nop 0
	v_pk_mul_f32 v[44:45], v[46:47], v[44:45]
	s_nop 0
	v_pk_mul_f32 v[42:43], v[42:43], v[44:45]
	s_nop 0
	v_cvt_pk_bf16_f32 v41, v42, v43
	v_lshl_add_u64 v[42:43], v[48:49], 0, s[0:1]
	v_mov_b32_e32 v250, v40
	v_mov_b32_e32 v251, v41
; #define GAS __attribute__((address_space(1)))
; __device__ __forceinline__ unsigned pk2(float lo, float hi) { const f32x2 v = {lo, hi}; return __builtin_bit_cast(unsigned, __builtin_convertvector(v, hwbf16x2)); }
; __device__ __forceinline__ float silu_f(float x) { return x * fast_rcp(1.0f + __expf(-x)); }
; template <int MODE, bool SMALL>
; __device__ __forceinline__ float epi_apply(const EpiArgs& a, int row, int g32, int fq, f32x4 v0, f32x4 v1, float rstd) {
;     ...
;         v0 *= rstd; v1 *= rstd;
;         float h[4];
; #pragma unroll
;         for (int j = 0; j < 4; ++j) h[j] = silu_f(v0[j]) * v1[j];
;         u32x2 w; w.x = pk2(h[0], h[1]); w.y = pk2(h[2], h[3]);
;         *(GAS u32x2*)(a.out + (size_t)row * DFF + 16 * g32 + 4 * fq) = w;
;     __device__ __forceinline__ void operator()(const f32x4 (&acc)[2][2][4][2], const pg8::Unit& u, int wr, int wc, int fr, int fq) const {
;     ...
; #pragma unroll
;             for (int ai = 0; ai < 2; ++ai)
; #pragma unroll
;                 for (int m = 0; m < 4; ++m) {
;                     const int row = u.pm * 256 + ai * 128 + wr * 64 + m * 16 + fr;
; #pragma unroll
;                     for (int bj = 0; bj < 2; ++bj) { const int g32 = (u.pn * 256 + bj * 128 + wc * 32) >> 5; (void)epi_apply<MODE, false>(a, row, g32, fq, acc[ai][bj][m][0], acc[ai][bj][m][1], rs[ai][m]); }
	v_mul_f32_e32 v40, 0xbfb8aa3b, v36
	v_mul_f32_e32 v41, 0xbfb8aa3b, v37
	v_exp_f32_e32 v40, v40
	v_exp_f32_e32 v41, v41
	v_add_f32_e32 v40, 1.0, v40
	v_add_f32_e32 v41, 1.0, v41
	v_rcp_f32_e32 v40, v40
	v_rcp_f32_e32 v41, v41
	s_nop 0
	v_pk_mul_f32 v[36:37], v[36:37], v[40:41]
	s_nop 0
	v_pk_mul_f32 v[32:33], v[32:33], v[36:37]
	v_mul_f32_e32 v36, 0xbfb8aa3b, v38
	v_mul_f32_e32 v37, 0xbfb8aa3b, v39
	v_exp_f32_e32 v36, v36
	v_exp_f32_e32 v37, v37
	v_cvt_pk_bf16_f32 v32, v32, v33
	v_add_f32_e32 v36, 1.0, v36
	v_add_f32_e32 v37, 1.0, v37
	v_rcp_f32_e32 v36, v36
	v_rcp_f32_e32 v37, v37
	s_nop 0
	v_pk_mul_f32 v[36:37], v[38:39], v[36:37]
	s_nop 0
	v_pk_mul_f32 v[34:35], v[34:35], v[36:37]
	s_nop 0
	v_cvt_pk_bf16_f32 v33, v34, v35
	v_mul_f32_e32 v34, 0xbfb8aa3b, v28
	v_mul_f32_e32 v35, 0xbfb8aa3b, v29
	v_exp_f32_e32 v34, v34
	v_exp_f32_e32 v35, v35
	v_mov_b32_e32 v252, v32
	v_mov_b32_e32 v253, v33
	v_lshl_add_u64 v[254:255], v[42:43], 0, v[248:249]
	s_nop 0
	v_permlane16_swap_b32_e32 v250, v252
	v_permlane16_swap_b32_e32 v251, v253
	global_store_dwordx4 v[254:255], v[250:253], off sc0 sc1
	v_mad_i64_i32 v[32:33], s[12:13], v174, s18, v[128:129]
	v_add_f32_e32 v34, 1.0, v34
	v_add_f32_e32 v35, 1.0, v35
	v_rcp_f32_e32 v34, v34
	v_rcp_f32_e32 v35, v35
	s_nop 0
	v_pk_mul_f32 v[28:29], v[28:29], v[34:35]
	s_nop 0
	v_pk_mul_f32 v[24:25], v[24:25], v[28:29]
	v_mul_f32_e32 v28, 0xbfb8aa3b, v30
	v_mul_f32_e32 v29, 0xbfb8aa3b, v31
	v_exp_f32_e32 v28, v28
	v_exp_f32_e32 v29, v29
	v_cvt_pk_bf16_f32 v24, v24, v25
	v_add_f32_e32 v28, 1.0, v28
	v_add_f32_e32 v29, 1.0, v29
	v_rcp_f32_e32 v28, v28
	v_rcp_f32_e32 v29, v29
	s_nop 0
	v_pk_mul_f32 v[28:29], v[30:31], v[28:29]
	s_nop 0
	v_pk_mul_f32 v[26:27], v[26:27], v[28:29]
	s_nop 0
	v_cvt_pk_bf16_f32 v25, v26, v27
	v_lshl_add_u64 v[26:27], v[32:33], 0, s[0:1]
	v_mov_b32_e32 v250, v24
	v_mov_b32_e32 v251, v25
	v_mul_f32_e32 v24, 0xbfb8aa3b, v20
	v_mul_f32_e32 v25, 0xbfb8aa3b, v21
	v_exp_f32_e32 v24, v24
	v_exp_f32_e32 v25, v25
	v_add_f32_e32 v24, 1.0, v24
	v_add_f32_e32 v25, 1.0, v25
	v_rcp_f32_e32 v24, v24
	v_rcp_f32_e32 v25, v25
	s_nop 0
	v_pk_mul_f32 v[20:21], v[20:21], v[24:25]
	s_nop 0
	v_pk_mul_f32 v[16:17], v[16:17], v[20:21]
	v_mul_f32_e32 v20, 0xbfb8aa3b, v22
	v_mul_f32_e32 v21, 0xbfb8aa3b, v23
	v_exp_f32_e32 v20, v20
	v_exp_f32_e32 v21, v21
	v_cvt_pk_bf16_f32 v16, v16, v17
	v_add_f32_e32 v20, 1.0, v20
	v_add_f32_e32 v21, 1.0, v21
	v_rcp_f32_e32 v20, v20
	v_rcp_f32_e32 v21, v21
	s_nop 0
	v_pk_mul_f32 v[20:21], v[22:23], v[20:21]
	s_nop 0
	v_pk_mul_f32 v[18:19], v[18:19], v[20:21]
	s_nop 0
	v_cvt_pk_bf16_f32 v17, v18, v19
	v_mul_f32_e32 v18, 0xbfb8aa3b, v12
	v_mul_f32_e32 v19, 0xbfb8aa3b, v13
	v_exp_f32_e32 v18, v18
	v_exp_f32_e32 v19, v19
	v_mov_b32_e32 v252, v16
	v_mov_b32_e32 v253, v17
	v_lshl_add_u64 v[254:255], v[26:27], 0, v[248:249]
	s_nop 0
	v_permlane16_swap_b32_e32 v250, v252
	v_permlane16_swap_b32_e32 v251, v253
	global_store_dwordx4 v[254:255], v[250:253], off sc0 sc1
	v_mad_i64_i32 v[16:17], s[12:13], v172, s18, v[128:129]
	v_add_f32_e32 v18, 1.0, v18
	v_add_f32_e32 v19, 1.0, v19
	v_rcp_f32_e32 v18, v18
	v_rcp_f32_e32 v19, v19
	s_nop 0
	v_pk_mul_f32 v[12:13], v[12:13], v[18:19]
	s_nop 0
	v_pk_mul_f32 v[8:9], v[8:9], v[12:13]
	v_mul_f32_e32 v12, 0xbfb8aa3b, v14
	v_mul_f32_e32 v13, 0xbfb8aa3b, v15
	v_exp_f32_e32 v12, v12
	v_exp_f32_e32 v13, v13
	v_cvt_pk_bf16_f32 v8, v8, v9
	v_add_f32_e32 v12, 1.0, v12
	v_add_f32_e32 v13, 1.0, v13
	v_rcp_f32_e32 v12, v12
	v_rcp_f32_e32 v13, v13
	s_nop 0
	v_pk_mul_f32 v[12:13], v[14:15], v[12:13]
	s_nop 0
	v_pk_mul_f32 v[10:11], v[10:11], v[12:13]
	s_nop 0
	v_cvt_pk_bf16_f32 v9, v10, v11
	v_lshl_add_u64 v[10:11], v[16:17], 0, s[0:1]
	v_mov_b32_e32 v250, v8
	v_mov_b32_e32 v251, v9
	v_mul_f32_e32 v8, 0xbfb8aa3b, v4
	v_mul_f32_e32 v9, 0xbfb8aa3b, v5
	v_exp_f32_e32 v8, v8
	v_exp_f32_e32 v9, v9
	s_mov_b64 s[0:1], -1
	v_add_f32_e32 v8, 1.0, v8
	v_add_f32_e32 v9, 1.0, v9
	v_rcp_f32_e32 v8, v8
	v_rcp_f32_e32 v9, v9
	s_nop 0
	v_pk_mul_f32 v[4:5], v[4:5], v[8:9]
	s_nop 0
	v_pk_mul_f32 v[0:1], v[0:1], v[4:5]
	v_mul_f32_e32 v4, 0xbfb8aa3b, v6
	v_mul_f32_e32 v5, 0xbfb8aa3b, v7
	v_exp_f32_e32 v4, v4
	v_exp_f32_e32 v5, v5
	v_cvt_pk_bf16_f32 v0, v0, v1
	v_add_f32_e32 v4, 1.0, v4
	v_add_f32_e32 v5, 1.0, v5
	v_rcp_f32_e32 v4, v4
	v_rcp_f32_e32 v5, v5
	s_nop 0
	v_pk_mul_f32 v[4:5], v[6:7], v[4:5]
	s_nop 0
	v_pk_mul_f32 v[2:3], v[2:3], v[4:5]
	s_nop 0
	v_cvt_pk_bf16_f32 v1, v2, v3
	v_mov_b32_e32 v252, v0
	v_mov_b32_e32 v253, v1
	v_lshl_add_u64 v[254:255], v[10:11], 0, v[248:249]
	s_nop 0
	v_permlane16_swap_b32_e32 v250, v252
	v_permlane16_swap_b32_e32 v251, v253
	global_store_dwordx4 v[254:255], v[250:253], off sc0 sc1
	s_cbranch_vccnz .LBB0_303
	s_andn2_b64 vcc, exec, s[64:65]
	s_cbranch_vccnz .LBB0_302
	s_barrier
	s_branch .LBB0_302

; #define GAS __attribute__((address_space(1)))
; __device__ __forceinline__ unsigned pk2(float lo, float hi) { const f32x2 v = {lo, hi}; return __builtin_bit_cast(unsigned, __builtin_convertvector(v, hwbf16x2)); }
;     __device__ __forceinline__ void operator()(const f32x4 (&acc)[2][2][4][2], const pg8::Unit& u, int wr, int wc, int fr, int fq) const {
;     ...
; #pragma unroll
;             for (int ai = 0; ai < 2; ++ai) {
;                 u32x4 bs[4][2];
; #pragma unroll
;                 for (int m = 0; m < 4; ++m)
; #pragma unroll
;                     for (int bj = 0; bj < 2; ++bj) { const int row = u.pm * 256 + ai * 128 + wr * 64 + m * 16 + fr, c0 = u.pn * 256 + bj * 128 + wc * 32 + 8 * fq;
;                         bs[m][bj] = *(const GAS u32x4*)(a.Xb + (size_t)row * DM + c0); }
; #pragma unroll
;                 for (int m = 0; m < 4; ++m) {
;                     const int row = u.pm * 256 + ai * 128 + wr * 64 + m * 16 + fr; float ss = 0.f;
; #pragma unroll
;                     for (int bj = 0; bj < 2; ++bj) { const int c0 = u.pn * 256 + bj * 128 + wc * 32 + 8 * fq; const u32x4 bw = bs[m][bj];
;                         f32x4 x0, x1;
;                         x0[0] = __builtin_bit_cast(float, bw[0] << 16); x0[1] = __builtin_bit_cast(float, bw[0] & 0xffff0000u); x0[2] = __builtin_bit_cast(float, bw[1] << 16); x0[3] = __builtin_bit_cast(float, bw[1] & 0xffff0000u);
;                         x1[0] = __builtin_bit_cast(float, bw[2] << 16); x1[1] = __builtin_bit_cast(float, bw[2] & 0xffff0000u); x1[2] = __builtin_bit_cast(float, bw[3] << 16); x1[3] = __builtin_bit_cast(float, bw[3] & 0xffff0000u);
;                         x0 += acc[ai][bj][m][0]; x1 += acc[ai][bj][m][1];
;                         u32x4 w; w.x = pk2(x0[0], x0[1]); w.y = pk2(x0[2], x0[3]); w.z = pk2(x1[0], x1[1]); w.w = pk2(x1[2], x1[3]);
;                         *(GAS u32x4*)(a.Xb + (size_t)row * DM + c0) = w;
;                         ss += ((x0[0] * x0[0] + x0[1] * x0[1]) + (x0[2] * x0[2] + x0[3] * x0[3])) + ((x1[0] * x1[0] + x1[1] * x1[1]) + (x1[2] * x1[2] + x1[3] * x1[3])); }
;                     ss += __shfl_xor(ss, 16); ss += __shfl_xor(ss, 32); if (fq == 0) a.ssp_out[(size_t)row * 16 + u.pn * 4 + wc] = ss;
.LBB0_349:
	v_and_b32_e32 v134, 64, v200
	v_readlane_b32 s13, v245, 11
	v_xor_b32_e32 v133, 16, v200
	v_add_u32_e32 v134, 64, v134
	v_mov_b32_e32 v120, s13
	v_cmp_lt_i32_e32 vcc, v133, v134
	ds_read_b128 v[120:123], v120
	v_lshl_add_u32 v174, s12, 8, v192
	v_cndmask_b32_e32 v133, v200, v133, vcc
	v_lshlrev_b32_e32 v210, 2, v133
	v_xor_b32_e32 v133, 32, v200
	v_cmp_lt_i32_e32 vcc, v133, v134
	v_lshl_or_b32 v132, s4, 8, v207
	v_ashrrev_i32_e32 v175, 31, v174
	v_cndmask_b32_e32 v133, v200, v133, vcc
	v_lshlrev_b32_e32 v209, 2, v133
	v_ashrrev_i32_e32 v133, 31, v132
	v_lshlrev_b64 v[134:135], 11, v[174:175]
	s_waitcnt lgkmcnt(0)
	v_lshl_add_u64 v[134:135], v[120:121], 0, v[134:135]
	v_lshlrev_b64 v[176:177], 1, v[132:133]
	v_lshl_add_u64 v[190:191], v[134:135], 0, v[176:177]
	global_load_dwordx4 v[214:217], v[190:191], off
	global_load_dwordx4 v[156:159], v[190:191], off offset:256
	v_or_b32_e32 v186, 16, v174
	v_ashrrev_i32_e32 v187, 31, v186
	v_lshlrev_b64 v[132:133], 11, v[186:187]
	v_or_b32_e32 v182, 32, v174
	v_lshl_add_u64 v[132:133], v[120:121], 0, v[132:133]
	v_ashrrev_i32_e32 v183, 31, v182
	v_lshl_add_u64 v[188:189], v[132:133], 0, v[176:177]
	v_lshlrev_b64 v[132:133], 11, v[182:183]
	v_or_b32_e32 v178, 48, v174
	v_lshl_add_u64 v[132:133], v[120:121], 0, v[132:133]
	v_ashrrev_i32_e32 v179, 31, v178
	v_lshl_add_u64 v[184:185], v[132:133], 0, v[176:177]
	v_lshlrev_b64 v[132:133], 11, v[178:179]
	v_lshl_add_u64 v[132:133], v[120:121], 0, v[132:133]
	v_lshl_add_u64 v[180:181], v[132:133], 0, v[176:177]
	global_load_dwordx4 v[152:155], v[188:189], off
	global_load_dwordx4 v[148:151], v[188:189], off offset:256
	global_load_dwordx4 v[144:147], v[184:185], off
	global_load_dwordx4 v[136:139], v[184:185], off offset:256
	global_load_dwordx4 v[140:143], v[180:181], off
	global_load_dwordx4 v[132:135], v[180:181], off offset:256
	s_lshl_b32 s12, s4, 2
	s_ashr_i32 s13, s12, 31
	s_lshl_b64 s[12:13], s[12:13], 2
	v_lshl_add_u64 v[122:123], v[122:123], 0, s[12:13]
	v_lshl_add_u64 v[122:123], v[122:123], 0, s[36:37]
	s_waitcnt vmcnt(0)
	v_lshlrev_b32_e32 v218, 16, v214
	v_and_b32_e32 v219, 0xffff0000, v214
	v_lshlrev_b32_e32 v214, 16, v215
	v_and_b32_e32 v215, 0xffff0000, v215
	v_lshlrev_b32_e32 v220, 16, v216
	v_and_b32_e32 v221, 0xffff0000, v216
	v_lshlrev_b32_e32 v216, 16, v217
	v_and_b32_e32 v217, 0xffff0000, v217
	v_pk_add_f32 v[130:131], v[130:131], v[214:215]
	v_pk_add_f32 v[128:129], v[128:129], v[218:219]
	v_pk_add_f32 v[214:215], v[126:127], v[216:217]
	v_pk_add_f32 v[216:217], v[124:125], v[220:221]
	v_cvt_pk_bf16_f32 v124, v128, v129
	v_cvt_pk_bf16_f32 v125, v130, v131
	v_cvt_pk_bf16_f32 v126, v216, v217
	v_cvt_pk_bf16_f32 v127, v214, v215
	global_store_dwordx4 v[190:191], v[124:127], off sc0 sc1
	s_nop 1
	v_mul_f32_e32 v124, v129, v129
	v_mul_f32_e32 v125, v131, v131
	v_fmac_f32_e32 v124, v128, v128
	v_fmac_f32_e32 v125, v130, v130
	v_add_f32_e32 v124, v124, v125
	v_mul_f32_e32 v125, v217, v217
	v_mul_f32_e32 v126, v215, v215
	v_fmac_f32_e32 v125, v216, v216
	v_fmac_f32_e32 v126, v214, v214
	v_add_f32_e32 v125, v125, v126
	v_add_f32_e32 v211, v124, v125
	v_lshlrev_b32_e32 v124, 16, v156
	v_and_b32_e32 v125, 0xffff0000, v156
	v_lshlrev_b32_e32 v126, 16, v157
	v_and_b32_e32 v127, 0xffff0000, v157
	v_lshlrev_b32_e32 v128, 16, v158
	v_and_b32_e32 v129, 0xffff0000, v158
	v_lshlrev_b32_e32 v130, 16, v159
	v_and_b32_e32 v131, 0xffff0000, v159
	v_pk_add_f32 v[118:119], v[118:119], v[126:127]
	v_pk_add_f32 v[116:117], v[116:117], v[124:125]
	v_pk_add_f32 v[124:125], v[114:115], v[130:131]
	v_pk_add_f32 v[126:127], v[112:113], v[128:129]
	v_cvt_pk_bf16_f32 v112, v116, v117
	v_cvt_pk_bf16_f32 v113, v118, v119
	v_cvt_pk_bf16_f32 v114, v126, v127
	v_cvt_pk_bf16_f32 v115, v124, v125
	global_store_dwordx4 v[190:191], v[112:115], off offset:256 sc0 sc1
	s_nop 1
	v_mul_f32_e32 v112, v117, v117
	v_mul_f32_e32 v113, v119, v119
	v_fmac_f32_e32 v112, v116, v116
	v_fmac_f32_e32 v113, v118, v118
	v_add_f32_e32 v112, v112, v113
	v_mul_f32_e32 v113, v127, v127
	v_mul_f32_e32 v114, v125, v125
	v_fmac_f32_e32 v113, v126, v126
	v_fmac_f32_e32 v114, v124, v124
	v_add_f32_e32 v113, v113, v114
	v_add_f32_e32 v112, v112, v113
	v_add_f32_e32 v112, v211, v112
	ds_bpermute_b32 v113, v210, v112
	s_waitcnt lgkmcnt(0)
	v_add_f32_e32 v112, v112, v113
	ds_bpermute_b32 v113, v209, v112
	s_and_saveexec_b64 s[18:19], s[38:39]
	s_cbranch_execz .LBB0_351
	s_waitcnt lgkmcnt(0)
	v_add_f32_e32 v114, v112, v113
	v_lshlrev_b64 v[112:113], 6, v[174:175]
	v_lshl_add_u64 v[112:113], v[122:123], 0, v[112:113]
	global_store_dword v[112:113], v114, off
; #define GAS __attribute__((address_space(1)))
; __device__ __forceinline__ unsigned pk2(float lo, float hi) { const f32x2 v = {lo, hi}; return __builtin_bit_cast(unsigned, __builtin_convertvector(v, hwbf16x2)); }
;     __device__ __forceinline__ void operator()(const f32x4 (&acc)[2][2][4][2], const pg8::Unit& u, int wr, int wc, int fr, int fq) const {
;     ...
;                 for (int m = 0; m < 4; ++m) {
;                     const int row = u.pm * 256 + ai * 128 + wr * 64 + m * 16 + fr; float ss = 0.f;
; #pragma unroll
;                     for (int bj = 0; bj < 2; ++bj) { const int c0 = u.pn * 256 + bj * 128 + wc * 32 + 8 * fq; const u32x4 bw = bs[m][bj];
;                         f32x4 x0, x1;
;                         x0[0] = __builtin_bit_cast(float, bw[0] << 16); x0[1] = __builtin_bit_cast(float, bw[0] & 0xffff0000u); x0[2] = __builtin_bit_cast(float, bw[1] << 16); x0[3] = __builtin_bit_cast(float, bw[1] & 0xffff0000u);
;                         x1[0] = __builtin_bit_cast(float, bw[2] << 16); x1[1] = __builtin_bit_cast(float, bw[2] & 0xffff0000u); x1[2] = __builtin_bit_cast(float, bw[3] << 16); x1[3] = __builtin_bit_cast(float, bw[3] & 0xffff0000u);
;                         x0 += acc[ai][bj][m][0]; x1 += acc[ai][bj][m][1];
;                         u32x4 w; w.x = pk2(x0[0], x0[1]); w.y = pk2(x0[2], x0[3]); w.z = pk2(x1[0], x1[1]); w.w = pk2(x1[2], x1[3]);
;                         *(GAS u32x4*)(a.Xb + (size_t)row * DM + c0) = w;
;                         ss += ((x0[0] * x0[0] + x0[1] * x0[1]) + (x0[2] * x0[2] + x0[3] * x0[3])) + ((x1[0] * x1[0] + x1[1] * x1[1]) + (x1[2] * x1[2] + x1[3] * x1[3])); }
;                     ss += __shfl_xor(ss, 16); ss += __shfl_xor(ss, 32); if (fq == 0) a.ssp_out[(size_t)row * 16 + u.pn * 4 + wc] = ss;
.LBB0_351:
	s_or_b64 exec, exec, s[18:19]
	v_lshlrev_b32_e32 v112, 16, v152
	s_waitcnt lgkmcnt(0)
	v_and_b32_e32 v113, 0xffff0000, v152
	v_lshlrev_b32_e32 v114, 16, v153
	v_and_b32_e32 v115, 0xffff0000, v153
	v_lshlrev_b32_e32 v116, 16, v154
	v_and_b32_e32 v117, 0xffff0000, v154
	v_lshlrev_b32_e32 v118, 16, v155
	v_and_b32_e32 v119, 0xffff0000, v155
	v_pk_add_f32 v[108:109], v[108:109], v[112:113]
	v_pk_add_f32 v[110:111], v[110:111], v[114:115]
	v_pk_add_f32 v[112:113], v[106:107], v[118:119]
	v_pk_add_f32 v[106:107], v[104:105], v[116:117]
	v_cvt_pk_bf16_f32 v104, v108, v109
	v_mul_f32_e32 v109, v109, v109
	v_fmac_f32_e32 v109, v108, v108
	v_mul_f32_e32 v108, v111, v111
	v_fmac_f32_e32 v108, v110, v110
	v_cvt_pk_bf16_f32 v105, v110, v111
	v_add_f32_e32 v108, v109, v108
	v_mul_f32_e32 v109, v107, v107
	v_mul_f32_e32 v110, v113, v113
	v_fmac_f32_e32 v109, v106, v106
	v_fmac_f32_e32 v110, v112, v112
	v_add_f32_e32 v109, v109, v110
	v_add_f32_e32 v118, v108, v109
	v_lshlrev_b32_e32 v108, 16, v148
	v_and_b32_e32 v109, 0xffff0000, v148
	v_lshlrev_b32_e32 v110, 16, v149
	v_and_b32_e32 v111, 0xffff0000, v149
	v_lshlrev_b32_e32 v114, 16, v150
	v_and_b32_e32 v115, 0xffff0000, v150
	v_pk_add_f32 v[102:103], v[102:103], v[110:111]
	v_pk_add_f32 v[100:101], v[100:101], v[108:109]
	v_lshlrev_b32_e32 v116, 16, v151
	v_and_b32_e32 v117, 0xffff0000, v151
	v_pk_add_f32 v[110:111], v[96:97], v[114:115]
	v_mul_f32_e32 v96, v101, v101
	v_mul_f32_e32 v97, v103, v103
	v_pk_add_f32 v[108:109], v[98:99], v[116:117]
	v_fmac_f32_e32 v96, v100, v100
	v_fmac_f32_e32 v97, v102, v102
	v_add_f32_e32 v96, v96, v97
	v_mul_f32_e32 v97, v111, v111
	v_mul_f32_e32 v98, v109, v109
	v_fmac_f32_e32 v97, v110, v110
	v_fmac_f32_e32 v98, v108, v108
	v_add_f32_e32 v97, v97, v98
	v_add_f32_e32 v96, v96, v97
	v_add_f32_e32 v96, v118, v96
	ds_bpermute_b32 v97, v210, v96
	v_cvt_pk_bf16_f32 v106, v106, v107
	v_cvt_pk_bf16_f32 v107, v112, v113
	v_cvt_pk_bf16_f32 v98, v100, v101
	v_cvt_pk_bf16_f32 v99, v102, v103
	s_waitcnt lgkmcnt(0)
	v_add_f32_e32 v96, v96, v97
	ds_bpermute_b32 v97, v209, v96
	v_cvt_pk_bf16_f32 v100, v110, v111
	v_cvt_pk_bf16_f32 v101, v108, v109
	global_store_dwordx4 v[188:189], v[104:107], off sc0 sc1
	global_store_dwordx4 v[188:189], v[98:101], off offset:256 sc0 sc1
	s_and_saveexec_b64 s[18:19], s[38:39]
	s_cbranch_execz .LBB0_353
	s_waitcnt lgkmcnt(0)
	v_add_f32_e32 v98, v96, v97
	v_lshlrev_b64 v[96:97], 6, v[186:187]
	v_lshl_add_u64 v[96:97], v[122:123], 0, v[96:97]
	global_store_dword v[96:97], v98, off
.LBB0_353:
	s_or_b64 exec, exec, s[18:19]
	v_lshlrev_b32_e32 v96, 16, v144
	s_waitcnt lgkmcnt(0)
	v_and_b32_e32 v97, 0xffff0000, v144
	v_lshlrev_b32_e32 v98, 16, v145
	v_and_b32_e32 v99, 0xffff0000, v145
	v_lshlrev_b32_e32 v100, 16, v146
	v_and_b32_e32 v101, 0xffff0000, v146
	v_lshlrev_b32_e32 v102, 16, v147
	v_and_b32_e32 v103, 0xffff0000, v147
	v_pk_add_f32 v[92:93], v[92:93], v[96:97]
	v_pk_add_f32 v[94:95], v[94:95], v[98:99]
	v_pk_add_f32 v[96:97], v[90:91], v[102:103]
	v_pk_add_f32 v[90:91], v[88:89], v[100:101]
	v_cvt_pk_bf16_f32 v88, v92, v93
	v_mul_f32_e32 v93, v93, v93
	v_fmac_f32_e32 v93, v92, v92
	v_mul_f32_e32 v92, v95, v95
	v_fmac_f32_e32 v92, v94, v94
	v_cvt_pk_bf16_f32 v89, v94, v95
	v_add_f32_e32 v92, v93, v92
	v_mul_f32_e32 v93, v91, v91
	v_mul_f32_e32 v94, v97, v97
	v_fmac_f32_e32 v93, v90, v90
	v_fmac_f32_e32 v94, v96, v96
	v_add_f32_e32 v93, v93, v94
	v_add_f32_e32 v102, v92, v93
	v_lshlrev_b32_e32 v92, 16, v136
	v_and_b32_e32 v93, 0xffff0000, v136
	v_lshlrev_b32_e32 v94, 16, v137
	v_and_b32_e32 v95, 0xffff0000, v137
	v_lshlrev_b32_e32 v98, 16, v138
	v_and_b32_e32 v99, 0xffff0000, v138
	v_pk_add_f32 v[86:87], v[86:87], v[94:95]
	v_pk_add_f32 v[84:85], v[84:85], v[92:93]
	v_lshlrev_b32_e32 v100, 16, v139
	v_and_b32_e32 v101, 0xffff0000, v139
	v_pk_add_f32 v[94:95], v[80:81], v[98:99]
	v_mul_f32_e32 v80, v85, v85
	v_mul_f32_e32 v81, v87, v87
	v_pk_add_f32 v[92:93], v[82:83], v[100:101]
	v_fmac_f32_e32 v80, v84, v84
	v_fmac_f32_e32 v81, v86, v86
	v_add_f32_e32 v80, v80, v81
	v_mul_f32_e32 v81, v95, v95
	v_mul_f32_e32 v82, v93, v93
	v_fmac_f32_e32 v81, v94, v94
	v_fmac_f32_e32 v82, v92, v92
	v_add_f32_e32 v81, v81, v82
	v_add_f32_e32 v80, v80, v81
	v_add_f32_e32 v80, v102, v80
	ds_bpermute_b32 v81, v210, v80
	v_cvt_pk_bf16_f32 v90, v90, v91
	v_cvt_pk_bf16_f32 v91, v96, v97
	v_cvt_pk_bf16_f32 v82, v84, v85
	v_cvt_pk_bf16_f32 v83, v86, v87
	s_waitcnt lgkmcnt(0)
	v_add_f32_e32 v80, v80, v81
	ds_bpermute_b32 v81, v209, v80
	v_cvt_pk_bf16_f32 v84, v94, v95
	v_cvt_pk_bf16_f32 v85, v92, v93
	global_store_dwordx4 v[184:185], v[88:91], off sc0 sc1
	global_store_dwordx4 v[184:185], v[82:85], off offset:256 sc0 sc1
	s_and_saveexec_b64 s[18:19], s[38:39]
	s_cbranch_execz .LBB0_355
	s_waitcnt lgkmcnt(0)
	v_add_f32_e32 v82, v80, v81
	v_lshlrev_b64 v[80:81], 6, v[182:183]
	v_lshl_add_u64 v[80:81], v[122:123], 0, v[80:81]
	global_store_dword v[80:81], v82, off
; #define GAS __attribute__((address_space(1)))
; __device__ __forceinline__ unsigned pk2(float lo, float hi) { const f32x2 v = {lo, hi}; return __builtin_bit_cast(unsigned, __builtin_convertvector(v, hwbf16x2)); }
;     __device__ __forceinline__ void operator()(const f32x4 (&acc)[2][2][4][2], const pg8::Unit& u, int wr, int wc, int fr, int fq) const {
;     ...
;             for (int ai = 0; ai < 2; ++ai) {
;                 u32x4 bs[4][2];
; #pragma unroll
;                 for (int m = 0; m < 4; ++m)
; #pragma unroll
;                     for (int bj = 0; bj < 2; ++bj) { const int row = u.pm * 256 + ai * 128 + wr * 64 + m * 16 + fr, c0 = u.pn * 256 + bj * 128 + wc * 32 + 8 * fq;
;                         bs[m][bj] = *(const GAS u32x4*)(a.Xb + (size_t)row * DM + c0); }
; #pragma unroll
;                 for (int m = 0; m < 4; ++m) {
;                     const int row = u.pm * 256 + ai * 128 + wr * 64 + m * 16 + fr; float ss = 0.f;
; #pragma unroll
;                     for (int bj = 0; bj < 2; ++bj) { const int c0 = u.pn * 256 + bj * 128 + wc * 32 + 8 * fq; const u32x4 bw = bs[m][bj];
;                         f32x4 x0, x1;
;                         x0[0] = __builtin_bit_cast(float, bw[0] << 16); x0[1] = __builtin_bit_cast(float, bw[0] & 0xffff0000u); x0[2] = __builtin_bit_cast(float, bw[1] << 16); x0[3] = __builtin_bit_cast(float, bw[1] & 0xffff0000u);
;                         x1[0] = __builtin_bit_cast(float, bw[2] << 16); x1[1] = __builtin_bit_cast(float, bw[2] & 0xffff0000u); x1[2] = __builtin_bit_cast(float, bw[3] << 16); x1[3] = __builtin_bit_cast(float, bw[3] & 0xffff0000u);
;                         x0 += acc[ai][bj][m][0]; x1 += acc[ai][bj][m][1];
;                         u32x4 w; w.x = pk2(x0[0], x0[1]); w.y = pk2(x0[2], x0[3]); w.z = pk2(x1[0], x1[1]); w.w = pk2(x1[2], x1[3]);
;                         *(GAS u32x4*)(a.Xb + (size_t)row * DM + c0) = w;
;                         ss += ((x0[0] * x0[0] + x0[1] * x0[1]) + (x0[2] * x0[2] + x0[3] * x0[3])) + ((x1[0] * x1[0] + x1[1] * x1[1]) + (x1[2] * x1[2] + x1[3] * x1[3])); }
;                     ss += __shfl_xor(ss, 16); ss += __shfl_xor(ss, 32); if (fq == 0) a.ssp_out[(size_t)row * 16 + u.pn * 4 + wc] = ss;
.LBB0_355:
	s_or_b64 exec, exec, s[18:19]
	v_lshlrev_b32_e32 v80, 16, v140
	s_waitcnt lgkmcnt(0)
	v_and_b32_e32 v81, 0xffff0000, v140
	v_lshlrev_b32_e32 v82, 16, v141
	v_and_b32_e32 v83, 0xffff0000, v141
	v_lshlrev_b32_e32 v84, 16, v142
	v_and_b32_e32 v85, 0xffff0000, v142
	v_lshlrev_b32_e32 v86, 16, v143
	v_and_b32_e32 v87, 0xffff0000, v143
	v_pk_add_f32 v[76:77], v[76:77], v[80:81]
	v_pk_add_f32 v[78:79], v[78:79], v[82:83]
	v_pk_add_f32 v[80:81], v[74:75], v[86:87]
	v_pk_add_f32 v[74:75], v[72:73], v[84:85]
	v_cvt_pk_bf16_f32 v72, v76, v77
	v_mul_f32_e32 v77, v77, v77
	v_fmac_f32_e32 v77, v76, v76
	v_mul_f32_e32 v76, v79, v79
	v_fmac_f32_e32 v76, v78, v78
	v_cvt_pk_bf16_f32 v73, v78, v79
	v_add_f32_e32 v76, v77, v76
	v_mul_f32_e32 v77, v75, v75
	v_mul_f32_e32 v78, v81, v81
	v_fmac_f32_e32 v77, v74, v74
	v_fmac_f32_e32 v78, v80, v80
	v_add_f32_e32 v77, v77, v78
	v_add_f32_e32 v86, v76, v77
	v_lshlrev_b32_e32 v76, 16, v132
	v_and_b32_e32 v77, 0xffff0000, v132
	v_lshlrev_b32_e32 v78, 16, v133
	v_and_b32_e32 v79, 0xffff0000, v133
	v_lshlrev_b32_e32 v82, 16, v134
	v_and_b32_e32 v83, 0xffff0000, v134
	v_pk_add_f32 v[70:71], v[70:71], v[78:79]
	v_pk_add_f32 v[68:69], v[68:69], v[76:77]
	v_lshlrev_b32_e32 v84, 16, v135
	v_and_b32_e32 v85, 0xffff0000, v135
	v_pk_add_f32 v[78:79], v[64:65], v[82:83]
	v_mul_f32_e32 v64, v69, v69
	v_mul_f32_e32 v65, v71, v71
	v_pk_add_f32 v[76:77], v[66:67], v[84:85]
	v_fmac_f32_e32 v64, v68, v68
	v_fmac_f32_e32 v65, v70, v70
	v_add_f32_e32 v64, v64, v65
	v_mul_f32_e32 v65, v79, v79
	v_mul_f32_e32 v66, v77, v77
	v_fmac_f32_e32 v65, v78, v78
	v_fmac_f32_e32 v66, v76, v76
	v_add_f32_e32 v65, v65, v66
	v_add_f32_e32 v64, v64, v65
	v_add_f32_e32 v64, v86, v64
	ds_bpermute_b32 v65, v210, v64
	v_cvt_pk_bf16_f32 v74, v74, v75
	v_cvt_pk_bf16_f32 v75, v80, v81
	v_cvt_pk_bf16_f32 v66, v68, v69
	v_cvt_pk_bf16_f32 v67, v70, v71
	s_waitcnt lgkmcnt(0)
	v_add_f32_e32 v64, v64, v65
	ds_bpermute_b32 v65, v209, v64
	v_cvt_pk_bf16_f32 v68, v78, v79
	v_cvt_pk_bf16_f32 v69, v76, v77
	global_store_dwordx4 v[180:181], v[72:75], off sc0 sc1
	global_store_dwordx4 v[180:181], v[66:69], off offset:256 sc0 sc1
	s_and_saveexec_b64 s[18:19], s[38:39]
	s_cbranch_execz .LBB0_357
	s_waitcnt lgkmcnt(0)
	v_add_f32_e32 v66, v64, v65
	v_lshlrev_b64 v[64:65], 6, v[178:179]
	v_lshl_add_u64 v[64:65], v[122:123], 0, v[64:65]
	global_store_dword v[64:65], v66, off
.LBB0_357:
	s_or_b64 exec, exec, s[18:19]
	v_add_u32_e32 v104, 0x80, v174
	v_ashrrev_i32_e32 v105, 31, v104
	s_waitcnt lgkmcnt(0)
	v_lshlrev_b64 v[64:65], 11, v[104:105]
	v_lshl_add_u64 v[64:65], v[120:121], 0, v[64:65]
	v_lshl_add_u64 v[106:107], v[64:65], 0, v[176:177]
	global_load_dwordx4 v[108:111], v[106:107], off
	global_load_dwordx4 v[88:91], v[106:107], off offset:256
	v_add_u32_e32 v100, 0x90, v174
	v_ashrrev_i32_e32 v101, 31, v100
	v_lshlrev_b64 v[64:65], 11, v[100:101]
	v_add_u32_e32 v96, 0xa0, v174
	v_lshl_add_u64 v[64:65], v[120:121], 0, v[64:65]
	v_ashrrev_i32_e32 v97, 31, v96
	v_lshl_add_u64 v[102:103], v[64:65], 0, v[176:177]
	v_lshlrev_b64 v[64:65], 11, v[96:97]
	v_add_u32_e32 v92, 0xb0, v174
	v_lshl_add_u64 v[64:65], v[120:121], 0, v[64:65]
	v_ashrrev_i32_e32 v93, 31, v92
	v_lshl_add_u64 v[98:99], v[64:65], 0, v[176:177]
	v_lshlrev_b64 v[64:65], 11, v[92:93]
	v_lshl_add_u64 v[64:65], v[120:121], 0, v[64:65]
	v_lshl_add_u64 v[94:95], v[64:65], 0, v[176:177]
	global_load_dwordx4 v[84:87], v[102:103], off
	global_load_dwordx4 v[80:83], v[102:103], off offset:256
	global_load_dwordx4 v[76:79], v[98:99], off
	global_load_dwordx4 v[68:71], v[98:99], off offset:256
	global_load_dwordx4 v[72:75], v[94:95], off
	global_load_dwordx4 v[64:67], v[94:95], off offset:256
	s_waitcnt vmcnt(7)
	v_lshlrev_b32_e32 v112, 16, v108
	v_and_b32_e32 v113, 0xffff0000, v108
	v_lshlrev_b32_e32 v108, 16, v109
	v_and_b32_e32 v109, 0xffff0000, v109
	v_lshlrev_b32_e32 v114, 16, v110
	v_and_b32_e32 v115, 0xffff0000, v110
	v_lshlrev_b32_e32 v110, 16, v111
	v_and_b32_e32 v111, 0xffff0000, v111
	v_pk_add_f32 v[62:63], v[62:63], v[108:109]
	v_pk_add_f32 v[60:61], v[60:61], v[112:113]
	v_pk_add_f32 v[108:109], v[58:59], v[110:111]
	v_pk_add_f32 v[110:111], v[56:57], v[114:115]
	v_cvt_pk_bf16_f32 v56, v60, v61
	v_cvt_pk_bf16_f32 v57, v62, v63
	v_cvt_pk_bf16_f32 v58, v110, v111
	v_cvt_pk_bf16_f32 v59, v108, v109
	global_store_dwordx4 v[106:107], v[56:59], off sc0 sc1
	s_nop 1
	v_mul_f32_e32 v56, v61, v61
	v_mul_f32_e32 v57, v63, v63
	v_fmac_f32_e32 v56, v60, v60
	v_fmac_f32_e32 v57, v62, v62
	v_add_f32_e32 v56, v56, v57
	v_mul_f32_e32 v57, v111, v111
	v_mul_f32_e32 v58, v109, v109
	v_fmac_f32_e32 v57, v110, v110
	v_fmac_f32_e32 v58, v108, v108
	v_add_f32_e32 v57, v57, v58
	v_add_f32_e32 v108, v56, v57
	s_waitcnt vmcnt(7)
	v_lshlrev_b32_e32 v56, 16, v88
	v_and_b32_e32 v57, 0xffff0000, v88
	v_lshlrev_b32_e32 v58, 16, v89
	v_and_b32_e32 v59, 0xffff0000, v89
	v_lshlrev_b32_e32 v60, 16, v90
	v_and_b32_e32 v61, 0xffff0000, v90
	v_lshlrev_b32_e32 v62, 16, v91
	v_and_b32_e32 v63, 0xffff0000, v91
	v_pk_add_f32 v[54:55], v[54:55], v[58:59]
	v_pk_add_f32 v[52:53], v[52:53], v[56:57]
	v_pk_add_f32 v[56:57], v[50:51], v[62:63]
	v_pk_add_f32 v[58:59], v[48:49], v[60:61]
	v_cvt_pk_bf16_f32 v48, v52, v53
	v_cvt_pk_bf16_f32 v49, v54, v55
	v_cvt_pk_bf16_f32 v50, v58, v59
	v_cvt_pk_bf16_f32 v51, v56, v57
	global_store_dwordx4 v[106:107], v[48:51], off offset:256 sc0 sc1
	s_nop 1
	v_mul_f32_e32 v48, v53, v53
	v_mul_f32_e32 v49, v55, v55
	v_fmac_f32_e32 v48, v52, v52
	v_fmac_f32_e32 v49, v54, v54
	v_add_f32_e32 v48, v48, v49
	v_mul_f32_e32 v49, v59, v59
	v_mul_f32_e32 v50, v57, v57
	v_fmac_f32_e32 v49, v58, v58
	v_fmac_f32_e32 v50, v56, v56
	v_add_f32_e32 v49, v49, v50
	v_add_f32_e32 v48, v48, v49
	v_add_f32_e32 v48, v108, v48
	ds_bpermute_b32 v49, v210, v48
	s_waitcnt lgkmcnt(0)
	v_add_f32_e32 v48, v48, v49
	ds_bpermute_b32 v49, v209, v48
	s_and_saveexec_b64 s[18:19], s[38:39]
	s_cbranch_execz .LBB0_359
	s_waitcnt lgkmcnt(0)
	v_add_f32_e32 v50, v48, v49
	v_lshlrev_b64 v[48:49], 6, v[104:105]
	v_lshl_add_u64 v[48:49], v[122:123], 0, v[48:49]
	global_store_dword v[48:49], v50, off
; #define GAS __attribute__((address_space(1)))
; __device__ __forceinline__ unsigned pk2(float lo, float hi) { const f32x2 v = {lo, hi}; return __builtin_bit_cast(unsigned, __builtin_convertvector(v, hwbf16x2)); }
;     __device__ __forceinline__ void operator()(const f32x4 (&acc)[2][2][4][2], const pg8::Unit& u, int wr, int wc, int fr, int fq) const {
;     ...
;                 for (int m = 0; m < 4; ++m) {
;                     const int row = u.pm * 256 + ai * 128 + wr * 64 + m * 16 + fr; float ss = 0.f;
; #pragma unroll
;                     for (int bj = 0; bj < 2; ++bj) { const int c0 = u.pn * 256 + bj * 128 + wc * 32 + 8 * fq; const u32x4 bw = bs[m][bj];
;                         f32x4 x0, x1;
;                         x0[0] = __builtin_bit_cast(float, bw[0] << 16); x0[1] = __builtin_bit_cast(float, bw[0] & 0xffff0000u); x0[2] = __builtin_bit_cast(float, bw[1] << 16); x0[3] = __builtin_bit_cast(float, bw[1] & 0xffff0000u);
;                         x1[0] = __builtin_bit_cast(float, bw[2] << 16); x1[1] = __builtin_bit_cast(float, bw[2] & 0xffff0000u); x1[2] = __builtin_bit_cast(float, bw[3] << 16); x1[3] = __builtin_bit_cast(float, bw[3] & 0xffff0000u);
;                         x0 += acc[ai][bj][m][0]; x1 += acc[ai][bj][m][1];
;                         u32x4 w; w.x = pk2(x0[0], x0[1]); w.y = pk2(x0[2], x0[3]); w.z = pk2(x1[0], x1[1]); w.w = pk2(x1[2], x1[3]);
;                         *(GAS u32x4*)(a.Xb + (size_t)row * DM + c0) = w;
;                         ss += ((x0[0] * x0[0] + x0[1] * x0[1]) + (x0[2] * x0[2] + x0[3] * x0[3])) + ((x1[0] * x1[0] + x1[1] * x1[1]) + (x1[2] * x1[2] + x1[3] * x1[3])); }
;                     ss += __shfl_xor(ss, 16); ss += __shfl_xor(ss, 32); if (fq == 0) a.ssp_out[(size_t)row * 16 + u.pn * 4 + wc] = ss;
.LBB0_359:
	s_or_b64 exec, exec, s[18:19]
	s_waitcnt vmcnt(7)
	v_lshlrev_b32_e32 v48, 16, v84
	s_waitcnt lgkmcnt(0)
	v_and_b32_e32 v49, 0xffff0000, v84
	v_lshlrev_b32_e32 v50, 16, v85
	v_and_b32_e32 v51, 0xffff0000, v85
	v_lshlrev_b32_e32 v52, 16, v86
	v_and_b32_e32 v53, 0xffff0000, v86
	v_lshlrev_b32_e32 v54, 16, v87
	v_and_b32_e32 v55, 0xffff0000, v87
	v_pk_add_f32 v[44:45], v[44:45], v[48:49]
	v_pk_add_f32 v[46:47], v[46:47], v[50:51]
	v_pk_add_f32 v[48:49], v[42:43], v[54:55]
	v_pk_add_f32 v[42:43], v[40:41], v[52:53]
	v_cvt_pk_bf16_f32 v40, v44, v45
	v_mul_f32_e32 v45, v45, v45
	v_fmac_f32_e32 v45, v44, v44
	v_mul_f32_e32 v44, v47, v47
	v_fmac_f32_e32 v44, v46, v46
	v_cvt_pk_bf16_f32 v41, v46, v47
	v_add_f32_e32 v44, v45, v44
	v_mul_f32_e32 v45, v43, v43
	v_mul_f32_e32 v46, v49, v49
	v_fmac_f32_e32 v45, v42, v42
	v_fmac_f32_e32 v46, v48, v48
	v_add_f32_e32 v45, v45, v46
	v_add_f32_e32 v54, v44, v45
	s_waitcnt vmcnt(6)
	v_lshlrev_b32_e32 v44, 16, v80
	v_and_b32_e32 v45, 0xffff0000, v80
	v_lshlrev_b32_e32 v46, 16, v81
	v_and_b32_e32 v47, 0xffff0000, v81
	v_lshlrev_b32_e32 v50, 16, v82
	v_and_b32_e32 v51, 0xffff0000, v82
	v_pk_add_f32 v[38:39], v[38:39], v[46:47]
	v_pk_add_f32 v[36:37], v[36:37], v[44:45]
	v_lshlrev_b32_e32 v52, 16, v83
	v_and_b32_e32 v53, 0xffff0000, v83
	v_pk_add_f32 v[46:47], v[32:33], v[50:51]
	v_mul_f32_e32 v32, v37, v37
	v_mul_f32_e32 v33, v39, v39
	v_pk_add_f32 v[44:45], v[34:35], v[52:53]
	v_fmac_f32_e32 v32, v36, v36
	v_fmac_f32_e32 v33, v38, v38
	v_add_f32_e32 v32, v32, v33
	v_mul_f32_e32 v33, v47, v47
	v_mul_f32_e32 v34, v45, v45
	v_fmac_f32_e32 v33, v46, v46
	v_fmac_f32_e32 v34, v44, v44
	v_add_f32_e32 v33, v33, v34
	v_add_f32_e32 v32, v32, v33
	v_add_f32_e32 v32, v54, v32
	ds_bpermute_b32 v33, v210, v32
	v_cvt_pk_bf16_f32 v42, v42, v43
	v_cvt_pk_bf16_f32 v43, v48, v49
	v_cvt_pk_bf16_f32 v34, v36, v37
	v_cvt_pk_bf16_f32 v35, v38, v39
	s_waitcnt lgkmcnt(0)
	v_add_f32_e32 v32, v32, v33
	ds_bpermute_b32 v33, v209, v32
	v_cvt_pk_bf16_f32 v36, v46, v47
	v_cvt_pk_bf16_f32 v37, v44, v45
	global_store_dwordx4 v[102:103], v[40:43], off sc0 sc1
	global_store_dwordx4 v[102:103], v[34:37], off offset:256 sc0 sc1
	s_and_saveexec_b64 s[18:19], s[38:39]
	s_cbranch_execz .LBB0_361
	s_waitcnt lgkmcnt(0)
	v_add_f32_e32 v34, v32, v33
	v_lshlrev_b64 v[32:33], 6, v[100:101]
	v_lshl_add_u64 v[32:33], v[122:123], 0, v[32:33]
	global_store_dword v[32:33], v34, off
; #define GAS __attribute__((address_space(1)))
; __device__ __forceinline__ unsigned pk2(float lo, float hi) { const f32x2 v = {lo, hi}; return __builtin_bit_cast(unsigned, __builtin_convertvector(v, hwbf16x2)); }
;     __device__ __forceinline__ void operator()(const f32x4 (&acc)[2][2][4][2], const pg8::Unit& u, int wr, int wc, int fr, int fq) const {
;     ...
;                 for (int m = 0; m < 4; ++m) {
;                     const int row = u.pm * 256 + ai * 128 + wr * 64 + m * 16 + fr; float ss = 0.f;
; #pragma unroll
;                     for (int bj = 0; bj < 2; ++bj) { const int c0 = u.pn * 256 + bj * 128 + wc * 32 + 8 * fq; const u32x4 bw = bs[m][bj];
;                         f32x4 x0, x1;
;                         x0[0] = __builtin_bit_cast(float, bw[0] << 16); x0[1] = __builtin_bit_cast(float, bw[0] & 0xffff0000u); x0[2] = __builtin_bit_cast(float, bw[1] << 16); x0[3] = __builtin_bit_cast(float, bw[1] & 0xffff0000u);
;                         x1[0] = __builtin_bit_cast(float, bw[2] << 16); x1[1] = __builtin_bit_cast(float, bw[2] & 0xffff0000u); x1[2] = __builtin_bit_cast(float, bw[3] << 16); x1[3] = __builtin_bit_cast(float, bw[3] & 0xffff0000u);
;                         x0 += acc[ai][bj][m][0]; x1 += acc[ai][bj][m][1];
;                         u32x4 w; w.x = pk2(x0[0], x0[1]); w.y = pk2(x0[2], x0[3]); w.z = pk2(x1[0], x1[1]); w.w = pk2(x1[2], x1[3]);
;                         *(GAS u32x4*)(a.Xb + (size_t)row * DM + c0) = w;
;                         ss += ((x0[0] * x0[0] + x0[1] * x0[1]) + (x0[2] * x0[2] + x0[3] * x0[3])) + ((x1[0] * x1[0] + x1[1] * x1[1]) + (x1[2] * x1[2] + x1[3] * x1[3])); }
;                     ss += __shfl_xor(ss, 16); ss += __shfl_xor(ss, 32); if (fq == 0) a.ssp_out[(size_t)row * 16 + u.pn * 4 + wc] = ss;
.LBB0_361:
	s_or_b64 exec, exec, s[18:19]
	s_waitcnt vmcnt(7)
	v_lshlrev_b32_e32 v32, 16, v76
	s_waitcnt lgkmcnt(0)
	v_and_b32_e32 v33, 0xffff0000, v76
	v_lshlrev_b32_e32 v34, 16, v77
	v_and_b32_e32 v35, 0xffff0000, v77
	v_lshlrev_b32_e32 v36, 16, v78
	v_and_b32_e32 v37, 0xffff0000, v78
	v_lshlrev_b32_e32 v38, 16, v79
	v_and_b32_e32 v39, 0xffff0000, v79
	v_pk_add_f32 v[28:29], v[28:29], v[32:33]
	v_pk_add_f32 v[30:31], v[30:31], v[34:35]
	v_pk_add_f32 v[32:33], v[26:27], v[38:39]
	v_pk_add_f32 v[26:27], v[24:25], v[36:37]
	v_cvt_pk_bf16_f32 v24, v28, v29
	v_mul_f32_e32 v29, v29, v29
	v_fmac_f32_e32 v29, v28, v28
	v_mul_f32_e32 v28, v31, v31
	v_fmac_f32_e32 v28, v30, v30
	v_cvt_pk_bf16_f32 v25, v30, v31
	v_add_f32_e32 v28, v29, v28
	v_mul_f32_e32 v29, v27, v27
	v_mul_f32_e32 v30, v33, v33
	v_fmac_f32_e32 v29, v26, v26
	v_fmac_f32_e32 v30, v32, v32
	v_add_f32_e32 v29, v29, v30
	v_add_f32_e32 v38, v28, v29
	s_waitcnt vmcnt(6)
	v_lshlrev_b32_e32 v28, 16, v68
	v_and_b32_e32 v29, 0xffff0000, v68
	v_lshlrev_b32_e32 v30, 16, v69
	v_and_b32_e32 v31, 0xffff0000, v69
	v_lshlrev_b32_e32 v34, 16, v70
	v_and_b32_e32 v35, 0xffff0000, v70
	v_pk_add_f32 v[22:23], v[22:23], v[30:31]
	v_pk_add_f32 v[20:21], v[20:21], v[28:29]
	v_lshlrev_b32_e32 v36, 16, v71
	v_and_b32_e32 v37, 0xffff0000, v71
	v_pk_add_f32 v[30:31], v[16:17], v[34:35]
	v_mul_f32_e32 v16, v21, v21
	v_mul_f32_e32 v17, v23, v23
	v_pk_add_f32 v[28:29], v[18:19], v[36:37]
	v_fmac_f32_e32 v16, v20, v20
	v_fmac_f32_e32 v17, v22, v22
	v_add_f32_e32 v16, v16, v17
	v_mul_f32_e32 v17, v31, v31
	v_mul_f32_e32 v18, v29, v29
	v_fmac_f32_e32 v17, v30, v30
	v_fmac_f32_e32 v18, v28, v28
	v_add_f32_e32 v17, v17, v18
	v_add_f32_e32 v16, v16, v17
	v_add_f32_e32 v16, v38, v16
	ds_bpermute_b32 v17, v210, v16
	v_cvt_pk_bf16_f32 v26, v26, v27
	v_cvt_pk_bf16_f32 v27, v32, v33
	v_cvt_pk_bf16_f32 v18, v20, v21
	v_cvt_pk_bf16_f32 v19, v22, v23
	s_waitcnt lgkmcnt(0)
	v_add_f32_e32 v16, v16, v17
	ds_bpermute_b32 v17, v209, v16
	v_cvt_pk_bf16_f32 v20, v30, v31
	v_cvt_pk_bf16_f32 v21, v28, v29
	global_store_dwordx4 v[98:99], v[24:27], off sc0 sc1
	global_store_dwordx4 v[98:99], v[18:21], off offset:256 sc0 sc1
	s_and_saveexec_b64 s[18:19], s[38:39]
	s_cbranch_execz .LBB0_363
	s_waitcnt lgkmcnt(0)
	v_add_f32_e32 v18, v16, v17
	v_lshlrev_b64 v[16:17], 6, v[96:97]
	v_lshl_add_u64 v[16:17], v[122:123], 0, v[16:17]
	global_store_dword v[16:17], v18, off
.LBB0_363:
	s_or_b64 exec, exec, s[18:19]
	s_waitcnt vmcnt(7)
	v_lshlrev_b32_e32 v16, 16, v72
	s_waitcnt lgkmcnt(0)
	v_and_b32_e32 v17, 0xffff0000, v72
	v_lshlrev_b32_e32 v18, 16, v73
	v_and_b32_e32 v19, 0xffff0000, v73
	v_lshlrev_b32_e32 v20, 16, v74
	v_and_b32_e32 v21, 0xffff0000, v74
	v_lshlrev_b32_e32 v22, 16, v75
	v_and_b32_e32 v23, 0xffff0000, v75
	v_pk_add_f32 v[12:13], v[12:13], v[16:17]
	v_pk_add_f32 v[14:15], v[14:15], v[18:19]
	v_pk_add_f32 v[16:17], v[10:11], v[22:23]
	v_pk_add_f32 v[10:11], v[8:9], v[20:21]
	v_cvt_pk_bf16_f32 v8, v12, v13
	v_mul_f32_e32 v13, v13, v13
	v_fmac_f32_e32 v13, v12, v12
	v_mul_f32_e32 v12, v15, v15
	v_fmac_f32_e32 v12, v14, v14
	v_cvt_pk_bf16_f32 v9, v14, v15
	v_add_f32_e32 v12, v13, v12
	v_mul_f32_e32 v13, v11, v11
	v_mul_f32_e32 v14, v17, v17
	v_fmac_f32_e32 v13, v10, v10
	v_fmac_f32_e32 v14, v16, v16
	v_add_f32_e32 v13, v13, v14
	v_add_f32_e32 v22, v12, v13
	s_waitcnt vmcnt(6)
	v_lshlrev_b32_e32 v12, 16, v64
	v_and_b32_e32 v13, 0xffff0000, v64
	v_lshlrev_b32_e32 v14, 16, v65
	v_and_b32_e32 v15, 0xffff0000, v65
	v_lshlrev_b32_e32 v18, 16, v66
	v_and_b32_e32 v19, 0xffff0000, v66
	v_pk_add_f32 v[6:7], v[6:7], v[14:15]
	v_pk_add_f32 v[4:5], v[4:5], v[12:13]
	v_lshlrev_b32_e32 v20, 16, v67
	v_and_b32_e32 v21, 0xffff0000, v67
	v_pk_add_f32 v[14:15], v[0:1], v[18:19]
	v_mul_f32_e32 v0, v5, v5
	v_mul_f32_e32 v1, v7, v7
	v_pk_add_f32 v[12:13], v[2:3], v[20:21]
	v_fmac_f32_e32 v0, v4, v4
	v_fmac_f32_e32 v1, v6, v6
	v_add_f32_e32 v0, v0, v1
	v_mul_f32_e32 v1, v15, v15
	v_mul_f32_e32 v2, v13, v13
	v_fmac_f32_e32 v1, v14, v14
	v_fmac_f32_e32 v2, v12, v12
	v_add_f32_e32 v1, v1, v2
	v_add_f32_e32 v0, v0, v1
	v_add_f32_e32 v0, v22, v0
	ds_bpermute_b32 v1, v210, v0
	v_cvt_pk_bf16_f32 v10, v10, v11
	v_cvt_pk_bf16_f32 v11, v16, v17
	v_cvt_pk_bf16_f32 v2, v4, v5
	v_cvt_pk_bf16_f32 v3, v6, v7
	s_waitcnt lgkmcnt(0)
	v_add_f32_e32 v0, v0, v1
	ds_bpermute_b32 v1, v209, v0
	v_cvt_pk_bf16_f32 v4, v14, v15
	v_cvt_pk_bf16_f32 v5, v12, v13
	global_store_dwordx4 v[94:95], v[8:11], off sc0 sc1
	global_store_dwordx4 v[94:95], v[2:5], off offset:256 sc0 sc1
	s_and_saveexec_b64 s[18:19], s[38:39]
	s_cbranch_execz .LBB0_365
	s_waitcnt lgkmcnt(0)
	v_add_f32_e32 v2, v0, v1
	v_lshlrev_b64 v[0:1], 6, v[92:93]
	v_lshl_add_u64 v[0:1], v[122:123], 0, v[0:1]
	global_store_dword v[0:1], v2, off

; #define GAS __attribute__((address_space(1)))
; template <int MODE, bool SMALL>
; __device__ __forceinline__ float epi_apply(const EpiArgs& a, int row, int g32, int fq, f32x4 v0, f32x4 v1, float rstd) {
;     ...
;     } else if constexpr (MODE == 1) {
;         v0 *= rstd; v1 *= rstd;
;         u32x4 w; w.x = pk2(v0[0], v0[1]); w.y = pk2(v0[2], v0[3]); w.z = pk2(v1[0], v1[1]); w.w = pk2(v1[2], v1[3]);
;         *(GAS u32x4*)(a.out + (size_t)row * NQKV + c0) = w;
;         if (c0 >= 1024) {
;             const int isv = c0 >= 2048, cc = c0 - 1024 - 1024 * isv;
;             if constexpr (!SMALL) { const int t = row & (SEQ - 1), b = row >> 12; if (t >= SEQ - 512) { GAS float* d = a.o0 + (size_t)isv * (O_CVP - O_CKP) + (size_t)(b * 512 + (t - (SEQ - 512))) * 1024 + cc; __builtin_nontemporal_store(v0, (GAS f32x4*)d); __builtin_nontemporal_store(v1, (GAS f32x4*)(d + 4)); } }
;             else { const int r = row - TP; GAS float* d = a.o2 + (size_t)isv * (O_CVS - O_CKS) + (size_t)r * 1024 + cc; *(GAS f32x4*)d = v0; *(GAS f32x4*)(d + 4) = v1; }
;         }
;     __device__ __forceinline__ void operator()(const f32x4 (&acc)[2][2][4][2], const pg8::Unit& u, int wr, int wc, int fr, int fq) const {
;     ...
;             f32x4 pq[2][4]; float rs[2][4];
; #pragma unroll
;             for (int ai = 0; ai < 2; ++ai)
; #pragma unroll
;                 for (int m = 0; m < 4; ++m) { const int row = u.pm * 256 + ai * 128 + wr * 64 + m * 16 + fr; pq[ai][m] = *(const GAS f32x4*)(a.ssp + (size_t)row * 16 + 4 * fq); }
; #pragma unroll
;             for (int ai = 0; ai < 2; ++ai)
; #pragma unroll
;                 for (int m = 0; m < 4; ++m) { float sp = (pq[ai][m][0] + pq[ai][m][1]) + (pq[ai][m][2] + pq[ai][m][3]); sp += __shfl_xor(sp, 16); sp += __shfl_xor(sp, 32); rs[ai][m] = rsqrtf(sp * (1.0f / 1024.0f) + EPS); }
; #pragma unroll
;             for (int ai = 0; ai < 2; ++ai)
; #pragma unroll
;                 for (int m = 0; m < 4; ++m) {
;                     const int row = u.pm * 256 + ai * 128 + wr * 64 + m * 16 + fr;
; #pragma unroll
;                     for (int bj = 0; bj < 2; ++bj) { const int g32 = (u.pn * 256 + bj * 128 + wc * 32) >> 5; (void)epi_apply<MODE, false>(a, row, g32, fq, acc[ai][bj][m][0], acc[ai][bj][m][1], rs[ai][m]); }
.LBB0_401:
	v_readlane_b32 s0, v245, 2
	s_lshl_b32 s27, s27, 8
	s_add_i32 s27, s27, s52
	v_mov_b32_e32 v104, s0
	ds_read_b128 v[104:107], v104
	v_readlane_b32 s0, v245, 7
	v_or_b32_e32 v172, s27, v165
	v_ashrrev_i32_e32 v173, 31, v172
	v_mov_b32_e32 v132, s0
	ds_read_b64 v[156:157], v132
	s_waitcnt lgkmcnt(0)
	v_lshl_add_u64 v[106:107], v[106:107], 0, v[160:161]
	v_lshlrev_b64 v[132:133], 6, v[172:173]
	v_or_b32_e32 v170, 16, v172
	v_lshl_add_u64 v[132:133], v[106:107], 0, v[132:133]
	v_ashrrev_i32_e32 v171, 31, v170
	global_load_dwordx4 v[174:177], v[132:133], off
	v_lshlrev_b64 v[132:133], 6, v[170:171]
	v_lshl_add_u64 v[132:133], v[106:107], 0, v[132:133]
	global_load_dwordx4 v[178:181], v[132:133], off
	v_or_b32_e32 v168, 32, v172
	v_ashrrev_i32_e32 v169, 31, v168
	v_lshlrev_b64 v[132:133], 6, v[168:169]
	v_or_b32_e32 v158, 48, v172
	v_lshl_add_u64 v[132:133], v[106:107], 0, v[132:133]
	v_ashrrev_i32_e32 v159, 31, v158
	global_load_dwordx4 v[184:187], v[132:133], off
	v_lshlrev_b64 v[132:133], 6, v[158:159]
	v_lshl_add_u64 v[132:133], v[106:107], 0, v[132:133]
	global_load_dwordx4 v[188:191], v[132:133], off
	v_add_u32_e32 v132, 0x80, v172
	v_ashrrev_i32_e32 v133, 31, v132
	v_lshlrev_b64 v[132:133], 6, v[132:133]
	v_lshl_add_u64 v[132:133], v[106:107], 0, v[132:133]
	global_load_dwordx4 v[144:147], v[132:133], off
	v_add_u32_e32 v132, 0x90, v172
	v_ashrrev_i32_e32 v133, 31, v132
	v_lshlrev_b64 v[132:133], 6, v[132:133]
	v_lshl_add_u64 v[132:133], v[106:107], 0, v[132:133]
	global_load_dwordx4 v[140:143], v[132:133], off
	v_add_u32_e32 v132, 0xa0, v172
	v_ashrrev_i32_e32 v133, 31, v132
	v_add_u32_e32 v136, 0xb0, v172
	v_lshlrev_b64 v[132:133], 6, v[132:133]
	v_ashrrev_i32_e32 v137, 31, v136
	v_lshl_add_u64 v[132:133], v[106:107], 0, v[132:133]
	v_lshlrev_b64 v[136:137], 6, v[136:137]
	global_load_dwordx4 v[132:135], v[132:133], off
	v_lshl_add_u64 v[106:107], v[106:107], 0, v[136:137]
	global_load_dwordx4 v[136:139], v[106:107], off
	v_and_b32_e32 v107, 64, v200
	v_xor_b32_e32 v106, 16, v200
	v_add_u32_e32 v107, 64, v107
	v_cmp_lt_i32_e32 vcc, v106, v107
	s_ashr_i32 s28, s27, 3
	s_and_b32 s34, s28, 0xfffffe00
	v_cndmask_b32_e32 v106, v200, v106, vcc
	v_lshlrev_b32_e32 v159, 2, v106
	v_xor_b32_e32 v106, 32, v200
	v_cmp_lt_i32_e32 vcc, v106, v107
	s_addk_i32 s34, 0xf200
	s_lshl_b32 s26, s26, 8
	v_cndmask_b32_e32 v106, v200, v106, vcc
	v_lshlrev_b32_e32 v169, 2, v106
	s_waitcnt vmcnt(0)
	v_mov_b32_e32 v106, v175
	v_mov_b32_e32 v107, v176
	v_mov_b32_e32 v175, v177
	v_pk_add_f32 v[106:107], v[106:107], v[174:175]
	v_mov_b32_e32 v174, v179
	v_mov_b32_e32 v175, v180
	v_mov_b32_e32 v179, v181
	v_pk_add_f32 v[174:175], v[174:175], v[178:179]
	v_mov_b32_e32 v177, v106
	v_mov_b32_e32 v176, v174
	v_mov_b32_e32 v106, v175
	v_pk_add_f32 v[106:107], v[176:177], v[106:107]
	ds_bpermute_b32 v175, v159, v107
	ds_bpermute_b32 v174, v159, v106
	s_waitcnt lgkmcnt(0)
	v_pk_add_f32 v[106:107], v[106:107], v[174:175]
	ds_bpermute_b32 v175, v169, v107
	ds_bpermute_b32 v174, v169, v106
	s_waitcnt lgkmcnt(0)
	v_pk_add_f32 v[106:107], v[106:107], v[174:175]
	s_nop 0
	v_pk_fma_f32 v[178:179], v[106:107], s[80:81], v[162:163] op_sel_hi:[1,0,0]
	v_mov_b32_e32 v174, v189
	v_mul_f32_e32 v106, 0x4b800000, v179
	v_cmp_gt_f32_e32 vcc, s3, v179
	v_mov_b32_e32 v175, v190
	v_mov_b32_e32 v189, v191
	v_cndmask_b32_e32 v106, v179, v106, vcc
	v_rsq_f32_e32 v106, v106
	v_pk_add_f32 v[174:175], v[174:175], v[188:189]
	v_cmp_gt_f32_e64 s[0:1], s3, v178
	v_mov_b32_e32 v176, v174
	v_mul_f32_e32 v107, 0x45800000, v106
	v_cndmask_b32_e32 v180, v106, v107, vcc
	v_mov_b32_e32 v106, v185
	v_mov_b32_e32 v107, v186
	v_mov_b32_e32 v185, v187
	v_pk_add_f32 v[106:107], v[106:107], v[184:185]
	v_pk_mul_f32 v[130:131], v[130:131], v[180:181] op_sel_hi:[1,0]
	v_mov_b32_e32 v177, v106
	v_mov_b32_e32 v106, v175
	v_pk_add_f32 v[106:107], v[176:177], v[106:107]
	ds_bpermute_b32 v175, v159, v107
	ds_bpermute_b32 v174, v159, v106
	v_pk_mul_f32 v[128:129], v[128:129], v[180:181] op_sel_hi:[1,0]
	v_pk_mul_f32 v[126:127], v[126:127], v[180:181] op_sel_hi:[1,0]
	v_pk_mul_f32 v[124:125], v[124:125], v[180:181] op_sel_hi:[1,0]
	s_waitcnt lgkmcnt(0)
	v_pk_add_f32 v[174:175], v[106:107], v[174:175]
	v_mov_b32_e32 v106, v145
	v_mov_b32_e32 v107, v146
	v_mov_b32_e32 v145, v147
	v_pk_add_f32 v[106:107], v[106:107], v[144:145]
	v_mov_b32_e32 v144, v141
	v_mov_b32_e32 v145, v142
	v_mov_b32_e32 v141, v143
	v_pk_add_f32 v[140:141], v[144:145], v[140:141]
	v_mov_b32_e32 v143, v106
	v_mov_b32_e32 v142, v140
	v_mov_b32_e32 v106, v141
	v_pk_add_f32 v[106:107], v[142:143], v[106:107]
	ds_bpermute_b32 v141, v159, v107
	ds_bpermute_b32 v140, v159, v106
	ds_bpermute_b32 v177, v169, v175
	ds_bpermute_b32 v176, v169, v174
	v_cvt_pk_bf16_f32 v144, v128, v129
	v_cvt_pk_bf16_f32 v145, v130, v131
	s_waitcnt lgkmcnt(2)
	v_pk_add_f32 v[140:141], v[106:107], v[140:141]
	v_mov_b32_e32 v106, v133
	v_mov_b32_e32 v107, v134
	v_mov_b32_e32 v133, v135
	v_pk_add_f32 v[106:107], v[106:107], v[132:133]
	v_mov_b32_e32 v132, v137
	v_mov_b32_e32 v133, v138
	v_mov_b32_e32 v137, v139
	v_pk_add_f32 v[132:133], v[132:133], v[136:137]
	v_mov_b32_e32 v135, v106
	v_mov_b32_e32 v134, v132
	v_mov_b32_e32 v106, v133
	v_pk_add_f32 v[106:107], v[134:135], v[106:107]
	ds_bpermute_b32 v133, v159, v107
	ds_bpermute_b32 v132, v159, v106
	ds_bpermute_b32 v143, v169, v141
	ds_bpermute_b32 v142, v169, v140
	v_mad_i64_i32 v[138:139], s[28:29], v172, s66, v[104:105]
	s_waitcnt lgkmcnt(2)
	v_pk_add_f32 v[132:133], v[106:107], v[132:133]
	v_and_b32_e32 v106, 0xfcf, v172
	v_cmp_gt_u32_e64 s[42:43], s72, v106
	v_add_u32_e32 v106, s34, v106
	ds_bpermute_b32 v135, v169, v133
	ds_bpermute_b32 v134, v169, v132
	v_ashrrev_i32_e32 v107, 31, v106
	v_lshlrev_b64 v[106:107], 12, v[106:107]
	v_lshl_add_u64 v[136:137], v[156:157], 0, v[106:107]
	v_or_b32_e32 v106, s26, v182
	v_ashrrev_i32_e32 v107, 31, v106
	v_cmp_gt_i32_e32 vcc, s45, v106
	v_cvt_pk_bf16_f32 v146, v124, v125
	v_cvt_pk_bf16_f32 v147, v126, v127
	v_lshl_add_u64 v[138:139], v[106:107], 1, v[138:139]
	s_nor_b64 s[40:41], vcc, s[42:43]
	global_store_dwordx4 v[138:139], v[144:147], off sc0 sc1
	s_and_saveexec_b64 s[28:29], s[40:41]
	s_cbranch_execz .LBB0_403
	s_cmpk_gt_u32 s26, 0x7ff
	s_cselect_b64 s[40:41], -1, 0
	s_and_b64 s[40:41], s[40:41], exec
	s_cselect_b32 s35, 0xfffffc00, 0
	s_cselect_b32 s36, 0x2100000, 0
	v_add_u32_e32 v146, s35, v106
	v_lshl_add_u64 v[144:145], v[136:137], 0, s[36:37]
	v_add_u32_e32 v146, 0xfffffc00, v146
	v_mov_b32_e32 v147, v161
	v_lshl_add_u64 v[144:145], v[146:147], 2, v[144:145]
	global_store_dwordx4 v[144:145], v[128:131], off nt
	global_store_dwordx4 v[144:145], v[124:127], off offset:16 nt
; #define GAS __attribute__((address_space(1)))
; __device__ __forceinline__ unsigned pk2(float lo, float hi) { const f32x2 v = {lo, hi}; return __builtin_bit_cast(unsigned, __builtin_convertvector(v, hwbf16x2)); }
; template <int MODE, bool SMALL>
; __device__ __forceinline__ float epi_apply(const EpiArgs& a, int row, int g32, int fq, f32x4 v0, f32x4 v1, float rstd) {
;     ...
;     } else if constexpr (MODE == 1) {
;         v0 *= rstd; v1 *= rstd;
;         u32x4 w; w.x = pk2(v0[0], v0[1]); w.y = pk2(v0[2], v0[3]); w.z = pk2(v1[0], v1[1]); w.w = pk2(v1[2], v1[3]);
;         *(GAS u32x4*)(a.out + (size_t)row * NQKV + c0) = w;
;         if (c0 >= 1024) {
;             const int isv = c0 >= 2048, cc = c0 - 1024 - 1024 * isv;
;             if constexpr (!SMALL) { const int t = row & (SEQ - 1), b = row >> 12; if (t >= SEQ - 512) { GAS float* d = a.o0 + (size_t)isv * (O_CVP - O_CKP) + (size_t)(b * 512 + (t - (SEQ - 512))) * 1024 + cc; __builtin_nontemporal_store(v0, (GAS f32x4*)d); __builtin_nontemporal_store(v1, (GAS f32x4*)(d + 4)); } }
;             else { const int r = row - TP; GAS float* d = a.o2 + (size_t)isv * (O_CVS - O_CKS) + (size_t)r * 1024 + cc; *(GAS f32x4*)d = v0; *(GAS f32x4*)(d + 4) = v1; }
;         }
.LBB0_403:
	s_or_b64 exec, exec, s[28:29]
	v_mov_b32_e32 v181, v180
	v_or_b32_e32 v128, 0x80, v106
	v_mov_b32_e32 v124, v180
	v_mov_b32_e32 v125, v180
	v_pk_mul_f32 v[122:123], v[122:123], v[124:125]
	v_pk_mul_f32 v[120:121], v[120:121], v[180:181]
	v_pk_mul_f32 v[118:119], v[118:119], v[124:125]
	v_pk_mul_f32 v[116:117], v[116:117], v[180:181]
	v_cmp_gt_i32_e64 s[40:41], s45, v128
	v_cvt_pk_bf16_f32 v124, v120, v121
	v_cvt_pk_bf16_f32 v125, v122, v123
	v_cvt_pk_bf16_f32 v126, v116, v117
	v_cvt_pk_bf16_f32 v127, v118, v119
	s_nor_b64 s[42:43], s[40:41], s[42:43]
	global_store_dwordx4 v[138:139], v[124:127], off offset:256 sc0 sc1
	s_and_saveexec_b64 s[28:29], s[42:43]
	s_cbranch_execz .LBB0_405
	s_cmpk_gt_u32 s26, 0x7ff
	s_cselect_b64 s[42:43], -1, 0
	s_and_b64 s[42:43], s[42:43], exec
	s_cselect_b32 s35, 0xfffffc00, 0
	s_cselect_b32 s36, 0x2100000, 0
	v_add_u32_e32 v126, s35, v106
	v_lshl_add_u64 v[124:125], v[136:137], 0, s[36:37]
	v_add_u32_e32 v126, 0xfffffc80, v126
	v_mov_b32_e32 v127, v161
	v_lshl_add_u64 v[124:125], v[126:127], 2, v[124:125]
	global_store_dwordx4 v[124:125], v[120:123], off nt
	global_store_dwordx4 v[124:125], v[116:119], off offset:16 nt
.LBB0_405:
	s_or_b64 exec, exec, s[28:29]
	s_nop 0
	v_mul_f32_e32 v116, 0x4b800000, v178
	v_cndmask_b32_e64 v116, v178, v116, s[0:1]
	v_rsq_f32_e32 v116, v116
	v_and_b32_e32 v117, 0xfdf, v170
	v_mad_i64_i32 v[120:121], s[28:29], v170, s66, v[104:105]
	v_mul_f32_e32 v118, 0x45800000, v116
	v_cndmask_b32_e64 v118, v116, v118, s[0:1]
	v_add_u32_e32 v116, s34, v117
	v_cmp_gt_u32_e64 s[0:1], s72, v117
	v_ashrrev_i32_e32 v117, 31, v116
	v_lshlrev_b64 v[116:117], 12, v[116:117]
	v_pk_mul_f32 v[114:115], v[114:115], v[118:119] op_sel_hi:[1,0]
	v_pk_mul_f32 v[112:113], v[112:113], v[118:119] op_sel_hi:[1,0]
	v_pk_mul_f32 v[110:111], v[110:111], v[118:119] op_sel_hi:[1,0]
	v_pk_mul_f32 v[108:109], v[108:109], v[118:119] op_sel_hi:[1,0]
	v_lshl_add_u64 v[116:117], v[156:157], 0, v[116:117]
	v_cvt_pk_bf16_f32 v122, v112, v113
	v_cvt_pk_bf16_f32 v123, v114, v115
	v_cvt_pk_bf16_f32 v124, v108, v109
	v_cvt_pk_bf16_f32 v125, v110, v111
	v_lshl_add_u64 v[120:121], v[106:107], 1, v[120:121]
	s_nor_b64 s[42:43], vcc, s[0:1]
	global_store_dwordx4 v[120:121], v[122:125], off sc0 sc1
	s_and_saveexec_b64 s[28:29], s[42:43]
	s_cbranch_execz .LBB0_407
	s_cmpk_gt_u32 s26, 0x7ff
	s_cselect_b64 s[42:43], -1, 0
	s_and_b64 s[42:43], s[42:43], exec
	s_cselect_b32 s35, 0xfffffc00, 0
	s_cselect_b32 s36, 0x2100000, 0
	v_add_u32_e32 v119, s35, v106
	v_lshl_add_u64 v[122:123], v[116:117], 0, s[36:37]
	v_add_u32_e32 v124, 0xfffffc00, v119
	v_mov_b32_e32 v125, v161
	v_lshl_add_u64 v[122:123], v[124:125], 2, v[122:123]
	global_store_dwordx4 v[122:123], v[112:115], off nt
	global_store_dwordx4 v[122:123], v[108:111], off offset:16 nt
.LBB0_407:
	s_or_b64 exec, exec, s[28:29]
	v_mov_b32_e32 v119, v118
	v_mov_b32_e32 v108, v118
	v_mov_b32_e32 v109, v118
	v_pk_mul_f32 v[102:103], v[102:103], v[108:109]
	v_pk_mul_f32 v[100:101], v[100:101], v[118:119]
	v_pk_mul_f32 v[98:99], v[98:99], v[108:109]
	v_pk_mul_f32 v[96:97], v[96:97], v[118:119]
	v_cvt_pk_bf16_f32 v108, v100, v101
	v_cvt_pk_bf16_f32 v109, v102, v103
	v_cvt_pk_bf16_f32 v110, v96, v97
	v_cvt_pk_bf16_f32 v111, v98, v99
	s_nor_b64 s[28:29], s[40:41], s[0:1]
	global_store_dwordx4 v[120:121], v[108:111], off offset:256 sc0 sc1
	s_and_saveexec_b64 s[0:1], s[28:29]
	s_cbranch_execz .LBB0_409
	s_cmpk_gt_u32 s26, 0x7ff
	s_cselect_b64 s[28:29], -1, 0
	s_and_b64 s[28:29], s[28:29], exec
	s_cselect_b32 s28, 0xfffffc00, 0
	s_cselect_b32 s36, 0x2100000, 0
	v_add_u32_e32 v110, s28, v106
	v_lshl_add_u64 v[108:109], v[116:117], 0, s[36:37]
	v_add_u32_e32 v110, 0xfffffc80, v110
	v_mov_b32_e32 v111, v161
	v_lshl_add_u64 v[108:109], v[110:111], 2, v[108:109]
	global_store_dwordx4 v[108:109], v[100:103], off nt
	global_store_dwordx4 v[108:109], v[96:99], off offset:16 nt
.LBB0_409:
	s_or_b64 exec, exec, s[0:1]
	s_nop 0
	v_pk_add_f32 v[96:97], v[174:175], v[176:177]
	v_mad_i64_i32 v[102:103], s[28:29], v168, s66, v[104:105]
	v_pk_fma_f32 v[96:97], v[96:97], s[80:81], v[162:163] op_sel_hi:[1,0,0]
	v_lshl_add_u64 v[102:103], v[106:107], 1, v[102:103]
	v_mul_f32_e32 v98, 0x4b800000, v97
	v_cmp_gt_f32_e64 s[42:43], s3, v97
	v_cmp_gt_f32_e64 s[0:1], s3, v96
	s_nop 0
	v_cndmask_b32_e64 v97, v97, v98, s[42:43]
	v_rsq_f32_e32 v97, v97
	s_nop 0
	v_mul_f32_e32 v98, 0x45800000, v97
	v_cndmask_b32_e64 v100, v97, v98, s[42:43]
	v_and_b32_e32 v97, 0xfef, v168
	v_add_u32_e32 v98, s34, v97
	v_ashrrev_i32_e32 v99, 31, v98
	v_cmp_gt_u32_e64 s[42:43], s72, v97
	v_lshlrev_b64 v[98:99], 12, v[98:99]
	v_pk_mul_f32 v[94:95], v[94:95], v[100:101] op_sel_hi:[1,0]
	v_pk_mul_f32 v[92:93], v[92:93], v[100:101] op_sel_hi:[1,0]
	v_pk_mul_f32 v[90:91], v[90:91], v[100:101] op_sel_hi:[1,0]
	v_pk_mul_f32 v[88:89], v[88:89], v[100:101] op_sel_hi:[1,0]
	v_lshl_add_u64 v[98:99], v[156:157], 0, v[98:99]
	v_cvt_pk_bf16_f32 v108, v92, v93
	v_cvt_pk_bf16_f32 v109, v94, v95
	v_cvt_pk_bf16_f32 v110, v88, v89
	v_cvt_pk_bf16_f32 v111, v90, v91
	s_nor_b64 s[72:73], vcc, s[42:43]
	global_store_dwordx4 v[102:103], v[108:111], off sc0 sc1
	s_and_saveexec_b64 s[28:29], s[72:73]
	s_cbranch_execz .LBB0_411
	s_cmpk_gt_u32 s26, 0x7ff
	s_cselect_b64 s[72:73], -1, 0
	s_and_b64 s[72:73], s[72:73], exec
	s_cselect_b32 s35, 0xfffffc00, 0
	s_cselect_b32 s36, 0x2100000, 0
	v_add_u32_e32 v97, s35, v106
	v_lshl_add_u64 v[108:109], v[98:99], 0, s[36:37]
	v_add_u32_e32 v110, 0xfffffc00, v97
	v_mov_b32_e32 v111, v161
	v_lshl_add_u64 v[108:109], v[110:111], 2, v[108:109]
	global_store_dwordx4 v[108:109], v[92:95], off nt
	global_store_dwordx4 v[108:109], v[88:91], off offset:16 nt
; #define GAS __attribute__((address_space(1)))
; __device__ __forceinline__ unsigned pk2(float lo, float hi) { const f32x2 v = {lo, hi}; return __builtin_bit_cast(unsigned, __builtin_convertvector(v, hwbf16x2)); }
; template <int MODE, bool SMALL>
; __device__ __forceinline__ float epi_apply(const EpiArgs& a, int row, int g32, int fq, f32x4 v0, f32x4 v1, float rstd) {
;     ...
;     } else if constexpr (MODE == 1) {
;         v0 *= rstd; v1 *= rstd;
;         u32x4 w; w.x = pk2(v0[0], v0[1]); w.y = pk2(v0[2], v0[3]); w.z = pk2(v1[0], v1[1]); w.w = pk2(v1[2], v1[3]);
;         *(GAS u32x4*)(a.out + (size_t)row * NQKV + c0) = w;
;         if (c0 >= 1024) {
;             const int isv = c0 >= 2048, cc = c0 - 1024 - 1024 * isv;
;             if constexpr (!SMALL) { const int t = row & (SEQ - 1), b = row >> 12; if (t >= SEQ - 512) { GAS float* d = a.o0 + (size_t)isv * (O_CVP - O_CKP) + (size_t)(b * 512 + (t - (SEQ - 512))) * 1024 + cc; __builtin_nontemporal_store(v0, (GAS f32x4*)d); __builtin_nontemporal_store(v1, (GAS f32x4*)(d + 4)); } }
;             else { const int r = row - TP; GAS float* d = a.o2 + (size_t)isv * (O_CVS - O_CKS) + (size_t)r * 1024 + cc; *(GAS f32x4*)d = v0; *(GAS f32x4*)(d + 4) = v1; }
;         }
;     __device__ __forceinline__ void operator()(const f32x4 (&acc)[2][2][4][2], const pg8::Unit& u, int wr, int wc, int fr, int fq) const {
;     ...
;             for (int ai = 0; ai < 2; ++ai)
; #pragma unroll
;                 for (int m = 0; m < 4; ++m) { float sp = (pq[ai][m][0] + pq[ai][m][1]) + (pq[ai][m][2] + pq[ai][m][3]); sp += __shfl_xor(sp, 16); sp += __shfl_xor(sp, 32); rs[ai][m] = rsqrtf(sp * (1.0f / 1024.0f) + EPS); }
.LBB0_411:
	s_or_b64 exec, exec, s[28:29]
	v_mov_b32_e32 v101, v100
	v_mov_b32_e32 v88, v100
	v_mov_b32_e32 v89, v100
	v_pk_mul_f32 v[86:87], v[86:87], v[88:89]
	v_pk_mul_f32 v[84:85], v[84:85], v[100:101]
	v_pk_mul_f32 v[82:83], v[82:83], v[88:89]
	v_pk_mul_f32 v[80:81], v[80:81], v[100:101]
	v_cvt_pk_bf16_f32 v88, v84, v85
	v_cvt_pk_bf16_f32 v89, v86, v87
	v_cvt_pk_bf16_f32 v90, v80, v81
	v_cvt_pk_bf16_f32 v91, v82, v83
	s_nor_b64 s[42:43], s[40:41], s[42:43]
	global_store_dwordx4 v[102:103], v[88:91], off offset:256 sc0 sc1
	s_and_saveexec_b64 s[28:29], s[42:43]
	s_cbranch_execz .LBB0_413
	s_cmpk_gt_u32 s26, 0x7ff
	s_cselect_b64 s[42:43], -1, 0
	s_and_b64 s[42:43], s[42:43], exec
	s_cselect_b32 s35, 0xfffffc00, 0
	s_cselect_b32 s36, 0x2100000, 0
	v_add_u32_e32 v90, s35, v106
	v_lshl_add_u64 v[88:89], v[98:99], 0, s[36:37]
	v_add_u32_e32 v90, 0xfffffc80, v90
	v_mov_b32_e32 v91, v161
	v_lshl_add_u64 v[88:89], v[90:91], 2, v[88:89]
	global_store_dwordx4 v[88:89], v[84:87], off nt
	global_store_dwordx4 v[88:89], v[80:83], off offset:16 nt
.LBB0_413:
	s_or_b64 exec, exec, s[28:29]
	s_nop 0
	v_mul_f32_e32 v80, 0x4b800000, v96
	v_cndmask_b32_e64 v80, v96, v80, s[0:1]
	v_rsq_f32_e32 v80, v80
	s_movk_i32 s72, 0xe00
	v_mul_f32_e32 v81, 0x45800000, v80
	v_cndmask_b32_e64 v82, v80, v81, s[0:1]
	v_mad_i64_i32 v[84:85], s[0:1], v158, s66, v[104:105]
	v_and_b32_e32 v80, 0xfff, v158
	v_cmp_gt_u32_e64 s[0:1], s72, v80
	v_add_u32_e32 v80, s34, v80
	v_ashrrev_i32_e32 v81, 31, v80
	v_lshlrev_b64 v[80:81], 12, v[80:81]
	v_pk_mul_f32 v[78:79], v[78:79], v[82:83] op_sel_hi:[1,0]
	v_pk_mul_f32 v[76:77], v[76:77], v[82:83] op_sel_hi:[1,0]
	v_pk_mul_f32 v[74:75], v[74:75], v[82:83] op_sel_hi:[1,0]
	v_pk_mul_f32 v[72:73], v[72:73], v[82:83] op_sel_hi:[1,0]
	v_lshl_add_u64 v[80:81], v[156:157], 0, v[80:81]
	v_cvt_pk_bf16_f32 v86, v76, v77
	v_cvt_pk_bf16_f32 v87, v78, v79
	v_cvt_pk_bf16_f32 v88, v72, v73
	v_cvt_pk_bf16_f32 v89, v74, v75
	v_lshl_add_u64 v[84:85], v[106:107], 1, v[84:85]
	s_nor_b64 s[34:35], vcc, s[0:1]
	global_store_dwordx4 v[84:85], v[86:89], off sc0 sc1
	s_and_saveexec_b64 s[28:29], s[34:35]
	s_cbranch_execz .LBB0_415
	s_cmpk_gt_u32 s26, 0x7ff
	s_cselect_b64 s[34:35], -1, 0
	s_and_b64 s[34:35], s[34:35], exec
	s_cselect_b32 s34, 0xfffffc00, 0
	s_cselect_b32 s36, 0x2100000, 0
	v_add_u32_e32 v83, s34, v106
	v_lshl_add_u64 v[86:87], v[80:81], 0, s[36:37]
	v_add_u32_e32 v88, 0xfffffc00, v83
	v_mov_b32_e32 v89, v161
	v_lshl_add_u64 v[86:87], v[88:89], 2, v[86:87]
	global_store_dwordx4 v[86:87], v[76:79], off nt
	global_store_dwordx4 v[86:87], v[72:75], off offset:16 nt
.LBB0_415:
	s_or_b64 exec, exec, s[28:29]
	v_mov_b32_e32 v83, v82
	v_mov_b32_e32 v72, v82
	v_mov_b32_e32 v73, v82
	v_pk_mul_f32 v[70:71], v[70:71], v[72:73]
	v_pk_mul_f32 v[68:69], v[68:69], v[82:83]
	v_pk_mul_f32 v[66:67], v[66:67], v[72:73]
	v_pk_mul_f32 v[64:65], v[64:65], v[82:83]
	v_cvt_pk_bf16_f32 v72, v68, v69
	v_cvt_pk_bf16_f32 v73, v70, v71
	v_cvt_pk_bf16_f32 v74, v64, v65
	v_cvt_pk_bf16_f32 v75, v66, v67
	s_nor_b64 s[28:29], s[40:41], s[0:1]
	global_store_dwordx4 v[84:85], v[72:75], off offset:256 sc0 sc1
	s_and_saveexec_b64 s[0:1], s[28:29]
	s_cbranch_execz .LBB0_417
	s_cmpk_gt_u32 s26, 0x7ff
	s_cselect_b64 s[28:29], -1, 0
	s_and_b64 s[28:29], s[28:29], exec
	s_cselect_b32 s28, 0xfffffc00, 0
	s_cselect_b32 s36, 0x2100000, 0
	v_add_u32_e32 v74, s28, v106
	v_lshl_add_u64 v[72:73], v[80:81], 0, s[36:37]
	v_add_u32_e32 v74, 0xfffffc80, v74
	v_mov_b32_e32 v75, v161
	v_lshl_add_u64 v[72:73], v[74:75], 2, v[72:73]
	global_store_dwordx4 v[72:73], v[68:71], off nt
	global_store_dwordx4 v[72:73], v[64:67], off offset:16 nt
.LBB0_417:
	s_or_b64 exec, exec, s[0:1]
	s_waitcnt lgkmcnt(2)
	v_pk_add_f32 v[64:65], v[140:141], v[142:143]
	s_add_i32 s34, s27, 0x80
	v_pk_fma_f32 v[64:65], v[64:65], s[80:81], v[162:163] op_sel_hi:[1,0,0]
	s_ashr_i32 s27, s34, 3
	v_mul_f32_e32 v66, 0x4b800000, v65
	v_cmp_gt_f32_e64 s[42:43], s3, v65
	s_and_b32 s27, s27, 0xfffffe00
	s_addk_i32 s27, 0xf200
	v_cndmask_b32_e64 v65, v65, v66, s[42:43]
	v_rsq_f32_e32 v65, v65
	v_cmp_gt_f32_e64 s[0:1], s3, v64
	v_mul_f32_e32 v66, 0x45800000, v65
	v_cndmask_b32_e64 v68, v65, v66, s[42:43]
	v_bitop3_b32 v66, s34, v205, v165 bitop3:0xc8
	v_cmp_gt_u32_e64 s[42:43], s72, v66
	v_add_u32_e32 v66, s27, v66
	v_or_b32_e32 v65, s34, v165
	v_ashrrev_i32_e32 v67, 31, v66
	v_mad_i64_i32 v[70:71], s[28:29], v65, s66, v[104:105]
	v_lshlrev_b64 v[66:67], 12, v[66:67]
	v_pk_mul_f32 v[62:63], v[62:63], v[68:69] op_sel_hi:[1,0]
	v_pk_mul_f32 v[60:61], v[60:61], v[68:69] op_sel_hi:[1,0]
	v_pk_mul_f32 v[58:59], v[58:59], v[68:69] op_sel_hi:[1,0]
	v_pk_mul_f32 v[56:57], v[56:57], v[68:69] op_sel_hi:[1,0]
	v_lshl_add_u64 v[66:67], v[156:157], 0, v[66:67]
	v_cvt_pk_bf16_f32 v72, v60, v61
	v_cvt_pk_bf16_f32 v73, v62, v63
	v_cvt_pk_bf16_f32 v74, v56, v57
	v_cvt_pk_bf16_f32 v75, v58, v59
	v_lshl_add_u64 v[70:71], v[106:107], 1, v[70:71]
	s_nor_b64 s[34:35], vcc, s[42:43]
	global_store_dwordx4 v[70:71], v[72:75], off sc0 sc1
	s_and_saveexec_b64 s[28:29], s[34:35]
	s_cbranch_execz .LBB0_419
	s_cmpk_gt_u32 s26, 0x7ff
	s_cselect_b64 s[34:35], -1, 0
	s_and_b64 s[34:35], s[34:35], exec
	s_cselect_b32 s34, 0xfffffc00, 0
	s_cselect_b32 s36, 0x2100000, 0
	v_add_u32_e32 v69, s34, v106
	v_lshl_add_u64 v[72:73], v[66:67], 0, s[36:37]
	v_add_u32_e32 v74, 0xfffffc00, v69
	v_mov_b32_e32 v75, v161
	v_lshl_add_u64 v[72:73], v[74:75], 2, v[72:73]
	global_store_dwordx4 v[72:73], v[60:63], off nt
	global_store_dwordx4 v[72:73], v[56:59], off offset:16 nt
; #define GAS __attribute__((address_space(1)))
; __device__ __forceinline__ unsigned pk2(float lo, float hi) { const f32x2 v = {lo, hi}; return __builtin_bit_cast(unsigned, __builtin_convertvector(v, hwbf16x2)); }
; template <int MODE, bool SMALL>
; __device__ __forceinline__ float epi_apply(const EpiArgs& a, int row, int g32, int fq, f32x4 v0, f32x4 v1, float rstd) {
;     ...
;     } else if constexpr (MODE == 1) {
;         v0 *= rstd; v1 *= rstd;
;         u32x4 w; w.x = pk2(v0[0], v0[1]); w.y = pk2(v0[2], v0[3]); w.z = pk2(v1[0], v1[1]); w.w = pk2(v1[2], v1[3]);
;         *(GAS u32x4*)(a.out + (size_t)row * NQKV + c0) = w;
;         if (c0 >= 1024) {
;             const int isv = c0 >= 2048, cc = c0 - 1024 - 1024 * isv;
;             if constexpr (!SMALL) { const int t = row & (SEQ - 1), b = row >> 12; if (t >= SEQ - 512) { GAS float* d = a.o0 + (size_t)isv * (O_CVP - O_CKP) + (size_t)(b * 512 + (t - (SEQ - 512))) * 1024 + cc; __builtin_nontemporal_store(v0, (GAS f32x4*)d); __builtin_nontemporal_store(v1, (GAS f32x4*)(d + 4)); } }
;             else { const int r = row - TP; GAS float* d = a.o2 + (size_t)isv * (O_CVS - O_CKS) + (size_t)r * 1024 + cc; *(GAS f32x4*)d = v0; *(GAS f32x4*)(d + 4) = v1; }
;         }
.LBB0_419:
	s_or_b64 exec, exec, s[28:29]
	v_mov_b32_e32 v69, v68
	v_mov_b32_e32 v56, v68
	v_mov_b32_e32 v57, v68
	v_pk_mul_f32 v[54:55], v[54:55], v[56:57]
	v_pk_mul_f32 v[52:53], v[52:53], v[68:69]
	v_pk_mul_f32 v[50:51], v[50:51], v[56:57]
	v_pk_mul_f32 v[48:49], v[48:49], v[68:69]
	v_cvt_pk_bf16_f32 v56, v52, v53
	v_cvt_pk_bf16_f32 v57, v54, v55
	v_cvt_pk_bf16_f32 v58, v48, v49
	v_cvt_pk_bf16_f32 v59, v50, v51
	s_nor_b64 s[34:35], s[40:41], s[42:43]
	global_store_dwordx4 v[70:71], v[56:59], off offset:256 sc0 sc1
	s_and_saveexec_b64 s[28:29], s[34:35]
	s_cbranch_execz .LBB0_421
	s_cmpk_gt_u32 s26, 0x7ff
	s_cselect_b64 s[34:35], -1, 0
	s_and_b64 s[34:35], s[34:35], exec
	s_cselect_b32 s34, 0xfffffc00, 0
	s_cselect_b32 s36, 0x2100000, 0
	v_add_u32_e32 v58, s34, v106
	v_lshl_add_u64 v[56:57], v[66:67], 0, s[36:37]
	v_add_u32_e32 v58, 0xfffffc80, v58
	v_mov_b32_e32 v59, v161
	v_lshl_add_u64 v[56:57], v[58:59], 2, v[56:57]
	global_store_dwordx4 v[56:57], v[52:55], off nt
	global_store_dwordx4 v[56:57], v[48:51], off offset:16 nt
.LBB0_421:
	s_or_b64 exec, exec, s[28:29]
	s_nop 0
	v_mul_f32_e32 v48, 0x4b800000, v64
	v_cndmask_b32_e64 v48, v64, v48, s[0:1]
	v_rsq_f32_e32 v48, v48
	v_or_b32_e32 v49, 16, v65
	v_mad_i64_i32 v[52:53], s[28:29], v49, s66, v[104:105]
	v_mul_f32_e32 v49, 0x45800000, v48
	v_cndmask_b32_e64 v50, v48, v49, s[0:1]
	s_movk_i32 s0, 0xfdf
	v_bitop3_b32 v48, v65, s0, 16 bitop3:0xc8
	v_cmp_gt_u32_e64 s[0:1], s72, v48
	v_add_u32_e32 v48, s27, v48
	v_ashrrev_i32_e32 v49, 31, v48
	v_lshlrev_b64 v[48:49], 12, v[48:49]
	v_pk_mul_f32 v[46:47], v[46:47], v[50:51] op_sel_hi:[1,0]
	v_pk_mul_f32 v[44:45], v[44:45], v[50:51] op_sel_hi:[1,0]
	v_pk_mul_f32 v[42:43], v[42:43], v[50:51] op_sel_hi:[1,0]
	v_pk_mul_f32 v[40:41], v[40:41], v[50:51] op_sel_hi:[1,0]
	v_lshl_add_u64 v[48:49], v[156:157], 0, v[48:49]
	v_cvt_pk_bf16_f32 v54, v44, v45
	v_cvt_pk_bf16_f32 v55, v46, v47
	v_cvt_pk_bf16_f32 v56, v40, v41
	v_cvt_pk_bf16_f32 v57, v42, v43
	v_lshl_add_u64 v[52:53], v[106:107], 1, v[52:53]
	s_nor_b64 s[34:35], vcc, s[0:1]
	global_store_dwordx4 v[52:53], v[54:57], off sc0 sc1
	s_and_saveexec_b64 s[28:29], s[34:35]
	s_cbranch_execz .LBB0_423
	s_cmpk_gt_u32 s26, 0x7ff
	s_cselect_b64 s[34:35], -1, 0
	s_and_b64 s[34:35], s[34:35], exec
	s_cselect_b32 s34, 0xfffffc00, 0
	s_cselect_b32 s36, 0x2100000, 0
	v_add_u32_e32 v51, s34, v106
	v_lshl_add_u64 v[54:55], v[48:49], 0, s[36:37]
	v_add_u32_e32 v56, 0xfffffc00, v51
	v_mov_b32_e32 v57, v161
	v_lshl_add_u64 v[54:55], v[56:57], 2, v[54:55]
	global_store_dwordx4 v[54:55], v[44:47], off nt
	global_store_dwordx4 v[54:55], v[40:43], off offset:16 nt
.LBB0_423:
	s_or_b64 exec, exec, s[28:29]
	v_mov_b32_e32 v51, v50
	v_mov_b32_e32 v40, v50
	v_mov_b32_e32 v41, v50
	v_pk_mul_f32 v[38:39], v[38:39], v[40:41]
	v_pk_mul_f32 v[36:37], v[36:37], v[50:51]
	v_pk_mul_f32 v[34:35], v[34:35], v[40:41]
	v_pk_mul_f32 v[32:33], v[32:33], v[50:51]
	v_cvt_pk_bf16_f32 v40, v36, v37
	v_cvt_pk_bf16_f32 v41, v38, v39
	v_cvt_pk_bf16_f32 v42, v32, v33
	v_cvt_pk_bf16_f32 v43, v34, v35
	s_nor_b64 s[28:29], s[40:41], s[0:1]
	global_store_dwordx4 v[52:53], v[40:43], off offset:256 sc0 sc1
	s_and_saveexec_b64 s[0:1], s[28:29]
	s_cbranch_execz .LBB0_425
	s_cmpk_gt_u32 s26, 0x7ff
	s_cselect_b64 s[28:29], -1, 0
	s_and_b64 s[28:29], s[28:29], exec
	s_cselect_b32 s28, 0xfffffc00, 0
	s_cselect_b32 s36, 0x2100000, 0
	v_add_u32_e32 v42, s28, v106
	v_lshl_add_u64 v[40:41], v[48:49], 0, s[36:37]
	v_add_u32_e32 v42, 0xfffffc80, v42
	v_mov_b32_e32 v43, v161
	v_lshl_add_u64 v[40:41], v[42:43], 2, v[40:41]
	global_store_dwordx4 v[40:41], v[36:39], off nt
	global_store_dwordx4 v[40:41], v[32:35], off offset:16 nt
; #define GAS __attribute__((address_space(1)))
; __device__ __forceinline__ unsigned pk2(float lo, float hi) { const f32x2 v = {lo, hi}; return __builtin_bit_cast(unsigned, __builtin_convertvector(v, hwbf16x2)); }
; template <int MODE, bool SMALL>
; __device__ __forceinline__ float epi_apply(const EpiArgs& a, int row, int g32, int fq, f32x4 v0, f32x4 v1, float rstd) {
;     ...
;     } else if constexpr (MODE == 1) {
;         v0 *= rstd; v1 *= rstd;
;         u32x4 w; w.x = pk2(v0[0], v0[1]); w.y = pk2(v0[2], v0[3]); w.z = pk2(v1[0], v1[1]); w.w = pk2(v1[2], v1[3]);
;         *(GAS u32x4*)(a.out + (size_t)row * NQKV + c0) = w;
;         if (c0 >= 1024) {
;             const int isv = c0 >= 2048, cc = c0 - 1024 - 1024 * isv;
;             if constexpr (!SMALL) { const int t = row & (SEQ - 1), b = row >> 12; if (t >= SEQ - 512) { GAS float* d = a.o0 + (size_t)isv * (O_CVP - O_CKP) + (size_t)(b * 512 + (t - (SEQ - 512))) * 1024 + cc; __builtin_nontemporal_store(v0, (GAS f32x4*)d); __builtin_nontemporal_store(v1, (GAS f32x4*)(d + 4)); } }
;             else { const int r = row - TP; GAS float* d = a.o2 + (size_t)isv * (O_CVS - O_CKS) + (size_t)r * 1024 + cc; *(GAS f32x4*)d = v0; *(GAS f32x4*)(d + 4) = v1; }
;         }
;     __device__ __forceinline__ void operator()(const f32x4 (&acc)[2][2][4][2], const pg8::Unit& u, int wr, int wc, int fr, int fq) const {
;     ...
;             for (int ai = 0; ai < 2; ++ai)
; #pragma unroll
;                 for (int m = 0; m < 4; ++m) { float sp = (pq[ai][m][0] + pq[ai][m][1]) + (pq[ai][m][2] + pq[ai][m][3]); sp += __shfl_xor(sp, 16); sp += __shfl_xor(sp, 32); rs[ai][m] = rsqrtf(sp * (1.0f / 1024.0f) + EPS); }
.LBB0_425:
	s_or_b64 exec, exec, s[0:1]
	s_waitcnt lgkmcnt(0)
	v_pk_add_f32 v[32:33], v[132:133], v[134:135]
	s_nop 0
	v_pk_fma_f32 v[32:33], v[32:33], s[80:81], v[162:163] op_sel_hi:[1,0,0]
	s_nop 0
	v_mul_f32_e32 v34, 0x4b800000, v33
	v_cmp_gt_f32_e64 s[42:43], s3, v33
	v_cmp_gt_f32_e64 s[0:1], s3, v32
	s_nop 0
	v_cndmask_b32_e64 v33, v33, v34, s[42:43]
	v_rsq_f32_e32 v33, v33
	v_or_b32_e32 v34, 32, v65
	v_mad_i64_i32 v[38:39], s[28:29], v34, s66, v[104:105]
	v_mul_f32_e32 v35, 0x45800000, v33
	s_movk_i32 s28, 0xfef
	v_cndmask_b32_e64 v36, v33, v35, s[42:43]
	v_bitop3_b32 v33, v65, s28, 32 bitop3:0xc8
	v_add_u32_e32 v34, s27, v33
	v_ashrrev_i32_e32 v35, 31, v34
	v_cmp_gt_u32_e64 s[42:43], s72, v33
	v_lshlrev_b64 v[34:35], 12, v[34:35]
	v_pk_mul_f32 v[30:31], v[30:31], v[36:37] op_sel_hi:[1,0]
	v_pk_mul_f32 v[28:29], v[28:29], v[36:37] op_sel_hi:[1,0]
	v_pk_mul_f32 v[26:27], v[26:27], v[36:37] op_sel_hi:[1,0]
	v_pk_mul_f32 v[24:25], v[24:25], v[36:37] op_sel_hi:[1,0]
	v_lshl_add_u64 v[34:35], v[156:157], 0, v[34:35]
	v_cvt_pk_bf16_f32 v40, v28, v29
	v_cvt_pk_bf16_f32 v41, v30, v31
	v_cvt_pk_bf16_f32 v42, v24, v25
	v_cvt_pk_bf16_f32 v43, v26, v27
	v_lshl_add_u64 v[38:39], v[106:107], 1, v[38:39]
	s_nor_b64 s[34:35], vcc, s[42:43]
	global_store_dwordx4 v[38:39], v[40:43], off sc0 sc1
	s_and_saveexec_b64 s[28:29], s[34:35]
	s_cbranch_execz .LBB0_427
	s_cmpk_gt_u32 s26, 0x7ff
	s_cselect_b64 s[34:35], -1, 0
	s_and_b64 s[34:35], s[34:35], exec
	s_cselect_b32 s34, 0xfffffc00, 0
	s_cselect_b32 s36, 0x2100000, 0
	v_add_u32_e32 v33, s34, v106
	v_lshl_add_u64 v[40:41], v[34:35], 0, s[36:37]
	v_add_u32_e32 v42, 0xfffffc00, v33
	v_mov_b32_e32 v43, v161
	v_lshl_add_u64 v[40:41], v[42:43], 2, v[40:41]
	global_store_dwordx4 v[40:41], v[28:31], off nt
	global_store_dwordx4 v[40:41], v[24:27], off offset:16 nt
.LBB0_427:
	s_or_b64 exec, exec, s[28:29]
	v_mov_b32_e32 v37, v36
	v_mov_b32_e32 v24, v36
	v_mov_b32_e32 v25, v36
	v_pk_mul_f32 v[22:23], v[22:23], v[24:25]
	v_pk_mul_f32 v[20:21], v[20:21], v[36:37]
	v_pk_mul_f32 v[18:19], v[18:19], v[24:25]
	v_pk_mul_f32 v[16:17], v[16:17], v[36:37]
	v_cvt_pk_bf16_f32 v24, v20, v21
	v_cvt_pk_bf16_f32 v25, v22, v23
	v_cvt_pk_bf16_f32 v26, v16, v17
	v_cvt_pk_bf16_f32 v27, v18, v19
	s_nor_b64 s[34:35], s[40:41], s[42:43]
	global_store_dwordx4 v[38:39], v[24:27], off offset:256 sc0 sc1
	s_and_saveexec_b64 s[28:29], s[34:35]
	s_cbranch_execz .LBB0_429
	s_cmpk_gt_u32 s26, 0x7ff
	s_cselect_b64 s[34:35], -1, 0
	s_and_b64 s[34:35], s[34:35], exec
	s_cselect_b32 s34, 0xfffffc00, 0
	s_cselect_b32 s36, 0x2100000, 0
	v_add_u32_e32 v26, s34, v106
	v_lshl_add_u64 v[24:25], v[34:35], 0, s[36:37]
	v_add_u32_e32 v26, 0xfffffc80, v26
	v_mov_b32_e32 v27, v161
	v_lshl_add_u64 v[24:25], v[26:27], 2, v[24:25]
	global_store_dwordx4 v[24:25], v[20:23], off nt
	global_store_dwordx4 v[24:25], v[16:19], off offset:16 nt
.LBB0_429:
	s_or_b64 exec, exec, s[28:29]
	s_nop 0
	v_mul_f32_e32 v16, 0x4b800000, v32
	v_cndmask_b32_e64 v16, v32, v16, s[0:1]
	v_rsq_f32_e32 v16, v16
	s_nop 0
	v_mul_f32_e32 v17, 0x45800000, v16
	v_cndmask_b32_e64 v18, v16, v17, s[0:1]
	v_or_b32_e32 v16, 48, v65
	v_mad_i64_i32 v[20:21], s[0:1], v16, s66, v[104:105]
	s_movk_i32 s0, 0xfff
	s_nop 0
	v_bitop3_b32 v16, v65, s0, 48 bitop3:0xc8
	v_cmp_gt_u32_e64 s[0:1], s72, v16
	v_add_u32_e32 v16, s27, v16
	v_ashrrev_i32_e32 v17, 31, v16
	v_lshlrev_b64 v[16:17], 12, v[16:17]
	v_pk_mul_f32 v[14:15], v[14:15], v[18:19] op_sel_hi:[1,0]
	v_pk_mul_f32 v[12:13], v[12:13], v[18:19] op_sel_hi:[1,0]
	v_pk_mul_f32 v[10:11], v[10:11], v[18:19] op_sel_hi:[1,0]
	v_pk_mul_f32 v[8:9], v[8:9], v[18:19] op_sel_hi:[1,0]
	v_lshl_add_u64 v[16:17], v[156:157], 0, v[16:17]
	v_cvt_pk_bf16_f32 v22, v12, v13
	v_cvt_pk_bf16_f32 v23, v14, v15
	v_cvt_pk_bf16_f32 v24, v8, v9
	v_cvt_pk_bf16_f32 v25, v10, v11
	v_lshl_add_u64 v[20:21], v[106:107], 1, v[20:21]
	s_nor_b64 s[34:35], vcc, s[0:1]
	global_store_dwordx4 v[20:21], v[22:25], off sc0 sc1
	s_and_saveexec_b64 s[28:29], s[34:35]
	s_cbranch_execz .LBB0_431
	s_cmpk_gt_u32 s26, 0x7ff
	s_cselect_b64 s[34:35], -1, 0
	s_and_b64 s[34:35], s[34:35], exec
	s_cselect_b32 s27, 0xfffffc00, 0
	s_cselect_b32 s36, 0x2100000, 0
	v_add_u32_e32 v19, s27, v106
	v_lshl_add_u64 v[22:23], v[16:17], 0, s[36:37]
	v_add_u32_e32 v24, 0xfffffc00, v19
	v_mov_b32_e32 v25, v161
	v_lshl_add_u64 v[22:23], v[24:25], 2, v[22:23]
	global_store_dwordx4 v[22:23], v[12:15], off nt
	global_store_dwordx4 v[22:23], v[8:11], off offset:16 nt
.LBB0_431:
	s_or_b64 exec, exec, s[28:29]
	v_mov_b32_e32 v19, v18
	v_mov_b32_e32 v8, v18
	v_mov_b32_e32 v9, v18
	v_pk_mul_f32 v[6:7], v[6:7], v[8:9]
	v_pk_mul_f32 v[4:5], v[4:5], v[18:19]
	v_pk_mul_f32 v[2:3], v[2:3], v[8:9]
	v_pk_mul_f32 v[0:1], v[0:1], v[18:19]
	v_cvt_pk_bf16_f32 v8, v4, v5
	v_cvt_pk_bf16_f32 v9, v6, v7
	v_cvt_pk_bf16_f32 v10, v0, v1
	v_cvt_pk_bf16_f32 v11, v2, v3
	s_nor_b64 s[28:29], s[40:41], s[0:1]
	global_store_dwordx4 v[20:21], v[8:11], off offset:256 sc0 sc1
	s_and_saveexec_b64 s[0:1], s[28:29]
	s_cbranch_execz .LBB0_433
	s_cmpk_gt_u32 s26, 0x7ff
	s_cselect_b64 s[26:27], -1, 0
	s_and_b64 s[26:27], s[26:27], exec
	s_cselect_b32 s26, 0xfffffc00, 0
	s_cselect_b32 s36, 0x2100000, 0
	v_add_u32_e32 v10, s26, v106
	v_lshl_add_u64 v[8:9], v[16:17], 0, s[36:37]
	v_add_u32_e32 v10, 0xfffffc80, v10
	v_mov_b32_e32 v11, v161
	v_lshl_add_u64 v[8:9], v[10:11], 2, v[8:9]
	global_store_dwordx4 v[8:9], v[4:7], off nt
	global_store_dwordx4 v[8:9], v[0:3], off offset:16 nt

; #define GAS __attribute__((address_space(1)))
; __device__ __forceinline__ unsigned pk2(float lo, float hi) { const f32x2 v = {lo, hi}; return __builtin_bit_cast(unsigned, __builtin_convertvector(v, hwbf16x2)); }
; template <int MODE, bool SMALL>
; __device__ __forceinline__ float epi_apply(const EpiArgs& a, int row, int g32, int fq, f32x4 v0, f32x4 v1, float rstd) {
;     ...
;     if constexpr (MODE == 0) {
;         if (g32 >= ABIN / 32) return 0.f;
;         v0 *= rstd; v1 *= rstd;
;         u32x4 w; w.x = pk2(v0[0], v0[1]); w.y = pk2(v0[2], v0[3]); w.z = pk2(v1[0], v1[1]); w.w = pk2(v1[2], v1[3]);
;         *(GAS u32x4*)(a.out + (size_t)row * ABIN + c0) = w;
;         if (g32 == 48 && fq < 2) { GAS float* gp = a.gates + (size_t)row * 32 + 8 * fq; *(GAS f32x4*)gp = v0; *(GAS f32x4*)(gp + 4) = v1; }
;         if (g32 == 96 && fq >= 2) { GAS float* gp = a.gates + (size_t)row * 32 + 16 + 8 * (fq - 2); *(GAS f32x4*)gp = v0; *(GAS f32x4*)(gp + 4) = v1; }
;     __device__ __forceinline__ void operator()(const f32x4 (&acc)[2][2][4][2], const pg8::Unit& u, int wr, int wc, int fr, int fq) const {
;     ...
;             f32x4 pq[2][4]; float rs[2][4];
; #pragma unroll
;             for (int ai = 0; ai < 2; ++ai)
; #pragma unroll
;                 for (int m = 0; m < 4; ++m) { const int row = u.pm * 256 + ai * 128 + wr * 64 + m * 16 + fr; pq[ai][m] = *(const GAS f32x4*)(a.ssp + (size_t)row * 16 + 4 * fq); }
; #pragma unroll
;             for (int ai = 0; ai < 2; ++ai)
; #pragma unroll
;                 for (int m = 0; m < 4; ++m) { float sp = (pq[ai][m][0] + pq[ai][m][1]) + (pq[ai][m][2] + pq[ai][m][3]); sp += __shfl_xor(sp, 16); sp += __shfl_xor(sp, 32); rs[ai][m] = rsqrtf(sp * (1.0f / 1024.0f) + EPS); }
; #pragma unroll
;             for (int ai = 0; ai < 2; ++ai)
; #pragma unroll
;                 for (int m = 0; m < 4; ++m) {
;                     const int row = u.pm * 256 + ai * 128 + wr * 64 + m * 16 + fr;
; #pragma unroll
;                     for (int bj = 0; bj < 2; ++bj) { const int g32 = (u.pn * 256 + bj * 128 + wc * 32) >> 5; (void)epi_apply<MODE, false>(a, row, g32, fq, acc[ai][bj][m][0], acc[ai][bj][m][1], rs[ai][m]); }
.LBB0_476:
	v_readlane_b32 s0, v245, 2
	s_lshl_b32 s74, s47, 8
	s_add_i32 s74, s74, s52
	v_mov_b32_e32 v120, s0
	ds_read_b128 v[124:127], v120
	v_or_b32_e32 v176, s74, v165
	v_ashrrev_i32_e32 v177, 31, v176
	v_or_b32_e32 v174, 16, v176
	v_ashrrev_i32_e32 v175, 31, v174
	s_waitcnt lgkmcnt(0)
	v_lshl_add_u64 v[140:141], v[126:127], 0, v[160:161]
	v_lshlrev_b64 v[126:127], 6, v[176:177]
	v_lshl_add_u64 v[126:127], v[140:141], 0, v[126:127]
	global_load_dwordx4 v[178:181], v[126:127], off
	v_lshlrev_b64 v[126:127], 6, v[174:175]
	v_lshl_add_u64 v[126:127], v[140:141], 0, v[126:127]
	global_load_dwordx4 v[186:189], v[126:127], off
	v_or_b32_e32 v172, 32, v176
	v_ashrrev_i32_e32 v173, 31, v172
	v_lshlrev_b64 v[126:127], 6, v[172:173]
	v_lshl_add_u64 v[126:127], v[140:141], 0, v[126:127]
	global_load_dwordx4 v[190:193], v[126:127], off
	v_or_b32_e32 v126, 48, v176
	v_ashrrev_i32_e32 v127, 31, v126
	v_lshlrev_b64 v[136:137], 6, v[126:127]
	v_lshl_add_u64 v[136:137], v[140:141], 0, v[136:137]
	global_load_dwordx4 v[208:211], v[136:137], off
	v_add_u32_e32 v136, 0x80, v176
	v_ashrrev_i32_e32 v137, 31, v136
	v_lshlrev_b64 v[136:137], 6, v[136:137]
	v_lshl_add_u64 v[136:137], v[140:141], 0, v[136:137]
	global_load_dwordx4 v[148:151], v[136:137], off
	v_add_u32_e32 v136, 0x90, v176
	v_ashrrev_i32_e32 v137, 31, v136
	v_lshlrev_b64 v[136:137], 6, v[136:137]
	v_lshl_add_u64 v[136:137], v[140:141], 0, v[136:137]
	global_load_dwordx4 v[144:147], v[136:137], off
	v_add_u32_e32 v136, 0xa0, v176
	v_add_u32_e32 v142, 0xb0, v176
	v_ashrrev_i32_e32 v137, 31, v136
	v_ashrrev_i32_e32 v143, 31, v142
	v_lshlrev_b64 v[136:137], 6, v[136:137]
	v_lshlrev_b64 v[142:143], 6, v[142:143]
	v_lshl_add_u64 v[136:137], v[140:141], 0, v[136:137]
	v_lshl_add_u64 v[140:141], v[140:141], 0, v[142:143]
	global_load_dwordx4 v[136:139], v[136:137], off
	v_and_b32_e32 v182, 64, v200
	global_load_dwordx4 v[140:143], v[140:141], off
	v_xor_b32_e32 v171, 16, v200
	v_add_u32_e32 v182, 64, v182
	v_cmp_lt_i32_e32 vcc, v171, v182
	v_xor_b32_e32 v183, 32, v200
	v_readlane_b32 s0, v245, 9
	v_cndmask_b32_e32 v171, v200, v171, vcc
	v_cmp_lt_i32_e32 vcc, v183, v182
	v_lshlrev_b32_e32 v171, 2, v171
	v_mov_b32_e32 v120, s0
	v_cndmask_b32_e32 v182, v200, v183, vcc
	v_lshlrev_b32_e32 v207, 2, v182
	ds_read_b128 v[120:123], v120
	s_lshl_b32 s34, s46, 8
	s_or_b32 s34, s34, s54
	s_cmpk_lt_i32 s34, 0xe01
	s_waitcnt vmcnt(0)
	v_mov_b32_e32 v182, v179
	v_mov_b32_e32 v183, v180
	v_mov_b32_e32 v179, v181
	v_mov_b32_e32 v180, v187
	v_mov_b32_e32 v181, v188
	v_mov_b32_e32 v187, v189
	v_pk_add_f32 v[178:179], v[182:183], v[178:179]
	v_pk_add_f32 v[180:181], v[180:181], v[186:187]
	v_mov_b32_e32 v183, v178
	v_mov_b32_e32 v182, v180
	v_mov_b32_e32 v178, v181
	v_pk_add_f32 v[178:179], v[182:183], v[178:179]
	ds_bpermute_b32 v181, v171, v179
	ds_bpermute_b32 v180, v171, v178
	v_mov_b32_e32 v182, v209
	v_mov_b32_e32 v183, v210
	v_mov_b32_e32 v209, v211
	v_pk_add_f32 v[182:183], v[182:183], v[208:209]
	s_waitcnt lgkmcnt(0)
	v_pk_add_f32 v[178:179], v[178:179], v[180:181]
	ds_bpermute_b32 v181, v207, v179
	ds_bpermute_b32 v180, v207, v178
	v_mov_b32_e32 v186, v182
	s_waitcnt lgkmcnt(0)
	v_pk_add_f32 v[178:179], v[178:179], v[180:181]
	s_nop 0
	v_pk_fma_f32 v[178:179], v[178:179], s[80:81], v[162:163] op_sel_hi:[1,0,0]
	v_mov_b32_e32 v181, v192
	v_mul_f32_e32 v180, 0x4b800000, v179
	v_cmp_gt_f32_e32 vcc, s3, v179
	v_cmp_gt_f32_e64 s[0:1], s3, v178
	s_nop 0
	v_cndmask_b32_e32 v179, v179, v180, vcc
	v_rsq_f32_e32 v179, v179
	s_nop 0
	v_mul_f32_e32 v180, 0x45800000, v179
	v_cndmask_b32_e32 v184, v179, v180, vcc
	v_mov_b32_e32 v180, v191
	v_mov_b32_e32 v191, v193
	v_pk_add_f32 v[180:181], v[180:181], v[190:191]
	s_nop 0
	v_mov_b32_e32 v187, v180
	v_mov_b32_e32 v180, v183
	v_pk_add_f32 v[180:181], v[186:187], v[180:181]
	v_mov_b32_e32 v186, v149
	v_mov_b32_e32 v187, v150
	v_mov_b32_e32 v149, v151
	v_mov_b32_e32 v150, v145
	v_mov_b32_e32 v151, v146
	v_mov_b32_e32 v145, v147
	v_pk_add_f32 v[148:149], v[186:187], v[148:149]
	v_pk_add_f32 v[144:145], v[150:151], v[144:145]
	v_mov_b32_e32 v147, v148
	v_mov_b32_e32 v146, v144
	v_mov_b32_e32 v148, v145
	v_pk_add_f32 v[144:145], v[146:147], v[148:149]
	v_mov_b32_e32 v148, v137
	v_mov_b32_e32 v149, v138
	v_mov_b32_e32 v137, v139
	v_mov_b32_e32 v138, v141
	v_mov_b32_e32 v139, v142
	v_mov_b32_e32 v141, v143
	v_pk_add_f32 v[136:137], v[148:149], v[136:137]
	v_pk_add_f32 v[138:139], v[138:139], v[140:141]
	v_mov_b32_e32 v141, v136
	v_mov_b32_e32 v140, v138
	v_mov_b32_e32 v136, v139
	v_pk_add_f32 v[136:137], v[140:141], v[136:137]
	ds_bpermute_b32 v183, v171, v181
	ds_bpermute_b32 v182, v171, v180
	ds_bpermute_b32 v147, v171, v145
	ds_bpermute_b32 v146, v171, v144
	ds_bpermute_b32 v139, v171, v137
	ds_bpermute_b32 v138, v171, v136
	s_waitcnt lgkmcnt(4)
	v_pk_add_f32 v[180:181], v[180:181], v[182:183]
	ds_bpermute_b32 v183, v207, v181
	s_waitcnt lgkmcnt(3)
	v_pk_add_f32 v[144:145], v[144:145], v[146:147]
	ds_bpermute_b32 v182, v207, v180
	s_waitcnt lgkmcnt(2)
	v_pk_add_f32 v[138:139], v[136:137], v[138:139]
	ds_bpermute_b32 v147, v207, v145
	ds_bpermute_b32 v146, v207, v144
	ds_bpermute_b32 v141, v207, v139
	ds_bpermute_b32 v140, v207, v138
	v_mov_b32_e32 v171, v161
	v_lshl_add_u64 v[136:137], v[120:121], 0, v[170:171]
	v_mad_i64_i32 v[142:143], s[44:45], v176, s5, v[124:125]
	v_or_b32_e32 v120, s34, v156
	s_cselect_b64 s[44:45], -1, 0
	s_cmpk_gt_i32 s34, 0xe00
	v_ashrrev_i32_e32 v121, 31, v120
	s_cbranch_scc1 .LBB0_482
	s_cmpk_eq_i32 s34, 0x600
	v_lshlrev_b64 v[148:149], 7, v[176:177]
	v_pk_mul_f32 v[134:135], v[134:135], v[184:185] op_sel_hi:[1,0]
	v_pk_mul_f32 v[132:133], v[132:133], v[184:185] op_sel_hi:[1,0]
	v_pk_mul_f32 v[130:131], v[130:131], v[184:185] op_sel_hi:[1,0]
	v_pk_mul_f32 v[128:129], v[128:129], v[184:185] op_sel_hi:[1,0]
	s_cselect_b64 s[46:47], -1, 0
	v_lshl_add_u64 v[148:149], v[136:137], 0, v[148:149]
	v_cvt_pk_bf16_f32 v186, v132, v133
	v_cvt_pk_bf16_f32 v187, v134, v135
	v_cvt_pk_bf16_f32 v188, v128, v129
	v_cvt_pk_bf16_f32 v189, v130, v131
	v_lshl_add_u64 v[150:151], v[120:121], 1, v[142:143]
	s_and_b64 s[50:51], s[46:47], s[38:39]
	global_store_dwordx4 v[150:151], v[186:189], off sc0 sc1
	s_and_saveexec_b64 s[46:47], s[50:51]
	s_cbranch_execz .LBB0_479
	global_store_dwordx4 v[148:149], v[132:135], off sc0 sc1
	global_store_dwordx4 v[148:149], v[128:131], off offset:16 sc0 sc1
.LBB0_479:
	s_or_b64 exec, exec, s[46:47]
	s_cmpk_eq_i32 s34, 0xc00
	s_cselect_b64 s[46:47], -1, 0
	s_and_b64 s[50:51], s[46:47], s[40:41]
	s_and_saveexec_b64 s[46:47], s[50:51]
	s_cbranch_execz .LBB0_481
	global_store_dwordx4 v[148:149], v[132:135], off sc0 sc1
	global_store_dwordx4 v[148:149], v[128:131], off offset:16 sc0 sc1

; #define GAS __attribute__((address_space(1)))
; __device__ __forceinline__ unsigned pk2(float lo, float hi) { const f32x2 v = {lo, hi}; return __builtin_bit_cast(unsigned, __builtin_convertvector(v, hwbf16x2)); }
; template <int MODE, bool SMALL>
; __device__ __forceinline__ float epi_apply(const EpiArgs& a, int row, int g32, int fq, f32x4 v0, f32x4 v1, float rstd) {
;     ...
;     if constexpr (MODE == 0) {
;         if (g32 >= ABIN / 32) return 0.f;
;         v0 *= rstd; v1 *= rstd;
;         u32x4 w; w.x = pk2(v0[0], v0[1]); w.y = pk2(v0[2], v0[3]); w.z = pk2(v1[0], v1[1]); w.w = pk2(v1[2], v1[3]);
;         *(GAS u32x4*)(a.out + (size_t)row * ABIN + c0) = w;
;         if (g32 == 48 && fq < 2) { GAS float* gp = a.gates + (size_t)row * 32 + 8 * fq; *(GAS f32x4*)gp = v0; *(GAS f32x4*)(gp + 4) = v1; }
;         if (g32 == 96 && fq >= 2) { GAS float* gp = a.gates + (size_t)row * 32 + 16 + 8 * (fq - 2); *(GAS f32x4*)gp = v0; *(GAS f32x4*)(gp + 4) = v1; }
.LBB0_482:
	s_or_b32 s75, s34, 0x80
	s_cmpk_lt_i32 s75, 0xe01
	s_cselect_b64 s[50:51], -1, 0
	s_cmpk_gt_i32 s75, 0xe00
	s_cbranch_scc1 .LBB0_484
	v_pk_mul_f32 v[116:117], v[116:117], v[184:185] op_sel_hi:[1,0]
	s_ashr_i32 s35, s34, 31
	v_pk_mul_f32 v[118:119], v[118:119], v[184:185] op_sel_hi:[1,0]
	v_pk_mul_f32 v[128:129], v[114:115], v[184:185] op_sel_hi:[1,0]
	v_pk_mul_f32 v[114:115], v[112:113], v[184:185] op_sel_hi:[1,0]
	v_cvt_pk_bf16_f32 v112, v116, v117
	v_lshl_add_u64 v[116:117], s[34:35], 0, v[156:157]
	v_cvt_pk_bf16_f32 v113, v118, v119
	v_cvt_pk_bf16_f32 v114, v114, v115
	v_cvt_pk_bf16_f32 v115, v128, v129
	v_lshl_add_u64 v[116:117], v[116:117], 1, v[142:143]
	global_store_dwordx4 v[116:117], v[112:115], off offset:256 sc0 sc1
.LBB0_484:
	s_nop 1
	v_mul_f32_e32 v112, 0x4b800000, v178
	v_cndmask_b32_e64 v112, v178, v112, s[0:1]
	v_rsq_f32_e32 v112, v112
	v_cndmask_b32_e64 v113, 0, 1, s[44:45]
	v_cmp_ne_u32_e64 s[46:47], 1, v113
	s_andn2_b64 vcc, exec, s[44:45]
	v_mul_f32_e32 v113, 0x45800000, v112
	v_cndmask_b32_e64 v114, v112, v113, s[0:1]
	v_mad_i64_i32 v[112:113], s[0:1], v174, s5, v[124:125]
	s_cbranch_vccnz .LBB0_490
	s_cmpk_eq_i32 s34, 0x600
	v_lshlrev_b64 v[116:117], 7, v[174:175]
	v_pk_mul_f32 v[110:111], v[110:111], v[114:115] op_sel_hi:[1,0]
	v_pk_mul_f32 v[108:109], v[108:109], v[114:115] op_sel_hi:[1,0]
	v_pk_mul_f32 v[106:107], v[106:107], v[114:115] op_sel_hi:[1,0]
	v_pk_mul_f32 v[104:105], v[104:105], v[114:115] op_sel_hi:[1,0]
	s_cselect_b64 s[0:1], -1, 0
	v_lshl_add_u64 v[116:117], v[136:137], 0, v[116:117]
	v_cvt_pk_bf16_f32 v128, v108, v109
	v_cvt_pk_bf16_f32 v129, v110, v111
	v_cvt_pk_bf16_f32 v130, v104, v105
	v_cvt_pk_bf16_f32 v131, v106, v107
	v_lshl_add_u64 v[118:119], v[120:121], 1, v[112:113]
	s_and_b64 s[44:45], s[0:1], s[38:39]
	global_store_dwordx4 v[118:119], v[128:131], off sc0 sc1
	s_and_saveexec_b64 s[0:1], s[44:45]
	s_cbranch_execz .LBB0_487
	global_store_dwordx4 v[116:117], v[108:111], off sc0 sc1
	global_store_dwordx4 v[116:117], v[104:107], off offset:16 sc0 sc1
.LBB0_487:
	s_or_b64 exec, exec, s[0:1]
	s_cmpk_eq_i32 s34, 0xc00
	s_cselect_b64 s[0:1], -1, 0
	s_and_b64 s[44:45], s[0:1], s[40:41]
	s_and_saveexec_b64 s[0:1], s[44:45]
	s_cbranch_execz .LBB0_489
	global_store_dwordx4 v[116:117], v[108:111], off sc0 sc1
	global_store_dwordx4 v[116:117], v[104:107], off offset:16 sc0 sc1

; #define GAS __attribute__((address_space(1)))
; __device__ __forceinline__ unsigned pk2(float lo, float hi) { const f32x2 v = {lo, hi}; return __builtin_bit_cast(unsigned, __builtin_convertvector(v, hwbf16x2)); }
; template <int MODE, bool SMALL>
; __device__ __forceinline__ float epi_apply(const EpiArgs& a, int row, int g32, int fq, f32x4 v0, f32x4 v1, float rstd) {
;     ...
;     if constexpr (MODE == 0) {
;         if (g32 >= ABIN / 32) return 0.f;
;         v0 *= rstd; v1 *= rstd;
;         u32x4 w; w.x = pk2(v0[0], v0[1]); w.y = pk2(v0[2], v0[3]); w.z = pk2(v1[0], v1[1]); w.w = pk2(v1[2], v1[3]);
;         *(GAS u32x4*)(a.out + (size_t)row * ABIN + c0) = w;
;         if (g32 == 48 && fq < 2) { GAS float* gp = a.gates + (size_t)row * 32 + 8 * fq; *(GAS f32x4*)gp = v0; *(GAS f32x4*)(gp + 4) = v1; }
;         if (g32 == 96 && fq >= 2) { GAS float* gp = a.gates + (size_t)row * 32 + 16 + 8 * (fq - 2); *(GAS f32x4*)gp = v0; *(GAS f32x4*)(gp + 4) = v1; }
;     __device__ __forceinline__ void operator()(const f32x4 (&acc)[2][2][4][2], const pg8::Unit& u, int wr, int wc, int fr, int fq) const {
;     ...
;             for (int ai = 0; ai < 2; ++ai)
; #pragma unroll
;                 for (int m = 0; m < 4; ++m) { float sp = (pq[ai][m][0] + pq[ai][m][1]) + (pq[ai][m][2] + pq[ai][m][3]); sp += __shfl_xor(sp, 16); sp += __shfl_xor(sp, 32); rs[ai][m] = rsqrtf(sp * (1.0f / 1024.0f) + EPS); }
.LBB0_490:
	s_nop 0
	v_cndmask_b32_e64 v104, 0, 1, s[50:51]
	v_cmp_ne_u32_e64 s[44:45], 1, v104
	s_andn2_b64 vcc, exec, s[50:51]
	s_cbranch_vccnz .LBB0_492
	v_pk_mul_f32 v[100:101], v[100:101], v[114:115] op_sel_hi:[1,0]
	s_ashr_i32 s35, s34, 31
	v_pk_mul_f32 v[102:103], v[102:103], v[114:115] op_sel_hi:[1,0]
	v_pk_mul_f32 v[104:105], v[98:99], v[114:115] op_sel_hi:[1,0]
	v_pk_mul_f32 v[98:99], v[96:97], v[114:115] op_sel_hi:[1,0]
	v_cvt_pk_bf16_f32 v96, v100, v101
	v_lshl_add_u64 v[100:101], s[34:35], 0, v[156:157]
	v_cvt_pk_bf16_f32 v97, v102, v103
	v_cvt_pk_bf16_f32 v98, v98, v99
	v_cvt_pk_bf16_f32 v99, v104, v105
	v_lshl_add_u64 v[100:101], v[100:101], 1, v[112:113]
	global_store_dwordx4 v[100:101], v[96:99], off offset:256 sc0 sc1
.LBB0_492:
	s_waitcnt lgkmcnt(4)
	s_nop 0
	v_pk_add_f32 v[96:97], v[180:181], v[182:183]
	s_and_b64 vcc, exec, s[46:47]
	v_pk_fma_f32 v[96:97], v[96:97], s[80:81], v[162:163] op_sel_hi:[1,0,0]
	s_nop 0
	v_mul_f32_e32 v98, 0x4b800000, v97
	v_cmp_gt_f32_e64 s[50:51], s3, v97
	v_cmp_gt_f32_e64 s[0:1], s3, v96
	s_nop 0
	v_cndmask_b32_e64 v97, v97, v98, s[50:51]
	v_rsq_f32_e32 v97, v97
	s_nop 0
	v_mul_f32_e32 v98, 0x45800000, v97
	v_cndmask_b32_e64 v100, v97, v98, s[50:51]
	v_mad_i64_i32 v[98:99], s[50:51], v172, s5, v[124:125]
	s_cbranch_vccnz .LBB0_498
	s_cmpk_eq_i32 s34, 0x600
	v_lshlrev_b64 v[102:103], 7, v[172:173]
	v_pk_mul_f32 v[94:95], v[94:95], v[100:101] op_sel_hi:[1,0]
	v_pk_mul_f32 v[92:93], v[92:93], v[100:101] op_sel_hi:[1,0]
	v_pk_mul_f32 v[90:91], v[90:91], v[100:101] op_sel_hi:[1,0]
	v_pk_mul_f32 v[88:89], v[88:89], v[100:101] op_sel_hi:[1,0]
	s_cselect_b64 s[50:51], -1, 0
	v_lshl_add_u64 v[102:103], v[136:137], 0, v[102:103]
	v_cvt_pk_bf16_f32 v104, v92, v93
	v_cvt_pk_bf16_f32 v105, v94, v95
	v_cvt_pk_bf16_f32 v106, v88, v89
	v_cvt_pk_bf16_f32 v107, v90, v91
	v_lshl_add_u64 v[108:109], v[120:121], 1, v[98:99]
	s_and_b64 s[76:77], s[50:51], s[38:39]
	global_store_dwordx4 v[108:109], v[104:107], off sc0 sc1
	s_and_saveexec_b64 s[50:51], s[76:77]
	s_cbranch_execz .LBB0_495
	global_store_dwordx4 v[102:103], v[92:95], off sc0 sc1
	global_store_dwordx4 v[102:103], v[88:91], off offset:16 sc0 sc1
.LBB0_495:
	s_or_b64 exec, exec, s[50:51]
	s_cmpk_eq_i32 s34, 0xc00
	s_cselect_b64 s[50:51], -1, 0
	s_and_b64 s[76:77], s[50:51], s[40:41]
	s_and_saveexec_b64 s[50:51], s[76:77]
	s_cbranch_execz .LBB0_497
	global_store_dwordx4 v[102:103], v[92:95], off sc0 sc1
	global_store_dwordx4 v[102:103], v[88:91], off offset:16 sc0 sc1

; #define GAS __attribute__((address_space(1)))
; __device__ __forceinline__ unsigned pk2(float lo, float hi) { const f32x2 v = {lo, hi}; return __builtin_bit_cast(unsigned, __builtin_convertvector(v, hwbf16x2)); }
; template <int MODE, bool SMALL>
; __device__ __forceinline__ float epi_apply(const EpiArgs& a, int row, int g32, int fq, f32x4 v0, f32x4 v1, float rstd) {
;     ...
;     if constexpr (MODE == 0) {
;         if (g32 >= ABIN / 32) return 0.f;
;         v0 *= rstd; v1 *= rstd;
;         u32x4 w; w.x = pk2(v0[0], v0[1]); w.y = pk2(v0[2], v0[3]); w.z = pk2(v1[0], v1[1]); w.w = pk2(v1[2], v1[3]);
;         *(GAS u32x4*)(a.out + (size_t)row * ABIN + c0) = w;
;         if (g32 == 48 && fq < 2) { GAS float* gp = a.gates + (size_t)row * 32 + 8 * fq; *(GAS f32x4*)gp = v0; *(GAS f32x4*)(gp + 4) = v1; }
;         if (g32 == 96 && fq >= 2) { GAS float* gp = a.gates + (size_t)row * 32 + 16 + 8 * (fq - 2); *(GAS f32x4*)gp = v0; *(GAS f32x4*)(gp + 4) = v1; }
;         if (c0 < DNQKV) {
;             if constexpr (!SMALL) { const int t = row & (SEQ - 1), b = row >> 12; if (t >= SEQ - 3) { GAS float* d = a.o0 + (size_t)(b * 3 + (t - (SEQ - 3))) * DNQKV + c0; *(GAS f32x4*)d = v0; *(GAS f32x4*)(d + 4) = v1; } }
.LBB0_498:
	s_and_b64 vcc, exec, s[44:45]
	s_cbranch_vccnz .LBB0_500
	v_pk_mul_f32 v[84:85], v[84:85], v[100:101] op_sel_hi:[1,0]
	s_ashr_i32 s35, s34, 31
	v_pk_mul_f32 v[86:87], v[86:87], v[100:101] op_sel_hi:[1,0]
	v_pk_mul_f32 v[88:89], v[82:83], v[100:101] op_sel_hi:[1,0]
	v_pk_mul_f32 v[82:83], v[80:81], v[100:101] op_sel_hi:[1,0]
	v_cvt_pk_bf16_f32 v80, v84, v85
	v_lshl_add_u64 v[84:85], s[34:35], 0, v[156:157]
	v_cvt_pk_bf16_f32 v81, v86, v87
	v_cvt_pk_bf16_f32 v82, v82, v83
	v_cvt_pk_bf16_f32 v83, v88, v89
	v_lshl_add_u64 v[84:85], v[84:85], 1, v[98:99]
	global_store_dwordx4 v[84:85], v[80:83], off offset:256 sc0 sc1
.LBB0_500:
	s_nop 1
	v_mul_f32_e32 v80, 0x4b800000, v96
	v_cndmask_b32_e64 v80, v96, v80, s[0:1]
	v_rsq_f32_e32 v80, v80
	s_ashr_i32 s35, s74, 12
	v_mad_i32_i24 v81, s35, 3, v206
	s_and_b64 vcc, exec, s[46:47]
	v_mul_f32_e32 v82, 0x45800000, v80
	v_cndmask_b32_e64 v84, v80, v82, s[0:1]
	v_mad_i64_i32 v[82:83], s[0:1], v126, s5, v[124:125]
	v_and_b32_e32 v80, 0xfff, v126
	s_movk_i32 s0, 0xffd
	v_cmp_gt_u32_e64 s[0:1], s0, v80
	v_add_u32_e32 v80, v81, v80
	v_mad_i64_i32 v[80:81], s[50:51], v80, s66, v[122:123]
	s_cbranch_vccnz .LBB0_508
	s_cmpk_eq_i32 s34, 0x600
	v_lshlrev_b64 v[86:87], 7, v[126:127]
	v_pk_mul_f32 v[78:79], v[78:79], v[84:85] op_sel_hi:[1,0]
	v_pk_mul_f32 v[76:77], v[76:77], v[84:85] op_sel_hi:[1,0]
	v_pk_mul_f32 v[74:75], v[74:75], v[84:85] op_sel_hi:[1,0]
	v_pk_mul_f32 v[72:73], v[72:73], v[84:85] op_sel_hi:[1,0]
	s_cselect_b64 s[50:51], -1, 0
	v_lshl_add_u64 v[86:87], v[136:137], 0, v[86:87]
	v_cvt_pk_bf16_f32 v88, v76, v77
	v_cvt_pk_bf16_f32 v89, v78, v79
	v_cvt_pk_bf16_f32 v90, v72, v73
	v_cvt_pk_bf16_f32 v91, v74, v75
	v_lshl_add_u64 v[92:93], v[120:121], 1, v[82:83]
	s_and_b64 s[76:77], s[50:51], s[38:39]
	global_store_dwordx4 v[92:93], v[88:91], off sc0 sc1
	s_and_saveexec_b64 s[50:51], s[76:77]
	s_cbranch_execz .LBB0_503
	global_store_dwordx4 v[86:87], v[76:79], off sc0 sc1
	global_store_dwordx4 v[86:87], v[72:75], off offset:16 sc0 sc1
.LBB0_503:
	s_or_b64 exec, exec, s[50:51]
	s_cmpk_eq_i32 s34, 0xc00
	s_cselect_b64 s[50:51], -1, 0
	s_and_b64 s[76:77], s[50:51], s[40:41]
	s_and_saveexec_b64 s[50:51], s[76:77]
	s_cbranch_execz .LBB0_505
	global_store_dwordx4 v[86:87], v[76:79], off sc0 sc1
	global_store_dwordx4 v[86:87], v[72:75], off offset:16 sc0 sc1
.LBB0_505:
	s_or_b64 exec, exec, s[50:51]
	v_cmp_gt_i32_e32 vcc, s78, v120
	s_xor_b64 s[50:51], s[0:1], -1
	s_and_b64 s[76:77], vcc, s[50:51]
	s_and_saveexec_b64 s[50:51], s[76:77]
	s_cbranch_execz .LBB0_507
	v_lshl_add_u64 v[86:87], v[120:121], 2, v[80:81]
	global_store_dwordx4 v[86:87], v[76:79], off sc0 sc1
	global_store_dwordx4 v[86:87], v[72:75], off offset:16 sc0 sc1

; #define GAS __attribute__((address_space(1)))
; __device__ __forceinline__ unsigned pk2(float lo, float hi) { const f32x2 v = {lo, hi}; return __builtin_bit_cast(unsigned, __builtin_convertvector(v, hwbf16x2)); }
; template <int MODE, bool SMALL>
; __device__ __forceinline__ float epi_apply(const EpiArgs& a, int row, int g32, int fq, f32x4 v0, f32x4 v1, float rstd) {
;     ...
;     if constexpr (MODE == 0) {
;         if (g32 >= ABIN / 32) return 0.f;
;         v0 *= rstd; v1 *= rstd;
;         u32x4 w; w.x = pk2(v0[0], v0[1]); w.y = pk2(v0[2], v0[3]); w.z = pk2(v1[0], v1[1]); w.w = pk2(v1[2], v1[3]);
;         *(GAS u32x4*)(a.out + (size_t)row * ABIN + c0) = w;
;         if (g32 == 48 && fq < 2) { GAS float* gp = a.gates + (size_t)row * 32 + 8 * fq; *(GAS f32x4*)gp = v0; *(GAS f32x4*)(gp + 4) = v1; }
;         if (g32 == 96 && fq >= 2) { GAS float* gp = a.gates + (size_t)row * 32 + 16 + 8 * (fq - 2); *(GAS f32x4*)gp = v0; *(GAS f32x4*)(gp + 4) = v1; }
;         if (c0 < DNQKV) {
;             if constexpr (!SMALL) { const int t = row & (SEQ - 1), b = row >> 12; if (t >= SEQ - 3) { GAS float* d = a.o0 + (size_t)(b * 3 + (t - (SEQ - 3))) * DNQKV + c0; *(GAS f32x4*)d = v0; *(GAS f32x4*)(d + 4) = v1; } }
.LBB0_508:
	s_nop 0
	v_or_b32_e32 v74, s75, v156
	s_and_b64 vcc, exec, s[44:45]
	v_cmp_gt_i32_e64 s[50:51], s78, v74
	s_movk_i32 s75, 0x2000
	s_cbranch_vccnz .LBB0_512
	s_ashr_i32 s35, s34, 31
	v_pk_mul_f32 v[70:71], v[70:71], v[84:85] op_sel_hi:[1,0]
	v_pk_mul_f32 v[68:69], v[68:69], v[84:85] op_sel_hi:[1,0]
	v_pk_mul_f32 v[66:67], v[66:67], v[84:85] op_sel_hi:[1,0]
	v_pk_mul_f32 v[64:65], v[64:65], v[84:85] op_sel_hi:[1,0]
	v_lshl_add_u64 v[72:73], s[34:35], 0, v[156:157]
	s_xor_b64 s[0:1], s[0:1], -1
	v_cvt_pk_bf16_f32 v76, v68, v69
	v_cvt_pk_bf16_f32 v77, v70, v71
	v_cvt_pk_bf16_f32 v78, v64, v65
	v_cvt_pk_bf16_f32 v79, v66, v67
	v_lshl_add_u64 v[82:83], v[72:73], 1, v[82:83]
	s_and_b64 s[50:51], s[50:51], s[0:1]
	global_store_dwordx4 v[82:83], v[76:79], off offset:256 sc0 sc1
	s_and_saveexec_b64 s[0:1], s[50:51]
	s_cbranch_execz .LBB0_511
	v_lshl_add_u64 v[72:73], v[72:73], 2, v[80:81]
	global_store_dwordx4 v[72:73], v[68:71], off offset:512 sc0 sc1
	global_store_dwordx4 v[72:73], v[64:67], off offset:528 sc0 sc1

; #define GAS __attribute__((address_space(1)))
; __device__ __forceinline__ unsigned pk2(float lo, float hi) { const f32x2 v = {lo, hi}; return __builtin_bit_cast(unsigned, __builtin_convertvector(v, hwbf16x2)); }
; template <int MODE, bool SMALL>
; __device__ __forceinline__ float epi_apply(const EpiArgs& a, int row, int g32, int fq, f32x4 v0, f32x4 v1, float rstd) {
;     ...
;     if constexpr (MODE == 0) {
;         if (g32 >= ABIN / 32) return 0.f;
;         v0 *= rstd; v1 *= rstd;
;         u32x4 w; w.x = pk2(v0[0], v0[1]); w.y = pk2(v0[2], v0[3]); w.z = pk2(v1[0], v1[1]); w.w = pk2(v1[2], v1[3]);
;         *(GAS u32x4*)(a.out + (size_t)row * ABIN + c0) = w;
;         if (g32 == 48 && fq < 2) { GAS float* gp = a.gates + (size_t)row * 32 + 8 * fq; *(GAS f32x4*)gp = v0; *(GAS f32x4*)(gp + 4) = v1; }
;         if (g32 == 96 && fq >= 2) { GAS float* gp = a.gates + (size_t)row * 32 + 16 + 8 * (fq - 2); *(GAS f32x4*)gp = v0; *(GAS f32x4*)(gp + 4) = v1; }
;     __device__ __forceinline__ void operator()(const f32x4 (&acc)[2][2][4][2], const pg8::Unit& u, int wr, int wc, int fr, int fq) const {
;     ...
;             for (int ai = 0; ai < 2; ++ai)
; #pragma unroll
;                 for (int m = 0; m < 4; ++m) { float sp = (pq[ai][m][0] + pq[ai][m][1]) + (pq[ai][m][2] + pq[ai][m][3]); sp += __shfl_xor(sp, 16); sp += __shfl_xor(sp, 32); rs[ai][m] = rsqrtf(sp * (1.0f / 1024.0f) + EPS); }
.LBB0_512:
	s_waitcnt lgkmcnt(2)
	v_pk_add_f32 v[64:65], v[144:145], v[146:147]
	s_addk_i32 s74, 0x80
	v_pk_fma_f32 v[66:67], v[64:65], s[80:81], v[162:163] op_sel_hi:[1,0,0]
	s_nop 0
	v_mul_f32_e32 v64, 0x4b800000, v67
	v_cmp_gt_f32_e32 vcc, s3, v67
	v_cmp_gt_f32_e64 s[0:1], s3, v66
	s_nop 0
	v_cndmask_b32_e32 v64, v67, v64, vcc
	v_rsq_f32_e32 v64, v64
	s_nop 0
	v_mul_f32_e32 v65, 0x45800000, v64
	v_cndmask_b32_e32 v70, v64, v65, vcc
	v_or_b32_e32 v64, s74, v165
	s_and_b64 vcc, exec, s[46:47]
	v_mad_i64_i32 v[68:69], s[50:51], v64, s5, v[124:125]
	s_cbranch_vccnz .LBB0_518
	v_ashrrev_i32_e32 v65, 31, v64
	s_cmpk_eq_i32 s34, 0x600
	v_lshlrev_b64 v[72:73], 7, v[64:65]
	v_pk_mul_f32 v[62:63], v[62:63], v[70:71] op_sel_hi:[1,0]
	v_pk_mul_f32 v[60:61], v[60:61], v[70:71] op_sel_hi:[1,0]
	v_pk_mul_f32 v[58:59], v[58:59], v[70:71] op_sel_hi:[1,0]
	v_pk_mul_f32 v[56:57], v[56:57], v[70:71] op_sel_hi:[1,0]
	s_cselect_b64 s[50:51], -1, 0
	v_lshl_add_u64 v[72:73], v[136:137], 0, v[72:73]
	v_cvt_pk_bf16_f32 v76, v60, v61
	v_cvt_pk_bf16_f32 v77, v62, v63
	v_cvt_pk_bf16_f32 v78, v56, v57
	v_cvt_pk_bf16_f32 v79, v58, v59
	v_lshl_add_u64 v[80:81], v[120:121], 1, v[68:69]
	s_and_b64 s[76:77], s[50:51], s[38:39]
	global_store_dwordx4 v[80:81], v[76:79], off sc0 sc1
	s_and_saveexec_b64 s[50:51], s[76:77]
	s_cbranch_execz .LBB0_515
	global_store_dwordx4 v[72:73], v[60:63], off sc0 sc1
	global_store_dwordx4 v[72:73], v[56:59], off offset:16 sc0 sc1
.LBB0_515:
	s_or_b64 exec, exec, s[50:51]
	s_cmpk_eq_i32 s34, 0xc00
	s_cselect_b64 s[50:51], -1, 0
	s_and_b64 s[76:77], s[50:51], s[40:41]
	s_and_saveexec_b64 s[50:51], s[76:77]
	s_cbranch_execz .LBB0_517
	global_store_dwordx4 v[72:73], v[60:63], off sc0 sc1
	global_store_dwordx4 v[72:73], v[56:59], off offset:16 sc0 sc1

; #define GAS __attribute__((address_space(1)))
; __device__ __forceinline__ unsigned pk2(float lo, float hi) { const f32x2 v = {lo, hi}; return __builtin_bit_cast(unsigned, __builtin_convertvector(v, hwbf16x2)); }
; template <int MODE, bool SMALL>
; __device__ __forceinline__ float epi_apply(const EpiArgs& a, int row, int g32, int fq, f32x4 v0, f32x4 v1, float rstd) {
;     ...
;     if constexpr (MODE == 0) {
;         if (g32 >= ABIN / 32) return 0.f;
;         v0 *= rstd; v1 *= rstd;
;         u32x4 w; w.x = pk2(v0[0], v0[1]); w.y = pk2(v0[2], v0[3]); w.z = pk2(v1[0], v1[1]); w.w = pk2(v1[2], v1[3]);
;         *(GAS u32x4*)(a.out + (size_t)row * ABIN + c0) = w;
;         if (g32 == 48 && fq < 2) { GAS float* gp = a.gates + (size_t)row * 32 + 8 * fq; *(GAS f32x4*)gp = v0; *(GAS f32x4*)(gp + 4) = v1; }
;         if (g32 == 96 && fq >= 2) { GAS float* gp = a.gates + (size_t)row * 32 + 16 + 8 * (fq - 2); *(GAS f32x4*)gp = v0; *(GAS f32x4*)(gp + 4) = v1; }
.LBB0_518:
	s_and_b64 vcc, exec, s[44:45]
	s_cbranch_vccnz .LBB0_520
	v_pk_mul_f32 v[52:53], v[52:53], v[70:71] op_sel_hi:[1,0]
	s_ashr_i32 s35, s34, 31
	v_pk_mul_f32 v[54:55], v[54:55], v[70:71] op_sel_hi:[1,0]
	v_pk_mul_f32 v[56:57], v[50:51], v[70:71] op_sel_hi:[1,0]
	v_pk_mul_f32 v[50:51], v[48:49], v[70:71] op_sel_hi:[1,0]
	v_cvt_pk_bf16_f32 v48, v52, v53
	v_lshl_add_u64 v[52:53], s[34:35], 0, v[156:157]
	v_cvt_pk_bf16_f32 v49, v54, v55
	v_cvt_pk_bf16_f32 v50, v50, v51
	v_cvt_pk_bf16_f32 v51, v56, v57
	v_lshl_add_u64 v[52:53], v[52:53], 1, v[68:69]
	global_store_dwordx4 v[52:53], v[48:51], off offset:256 sc0 sc1
.LBB0_520:
	s_nop 1
	v_mul_f32_e32 v48, 0x4b800000, v66
	v_cndmask_b32_e64 v48, v66, v48, s[0:1]
	v_rsq_f32_e32 v48, v48
	v_or_b32_e32 v52, 16, v64
	s_and_b64 vcc, exec, s[46:47]
	v_mul_f32_e32 v49, 0x45800000, v48
	v_cndmask_b32_e64 v50, v48, v49, s[0:1]
	v_mad_i64_i32 v[48:49], s[0:1], v52, s5, v[124:125]
	s_cbranch_vccnz .LBB0_526
	v_ashrrev_i32_e32 v53, 31, v52
	s_cmpk_eq_i32 s34, 0x600
	v_lshlrev_b64 v[52:53], 7, v[52:53]
	v_pk_mul_f32 v[46:47], v[46:47], v[50:51] op_sel_hi:[1,0]
	v_pk_mul_f32 v[44:45], v[44:45], v[50:51] op_sel_hi:[1,0]
	v_pk_mul_f32 v[42:43], v[42:43], v[50:51] op_sel_hi:[1,0]
	v_pk_mul_f32 v[40:41], v[40:41], v[50:51] op_sel_hi:[1,0]
	s_cselect_b64 s[0:1], -1, 0
	v_lshl_add_u64 v[52:53], v[136:137], 0, v[52:53]
	v_cvt_pk_bf16_f32 v54, v44, v45
	v_cvt_pk_bf16_f32 v55, v46, v47
	v_cvt_pk_bf16_f32 v56, v40, v41
	v_cvt_pk_bf16_f32 v57, v42, v43
	v_lshl_add_u64 v[58:59], v[120:121], 1, v[48:49]
	s_and_b64 s[50:51], s[0:1], s[38:39]
	global_store_dwordx4 v[58:59], v[54:57], off sc0 sc1
	s_and_saveexec_b64 s[0:1], s[50:51]
	s_cbranch_execz .LBB0_523
	global_store_dwordx4 v[52:53], v[44:47], off sc0 sc1
	global_store_dwordx4 v[52:53], v[40:43], off offset:16 sc0 sc1
.LBB0_523:
	s_or_b64 exec, exec, s[0:1]
	s_cmpk_eq_i32 s34, 0xc00
	s_cselect_b64 s[0:1], -1, 0
	s_and_b64 s[50:51], s[0:1], s[40:41]
	s_and_saveexec_b64 s[0:1], s[50:51]
	s_cbranch_execz .LBB0_525
	global_store_dwordx4 v[52:53], v[44:47], off sc0 sc1
	global_store_dwordx4 v[52:53], v[40:43], off offset:16 sc0 sc1

; #define GAS __attribute__((address_space(1)))
; __device__ __forceinline__ unsigned pk2(float lo, float hi) { const f32x2 v = {lo, hi}; return __builtin_bit_cast(unsigned, __builtin_convertvector(v, hwbf16x2)); }
; template <int MODE, bool SMALL>
; __device__ __forceinline__ float epi_apply(const EpiArgs& a, int row, int g32, int fq, f32x4 v0, f32x4 v1, float rstd) {
;     ...
;     if constexpr (MODE == 0) {
;         if (g32 >= ABIN / 32) return 0.f;
;         v0 *= rstd; v1 *= rstd;
;         u32x4 w; w.x = pk2(v0[0], v0[1]); w.y = pk2(v0[2], v0[3]); w.z = pk2(v1[0], v1[1]); w.w = pk2(v1[2], v1[3]);
;         *(GAS u32x4*)(a.out + (size_t)row * ABIN + c0) = w;
;         if (g32 == 48 && fq < 2) { GAS float* gp = a.gates + (size_t)row * 32 + 8 * fq; *(GAS f32x4*)gp = v0; *(GAS f32x4*)(gp + 4) = v1; }
;         if (g32 == 96 && fq >= 2) { GAS float* gp = a.gates + (size_t)row * 32 + 16 + 8 * (fq - 2); *(GAS f32x4*)gp = v0; *(GAS f32x4*)(gp + 4) = v1; }
;     __device__ __forceinline__ void operator()(const f32x4 (&acc)[2][2][4][2], const pg8::Unit& u, int wr, int wc, int fr, int fq) const {
;     ...
;             for (int ai = 0; ai < 2; ++ai)
; #pragma unroll
;                 for (int m = 0; m < 4; ++m) { float sp = (pq[ai][m][0] + pq[ai][m][1]) + (pq[ai][m][2] + pq[ai][m][3]); sp += __shfl_xor(sp, 16); sp += __shfl_xor(sp, 32); rs[ai][m] = rsqrtf(sp * (1.0f / 1024.0f) + EPS); }
.LBB0_526:
	s_and_b64 vcc, exec, s[44:45]
	s_cbranch_vccnz .LBB0_528
	v_pk_mul_f32 v[36:37], v[36:37], v[50:51] op_sel_hi:[1,0]
	s_ashr_i32 s35, s34, 31
	v_pk_mul_f32 v[38:39], v[38:39], v[50:51] op_sel_hi:[1,0]
	v_pk_mul_f32 v[40:41], v[34:35], v[50:51] op_sel_hi:[1,0]
	v_pk_mul_f32 v[34:35], v[32:33], v[50:51] op_sel_hi:[1,0]
	v_cvt_pk_bf16_f32 v32, v36, v37
	v_lshl_add_u64 v[36:37], s[34:35], 0, v[156:157]
	v_cvt_pk_bf16_f32 v33, v38, v39
	v_cvt_pk_bf16_f32 v34, v34, v35
	v_cvt_pk_bf16_f32 v35, v40, v41
	v_lshl_add_u64 v[36:37], v[36:37], 1, v[48:49]
	global_store_dwordx4 v[36:37], v[32:35], off offset:256 sc0 sc1
.LBB0_528:
	s_waitcnt lgkmcnt(0)
	s_nop 0
	v_pk_add_f32 v[32:33], v[138:139], v[140:141]
	v_or_b32_e32 v38, 32, v64
	v_pk_fma_f32 v[32:33], v[32:33], s[80:81], v[162:163] op_sel_hi:[1,0,0]
	s_nop 0
	v_mul_f32_e32 v34, 0x4b800000, v33
	v_cmp_gt_f32_e32 vcc, s3, v33
	v_cmp_gt_f32_e64 s[0:1], s3, v32
	s_nop 0
	v_cndmask_b32_e32 v33, v33, v34, vcc
	v_rsq_f32_e32 v33, v33
	s_nop 0
	v_mul_f32_e32 v34, 0x45800000, v33
	v_cndmask_b32_e32 v36, v33, v34, vcc
	s_and_b64 vcc, exec, s[46:47]
	v_mad_i64_i32 v[34:35], s[50:51], v38, s5, v[124:125]
	s_cbranch_vccnz .LBB0_534
	v_ashrrev_i32_e32 v39, 31, v38
	s_cmpk_eq_i32 s34, 0x600
	v_lshlrev_b64 v[38:39], 7, v[38:39]
	v_pk_mul_f32 v[30:31], v[30:31], v[36:37] op_sel_hi:[1,0]
	v_pk_mul_f32 v[28:29], v[28:29], v[36:37] op_sel_hi:[1,0]
	v_pk_mul_f32 v[26:27], v[26:27], v[36:37] op_sel_hi:[1,0]
	v_pk_mul_f32 v[24:25], v[24:25], v[36:37] op_sel_hi:[1,0]
	s_cselect_b64 s[50:51], -1, 0
	v_lshl_add_u64 v[38:39], v[136:137], 0, v[38:39]
	v_cvt_pk_bf16_f32 v40, v28, v29
	v_cvt_pk_bf16_f32 v41, v30, v31
	v_cvt_pk_bf16_f32 v42, v24, v25
	v_cvt_pk_bf16_f32 v43, v26, v27
	v_lshl_add_u64 v[44:45], v[120:121], 1, v[34:35]
	s_and_b64 s[76:77], s[50:51], s[38:39]
	global_store_dwordx4 v[44:45], v[40:43], off sc0 sc1
	s_and_saveexec_b64 s[50:51], s[76:77]
	s_cbranch_execz .LBB0_531
	global_store_dwordx4 v[38:39], v[28:31], off sc0 sc1
	global_store_dwordx4 v[38:39], v[24:27], off offset:16 sc0 sc1
.LBB0_531:
	s_or_b64 exec, exec, s[50:51]
	s_cmpk_eq_i32 s34, 0xc00
	s_cselect_b64 s[50:51], -1, 0
	s_and_b64 s[76:77], s[50:51], s[40:41]
	s_and_saveexec_b64 s[50:51], s[76:77]
	s_cbranch_execz .LBB0_533
	global_store_dwordx4 v[38:39], v[28:31], off sc0 sc1
	global_store_dwordx4 v[38:39], v[24:27], off offset:16 sc0 sc1

; #define GAS __attribute__((address_space(1)))
; __device__ __forceinline__ unsigned pk2(float lo, float hi) { const f32x2 v = {lo, hi}; return __builtin_bit_cast(unsigned, __builtin_convertvector(v, hwbf16x2)); }
; template <int MODE, bool SMALL>
; __device__ __forceinline__ float epi_apply(const EpiArgs& a, int row, int g32, int fq, f32x4 v0, f32x4 v1, float rstd) {
;     ...
;     if constexpr (MODE == 0) {
;         if (g32 >= ABIN / 32) return 0.f;
;         v0 *= rstd; v1 *= rstd;
;         u32x4 w; w.x = pk2(v0[0], v0[1]); w.y = pk2(v0[2], v0[3]); w.z = pk2(v1[0], v1[1]); w.w = pk2(v1[2], v1[3]);
;         *(GAS u32x4*)(a.out + (size_t)row * ABIN + c0) = w;
;         if (g32 == 48 && fq < 2) { GAS float* gp = a.gates + (size_t)row * 32 + 8 * fq; *(GAS f32x4*)gp = v0; *(GAS f32x4*)(gp + 4) = v1; }
;         if (g32 == 96 && fq >= 2) { GAS float* gp = a.gates + (size_t)row * 32 + 16 + 8 * (fq - 2); *(GAS f32x4*)gp = v0; *(GAS f32x4*)(gp + 4) = v1; }
;         if (c0 < DNQKV) {
;             if constexpr (!SMALL) { const int t = row & (SEQ - 1), b = row >> 12; if (t >= SEQ - 3) { GAS float* d = a.o0 + (size_t)(b * 3 + (t - (SEQ - 3))) * DNQKV + c0; *(GAS f32x4*)d = v0; *(GAS f32x4*)(d + 4) = v1; } }
.LBB0_534:
	s_and_b64 vcc, exec, s[44:45]
	s_cbranch_vccnz .LBB0_536
	v_pk_mul_f32 v[20:21], v[20:21], v[36:37] op_sel_hi:[1,0]
	s_ashr_i32 s35, s34, 31
	v_pk_mul_f32 v[22:23], v[22:23], v[36:37] op_sel_hi:[1,0]
	v_pk_mul_f32 v[24:25], v[18:19], v[36:37] op_sel_hi:[1,0]
	v_pk_mul_f32 v[18:19], v[16:17], v[36:37] op_sel_hi:[1,0]
	v_cvt_pk_bf16_f32 v16, v20, v21
	v_lshl_add_u64 v[20:21], s[34:35], 0, v[156:157]
	v_cvt_pk_bf16_f32 v17, v22, v23
	v_cvt_pk_bf16_f32 v18, v18, v19
	v_cvt_pk_bf16_f32 v19, v24, v25
	v_lshl_add_u64 v[20:21], v[20:21], 1, v[34:35]
	global_store_dwordx4 v[20:21], v[16:19], off offset:256 sc0 sc1
.LBB0_536:
	s_nop 1
	v_mul_f32_e32 v16, 0x4b800000, v32
	v_cndmask_b32_e64 v16, v32, v16, s[0:1]
	v_rsq_f32_e32 v16, v16
	v_or_b32_e32 v22, 48, v64
	s_ashr_i32 s35, s74, 12
	v_mad_i32_i24 v17, s35, 3, v206
	v_mul_f32_e32 v18, 0x45800000, v16
	v_cndmask_b32_e64 v20, v16, v18, s[0:1]
	v_mad_i64_i32 v[18:19], s[0:1], v22, s5, v[124:125]
	s_movk_i32 s0, 0xfff
	s_nop 0
	v_bitop3_b32 v16, v64, s0, 48 bitop3:0xc8
	s_movk_i32 s0, 0xffd
	v_cmp_gt_u32_e64 s[0:1], s0, v16
	v_add_u32_e32 v16, v17, v16
	s_and_b64 vcc, exec, s[46:47]
	v_mad_i64_i32 v[16:17], s[46:47], v16, s66, v[122:123]
	s_cbranch_vccnz .LBB0_545
	v_ashrrev_i32_e32 v23, 31, v22
	s_cmpk_eq_i32 s34, 0x600
	v_lshlrev_b64 v[22:23], 7, v[22:23]
	v_pk_mul_f32 v[14:15], v[14:15], v[20:21] op_sel_hi:[1,0]
	v_pk_mul_f32 v[12:13], v[12:13], v[20:21] op_sel_hi:[1,0]
	v_pk_mul_f32 v[10:11], v[10:11], v[20:21] op_sel_hi:[1,0]
	v_pk_mul_f32 v[8:9], v[8:9], v[20:21] op_sel_hi:[1,0]
	s_cselect_b64 s[46:47], -1, 0
	v_lshl_add_u64 v[22:23], v[136:137], 0, v[22:23]
	v_cvt_pk_bf16_f32 v24, v12, v13
	v_cvt_pk_bf16_f32 v25, v14, v15
	v_cvt_pk_bf16_f32 v26, v8, v9
	v_cvt_pk_bf16_f32 v27, v10, v11
	v_lshl_add_u64 v[28:29], v[120:121], 1, v[18:19]
	s_and_b64 s[50:51], s[46:47], s[38:39]
	global_store_dwordx4 v[28:29], v[24:27], off sc0 sc1
	s_and_saveexec_b64 s[46:47], s[50:51]
	s_cbranch_execz .LBB0_539
	global_store_dwordx4 v[22:23], v[12:15], off sc0 sc1
	global_store_dwordx4 v[22:23], v[8:11], off offset:16 sc0 sc1
.LBB0_539:
	s_or_b64 exec, exec, s[46:47]
	s_cmpk_eq_i32 s34, 0xc00
	s_cselect_b64 s[46:47], -1, 0
	s_and_b64 s[50:51], s[46:47], s[40:41]
	s_and_saveexec_b64 s[46:47], s[50:51]
	s_cbranch_execz .LBB0_541
	global_store_dwordx4 v[22:23], v[12:15], off sc0 sc1
	global_store_dwordx4 v[22:23], v[8:11], off offset:16 sc0 sc1
.LBB0_541:
	s_or_b64 exec, exec, s[46:47]
	v_cmp_gt_i32_e32 vcc, s78, v120
	s_xor_b64 s[46:47], s[0:1], -1
	s_and_b64 s[50:51], vcc, s[46:47]
	s_and_saveexec_b64 s[46:47], s[50:51]
	s_cbranch_execz .LBB0_543
	v_lshl_add_u64 v[22:23], v[120:121], 2, v[16:17]
	global_store_dwordx4 v[22:23], v[12:15], off sc0 sc1
	global_store_dwordx4 v[22:23], v[8:11], off offset:16 sc0 sc1

; #define GAS __attribute__((address_space(1)))
; __device__ __forceinline__ unsigned pk2(float lo, float hi) { const f32x2 v = {lo, hi}; return __builtin_bit_cast(unsigned, __builtin_convertvector(v, hwbf16x2)); }
; template <int MODE, bool SMALL>
; __device__ __forceinline__ float epi_apply(const EpiArgs& a, int row, int g32, int fq, f32x4 v0, f32x4 v1, float rstd) {
;     ...
;         if (g32 >= ABIN / 32) return 0.f;
;         v0 *= rstd; v1 *= rstd;
;         u32x4 w; w.x = pk2(v0[0], v0[1]); w.y = pk2(v0[2], v0[3]); w.z = pk2(v1[0], v1[1]); w.w = pk2(v1[2], v1[3]);
;         *(GAS u32x4*)(a.out + (size_t)row * ABIN + c0) = w;
;         if (g32 == 48 && fq < 2) { GAS float* gp = a.gates + (size_t)row * 32 + 8 * fq; *(GAS f32x4*)gp = v0; *(GAS f32x4*)(gp + 4) = v1; }
;         if (g32 == 96 && fq >= 2) { GAS float* gp = a.gates + (size_t)row * 32 + 16 + 8 * (fq - 2); *(GAS f32x4*)gp = v0; *(GAS f32x4*)(gp + 4) = v1; }
;         if (c0 < DNQKV) {
;             if constexpr (!SMALL) { const int t = row & (SEQ - 1), b = row >> 12; if (t >= SEQ - 3) { GAS float* d = a.o0 + (size_t)(b * 3 + (t - (SEQ - 3))) * DNQKV + c0; *(GAS f32x4*)d = v0; *(GAS f32x4*)(d + 4) = v1; } }
.LBB0_546:
	s_ashr_i32 s35, s34, 31
	v_pk_mul_f32 v[6:7], v[6:7], v[20:21] op_sel_hi:[1,0]
	v_pk_mul_f32 v[4:5], v[4:5], v[20:21] op_sel_hi:[1,0]
	v_pk_mul_f32 v[2:3], v[2:3], v[20:21] op_sel_hi:[1,0]
	v_pk_mul_f32 v[0:1], v[0:1], v[20:21] op_sel_hi:[1,0]
	v_lshl_add_u64 v[8:9], s[34:35], 0, v[156:157]
	v_cmp_gt_i32_e32 vcc, s78, v74
	s_xor_b64 s[0:1], s[0:1], -1
	v_cvt_pk_bf16_f32 v10, v4, v5
	v_cvt_pk_bf16_f32 v11, v6, v7
	v_cvt_pk_bf16_f32 v12, v0, v1
	v_cvt_pk_bf16_f32 v13, v2, v3
	v_lshl_add_u64 v[14:15], v[8:9], 1, v[18:19]
	s_and_b64 s[34:35], vcc, s[0:1]
	global_store_dwordx4 v[14:15], v[10:13], off offset:256 sc0 sc1
	s_and_saveexec_b64 s[0:1], s[34:35]
	s_cbranch_execz .LBB0_548
	v_lshl_add_u64 v[8:9], v[8:9], 2, v[16:17]
	global_store_dwordx4 v[8:9], v[4:7], off offset:512 sc0 sc1
	global_store_dwordx4 v[8:9], v[0:3], off offset:528 sc0 sc1
